# loop-edge edit: K-loop counter updates and exit compare moved above the closing barrier; scalar address block after the first ds_reads in the in-proj and vT K-loops
# baseline (speedup 1.0000x reference)
;     __device__ __forceinline__ bool next(int i, Unit& u) const { if (i >= n) return false; int o = own; asm volatile("" : "+s"(o)); u.pm = swap ? i : o; u.pn = swap ? o : i; u.idx = i; return true; }
; #define PG8_STAGE(bufoff, gbase, voff) do { _Pragma("unroll") for (int _i = 0; _i < 2; ++_i) \
;         __builtin_amdgcn_global_load_lds((const unsigned*)((const char*)(gbase) + (voff)[_i]), (PG8_LAS unsigned*)(lds + (bufoff) + ldsw + _i * 8192), 16, 0, 0); } while (0)
; #define PG8_LDA(dst, b, h) do { _Pragma("unroll") for (int m = 0; m < 4; ++m) _Pragma("unroll") for (int k = 0; k < 2; ++k) dst[m][k] = *(const PG8_LAS bf16x8*)(lds + PG8_SA(b, h) + aoff + m * 2048 + k * 1024); } while (0)
; #define PG8_LDB(dst, b, h) do { _Pragma("unroll") for (int n = 0; n < 2; ++n) _Pragma("unroll") for (int k = 0; k < 2; ++k) dst[n][k] = *(const PG8_LAS bf16x8*)(lds + PG8_SB(b, h) + boff + n * 2048 + k * 1024); } while (0)
; #define PG8_WAIT_V(n) asm volatile("s_waitcnt vmcnt(" #n ")" ::: "memory")
; template <class Epi, class Sched, bool ALIGN_EPI = false, bool SP2 = false>
; __device__ __forceinline__ void gemm_phase(PG8_LAS unsigned char* lds, const Gemm g, const Sched& S, const Epi& E, int tid_in) {
;     ...
;         const bool has_next = S.next(ui + 1, nxt);
;         const char* nA = has_next ? (const char*)g.A + (size_t)nxt.pm * tstep : cA; const char* nB = has_next ? (const char*)g.Bt + (size_t)nxt.pn * tstep : cB;
;         for (int t = 0; t < nt; t += 2) {
;             const bool last = (t == nt - 2);
;             const char* a1 = cA + (size_t)(t + 1) * kstep;
;             const char* a2 = last ? nA : cA + (size_t)(t + 2) * kstep; const char* b2 = last ? nB : cB + (size_t)(t + 2) * kstep;
;             const char* a3 = a2 + kstep; const char* b3 = b2 + kstep;
;             if (last && has_next) S.a_ready(nxt);
;             if constexpr (SP2) {
;             PG8_LDB(B0, 0, 0); PG8_LDB(B1, 0, 1); PG8_SCHED; PG8_LDA(At, 0, 0); PG8_STAGE(PG8_SA(1, 1), a1 + hstep, voffA);
;             PG8_WAIT_V(8); PG8_WAIT_L(0); PG8_BAR; PG8_MMA(0, 0, At, B0); PG8_MMA(0, 1, At, B1); PG8_BAR; PG8_SCHED;
;             PG8_LDA(At, 0, 1); PG8_STAGE(PG8_SB(0, 0), b2, voffB); PG8_STAGE(PG8_SB(0, 1), b2 + hstep, voffB); PG8_STAGE(PG8_SA(0, 0), a2, voffA);
;             PG8_WAIT_V(8); PG8_WAIT_L(0); PG8_BAR; PG8_MMA(1, 0, At, B0); PG8_MMA(1, 1, At, B1); PG8_BAR; PG8_SCHED;
.LBB0_190:
	s_ashr_i32 s41, s40, 31
	s_lshl_b64 s[46:47], s[40:41], 19
	s_add_u32 s46, s59, s46
	s_addc_u32 s47, s60, s47
	s_and_b64 s[48:49], s[44:45], exec
	s_cselect_b32 s41, s47, s51
	s_cselect_b32 s79, s46, s50
	s_ashr_i32 s43, s42, 31
	s_lshl_b64 s[48:49], s[42:43], 19
	s_add_u32 s48, s33, s48
	s_addc_u32 s49, s56, s49
	s_and_b64 s[54:55], s[44:45], exec
	s_cselect_b32 s43, s49, s53
	s_cselect_b32 s80, s48, s52
	s_add_u32 s50, s50, 0x40080
	s_addc_u32 s51, s51, 0
	s_add_u32 s81, s52, 0x100
	s_addc_u32 s82, s53, 0
	s_mov_b32 s83, -2
	s_add_i32 s84, 0, 0x10000
	v_add_u32_e32 v149, s84, v147
	s_add_i32 s86, 0, 0x14000
	ds_read_b128 v[142:145], v149
	ds_read_b128 v[150:153], v149 offset:1024
	ds_read_b128 v[154:157], v149 offset:2048
	ds_read_b128 v[158:161], v149 offset:3072
	v_add_u32_e32 v149, s86, v147
	ds_read_b128 v[162:165], v149
	ds_read_b128 v[166:169], v149 offset:1024
	ds_read_b128 v[170:173], v149 offset:2048
	ds_read_b128 v[174:177], v149 offset:3072
	s_add_u32 s52, s50, 0xfffc0080
	s_addc_u32 s53, s51, -1
	s_cmp_eq_u32 s83, 12
	s_cselect_b32 s55, s41, s53
	s_cselect_b32 s54, s79, s52
	s_cselect_b32 s53, s43, s82
	s_cselect_b32 s52, s80, s81
	v_lshl_add_u64 v[220:221], s[50:51], 0, v[138:139]
	s_add_i32 m0, s61, 0xc000
	ds_read_b128 v[178:181], v148
	ds_read_b128 v[182:185], v148 offset:1024
	ds_read_b128 v[196:199], v148 offset:2048
	ds_read_b128 v[200:203], v148 offset:3072
	ds_read_b128 v[204:207], v148 offset:4096
	ds_read_b128 v[208:211], v148 offset:5120
	ds_read_b128 v[212:215], v148 offset:6144
	ds_read_b128 v[216:219], v148 offset:7168
	global_load_lds_dwordx4 v[220:221], off
	v_lshl_add_u64 v[220:221], s[50:51], 0, v[140:141]
	s_add_i32 m0, s61, 0xe000
	s_nop 0
	global_load_lds_dwordx4 v[220:221], off
	s_waitcnt vmcnt(8)
	s_waitcnt lgkmcnt(0)
	s_barrier
	s_setprio 1
	s_waitcnt lgkmcnt(0)
	v_mfma_f32_16x16x32_bf16 v[126:129], v[142:145], v[178:181], 0
	v_mfma_f32_16x16x32_bf16 v[122:125], v[154:157], v[178:181], 0
	v_mfma_f32_16x16x32_bf16 v[110:113], v[142:145], v[196:199], 0
	v_mfma_f32_16x16x32_bf16 v[106:109], v[154:157], v[196:199], 0
	v_mfma_f32_16x16x32_bf16 v[94:97], v[142:145], v[204:207], 0
	v_mfma_f32_16x16x32_bf16 v[90:93], v[154:157], v[204:207], 0
	v_mfma_f32_16x16x32_bf16 v[78:81], v[142:145], v[212:215], 0
	v_mfma_f32_16x16x32_bf16 v[74:77], v[154:157], v[212:215], 0
	v_mfma_f32_16x16x32_bf16 v[126:129], v[150:153], v[182:185], v[126:129]
	v_mfma_f32_16x16x32_bf16 v[122:125], v[158:161], v[182:185], v[122:125]
	v_mfma_f32_16x16x32_bf16 v[110:113], v[150:153], v[200:203], v[110:113]
	v_mfma_f32_16x16x32_bf16 v[106:109], v[158:161], v[200:203], v[106:109]
	v_mfma_f32_16x16x32_bf16 v[94:97], v[150:153], v[208:211], v[94:97]
	v_mfma_f32_16x16x32_bf16 v[90:93], v[158:161], v[208:211], v[90:93]
	v_mfma_f32_16x16x32_bf16 v[78:81], v[150:153], v[216:219], v[78:81]
	v_mfma_f32_16x16x32_bf16 v[74:77], v[158:161], v[216:219], v[74:77]
	s_setprio 0
	s_setprio 1
	v_mfma_f32_16x16x32_bf16 v[118:121], v[162:165], v[178:181], 0
	v_mfma_f32_16x16x32_bf16 v[114:117], v[170:173], v[178:181], 0
	v_mfma_f32_16x16x32_bf16 v[102:105], v[162:165], v[196:199], 0
	v_mfma_f32_16x16x32_bf16 v[98:101], v[170:173], v[196:199], 0
	v_mfma_f32_16x16x32_bf16 v[86:89], v[162:165], v[204:207], 0
	v_mfma_f32_16x16x32_bf16 v[82:85], v[170:173], v[204:207], 0
	v_mfma_f32_16x16x32_bf16 v[70:73], v[162:165], v[212:215], 0
	v_mfma_f32_16x16x32_bf16 v[66:69], v[170:173], v[212:215], 0
	v_mfma_f32_16x16x32_bf16 v[118:121], v[166:169], v[182:185], v[118:121]
	v_mfma_f32_16x16x32_bf16 v[114:117], v[174:177], v[182:185], v[114:117]
	v_mfma_f32_16x16x32_bf16 v[102:105], v[166:169], v[200:203], v[102:105]
	v_mfma_f32_16x16x32_bf16 v[98:101], v[174:177], v[200:203], v[98:101]
	v_mfma_f32_16x16x32_bf16 v[86:89], v[166:169], v[208:211], v[86:89]
	v_mfma_f32_16x16x32_bf16 v[82:85], v[174:177], v[208:211], v[82:85]
	v_mfma_f32_16x16x32_bf16 v[70:73], v[166:169], v[216:219], v[70:73]
	v_mfma_f32_16x16x32_bf16 v[66:69], v[174:177], v[216:219], v[66:69]
	s_setprio 0
	s_barrier
	s_add_i32 s84, s84, s57
	v_lshl_add_u64 v[220:221], s[52:53], 0, v[0:1]
	s_mov_b32 m0, s84
	ds_read_b128 v[178:181], v148 offset:16384
	ds_read_b128 v[182:185], v148 offset:17408
	ds_read_b128 v[196:199], v148 offset:18432
	ds_read_b128 v[200:203], v148 offset:19456
	ds_read_b128 v[204:207], v148 offset:20480
	ds_read_b128 v[208:211], v148 offset:21504
	ds_read_b128 v[212:215], v148 offset:22528
	ds_read_b128 v[216:219], v148 offset:23552
	global_load_lds_dwordx4 v[220:221], off
	s_add_i32 m0, s84, 0x2000
	s_add_u32 s84, s52, 0x40000
	v_lshl_add_u64 v[222:223], s[52:53], 0, v[132:133]
	s_addc_u32 s85, s53, 0
	s_add_i32 s86, s86, s57
	global_load_lds_dwordx4 v[222:223], off
	v_lshl_add_u64 v[224:225], s[84:85], 0, v[0:1]
	s_mov_b32 m0, s86
	v_lshl_add_u64 v[226:227], s[54:55], 0, v[134:135]
	global_load_lds_dwordx4 v[224:225], off
	v_lshl_add_u64 v[224:225], s[84:85], 0, v[132:133]
	s_add_i32 m0, s86, 0x2000
	s_nop 0
	global_load_lds_dwordx4 v[224:225], off
	v_lshl_add_u64 v[224:225], s[54:55], 0, v[136:137]
	s_mov_b32 m0, s61
	s_nop 0
	global_load_lds_dwordx4 v[224:225], off
	s_mov_b32 m0, s62
	s_nop 0
	global_load_lds_dwordx4 v[226:227], off
	s_waitcnt vmcnt(8)
	s_waitcnt lgkmcnt(0)
	s_barrier
; #define PG8_STAGE(bufoff, gbase, voff) do { _Pragma("unroll") for (int _i = 0; _i < 2; ++_i) \
;         __builtin_amdgcn_global_load_lds((const unsigned*)((const char*)(gbase) + (voff)[_i]), (PG8_LAS unsigned*)(lds + (bufoff) + ldsw + _i * 8192), 16, 0, 0); } while (0)
; #define PG8_LDA(dst, b, h) do { _Pragma("unroll") for (int m = 0; m < 4; ++m) _Pragma("unroll") for (int k = 0; k < 2; ++k) dst[m][k] = *(const PG8_LAS bf16x8*)(lds + PG8_SA(b, h) + aoff + m * 2048 + k * 1024); } while (0)
; #define PG8_LDB(dst, b, h) do { _Pragma("unroll") for (int n = 0; n < 2; ++n) _Pragma("unroll") for (int k = 0; k < 2; ++k) dst[n][k] = *(const PG8_LAS bf16x8*)(lds + PG8_SB(b, h) + boff + n * 2048 + k * 1024); } while (0)
; #define PG8_MMA(ai, bj, At, Bt) do { __builtin_amdgcn_s_setprio(1); _Pragma("unroll") for (int k = 0; k < 2; ++k) _Pragma("unroll") for (int m = 0; m < 4; ++m) _Pragma("unroll") for (int n = 0; n < 2; ++n) \
;         acc[ai][bj][m][n] = __builtin_amdgcn_mfma_f32_16x16x32_bf16(Bt[n][k], At[m][k], acc[ai][bj][m][n], 0, 0, 0); __builtin_amdgcn_s_setprio(0); } while (0)
; #define PG8_WAIT_V(n) asm volatile("s_waitcnt vmcnt(" #n ")" ::: "memory")
; #define PG8_WAIT_L(n) asm volatile("s_waitcnt lgkmcnt(" #n ")" ::: "memory")
; #define PG8_BAR __builtin_amdgcn_s_barrier()
; #define PG8_SCHED __builtin_amdgcn_sched_barrier(0)
; template <class Epi, class Sched, bool ALIGN_EPI = false, bool SP2 = false>
; __device__ __forceinline__ void gemm_phase(PG8_LAS unsigned char* lds, const Gemm g, const Sched& S, const Epi& E, int tid_in) {
;     ...
;             PG8_WAIT_V(8); PG8_WAIT_L(0); PG8_BAR; PG8_MMA(1, 0, At, B0); PG8_MMA(1, 1, At, B1); PG8_BAR; PG8_SCHED;
;             PG8_LDB(B0, 1, 0); PG8_LDB(B1, 1, 1); PG8_SCHED; PG8_LDA(At, 1, 0); PG8_STAGE(PG8_SA(0, 1), a2 + hstep, voffA);
;             PG8_WAIT_V(8); PG8_WAIT_L(0); PG8_BAR; PG8_MMA(0, 0, At, B0); PG8_MMA(0, 1, At, B1); PG8_BAR; PG8_SCHED;
	s_setprio 1
	s_waitcnt lgkmcnt(0)
	v_mfma_f32_16x16x32_bf16 v[62:65], v[142:145], v[178:181], 0
	v_mfma_f32_16x16x32_bf16 v[58:61], v[154:157], v[178:181], 0
	v_mfma_f32_16x16x32_bf16 v[46:49], v[142:145], v[196:199], 0
	v_mfma_f32_16x16x32_bf16 v[42:45], v[154:157], v[196:199], 0
	v_mfma_f32_16x16x32_bf16 v[30:33], v[142:145], v[204:207], 0
	v_mfma_f32_16x16x32_bf16 v[26:29], v[154:157], v[204:207], 0
	v_mfma_f32_16x16x32_bf16 v[14:17], v[142:145], v[212:215], 0
	v_mfma_f32_16x16x32_bf16 v[10:13], v[154:157], v[212:215], 0
	v_mfma_f32_16x16x32_bf16 v[62:65], v[150:153], v[182:185], v[62:65]
	v_mfma_f32_16x16x32_bf16 v[58:61], v[158:161], v[182:185], v[58:61]
	v_mfma_f32_16x16x32_bf16 v[46:49], v[150:153], v[200:203], v[46:49]
	v_mfma_f32_16x16x32_bf16 v[42:45], v[158:161], v[200:203], v[42:45]
	v_mfma_f32_16x16x32_bf16 v[30:33], v[150:153], v[208:211], v[30:33]
	v_mfma_f32_16x16x32_bf16 v[26:29], v[158:161], v[208:211], v[26:29]
	v_mfma_f32_16x16x32_bf16 v[14:17], v[150:153], v[216:219], v[14:17]
	v_mfma_f32_16x16x32_bf16 v[10:13], v[158:161], v[216:219], v[10:13]
	s_setprio 0
	s_setprio 1
	v_mfma_f32_16x16x32_bf16 v[54:57], v[162:165], v[178:181], 0
	v_mfma_f32_16x16x32_bf16 v[50:53], v[170:173], v[178:181], 0
	v_mfma_f32_16x16x32_bf16 v[38:41], v[162:165], v[196:199], 0
	v_mfma_f32_16x16x32_bf16 v[34:37], v[170:173], v[196:199], 0
	v_mfma_f32_16x16x32_bf16 v[22:25], v[162:165], v[204:207], 0
	v_mfma_f32_16x16x32_bf16 v[18:21], v[170:173], v[204:207], 0
	v_mfma_f32_16x16x32_bf16 v[6:9], v[162:165], v[212:215], 0
	v_mfma_f32_16x16x32_bf16 v[2:5], v[170:173], v[212:215], 0
	v_mfma_f32_16x16x32_bf16 v[54:57], v[166:169], v[182:185], v[54:57]
	v_mfma_f32_16x16x32_bf16 v[50:53], v[174:177], v[182:185], v[50:53]
	v_mfma_f32_16x16x32_bf16 v[38:41], v[166:169], v[200:203], v[38:41]
	v_mfma_f32_16x16x32_bf16 v[34:37], v[174:177], v[200:203], v[34:37]
	v_mfma_f32_16x16x32_bf16 v[22:25], v[166:169], v[208:211], v[22:25]
	v_mfma_f32_16x16x32_bf16 v[18:21], v[174:177], v[208:211], v[18:21]
	v_mfma_f32_16x16x32_bf16 v[6:9], v[166:169], v[216:219], v[6:9]
	v_mfma_f32_16x16x32_bf16 v[2:5], v[174:177], v[216:219], v[2:5]
	s_setprio 0
	s_barrier
	s_add_i32 s84, 0, 0x18000
	v_add_u32_e32 v149, s84, v147
	s_add_i32 s85, 0, 0x1c000
	ds_read_b128 v[142:145], v149
	ds_read_b128 v[150:153], v149 offset:1024
	ds_read_b128 v[154:157], v149 offset:2048
	ds_read_b128 v[158:161], v149 offset:3072
	v_add_u32_e32 v149, s85, v147
	ds_read_b128 v[162:165], v149
	ds_read_b128 v[166:169], v149 offset:1024
	ds_read_b128 v[170:173], v149 offset:2048
	ds_read_b128 v[174:177], v149 offset:3072
	s_add_u32 s54, s54, 0x40000
	s_addc_u32 s55, s55, 0
	s_mov_b32 m0, s63
	v_lshl_add_u64 v[228:229], s[54:55], 0, v[136:137]
	ds_read_b128 v[178:181], v148 offset:32768
	ds_read_b128 v[182:185], v148 offset:33792
	ds_read_b128 v[196:199], v148 offset:34816
	ds_read_b128 v[200:203], v148 offset:35840
	ds_read_b128 v[204:207], v148 offset:36864
	ds_read_b128 v[208:211], v148 offset:37888
	ds_read_b128 v[212:215], v148 offset:38912
	ds_read_b128 v[216:219], v148 offset:39936
	global_load_lds_dwordx4 v[228:229], off
	v_lshl_add_u64 v[228:229], s[54:55], 0, v[134:135]
	s_mov_b32 m0, s64
	s_nop 0
	global_load_lds_dwordx4 v[228:229], off
	s_waitcnt vmcnt(8)
	s_waitcnt lgkmcnt(0)
	s_barrier
	s_setprio 1
	s_waitcnt lgkmcnt(0)
	v_mfma_f32_16x16x32_bf16 v[126:129], v[142:145], v[178:181], v[126:129]
	v_mfma_f32_16x16x32_bf16 v[122:125], v[154:157], v[178:181], v[122:125]
	v_mfma_f32_16x16x32_bf16 v[110:113], v[142:145], v[196:199], v[110:113]
	v_mfma_f32_16x16x32_bf16 v[106:109], v[154:157], v[196:199], v[106:109]
	v_mfma_f32_16x16x32_bf16 v[94:97], v[142:145], v[204:207], v[94:97]
	v_mfma_f32_16x16x32_bf16 v[90:93], v[154:157], v[204:207], v[90:93]
	v_mfma_f32_16x16x32_bf16 v[78:81], v[142:145], v[212:215], v[78:81]
	v_mfma_f32_16x16x32_bf16 v[74:77], v[154:157], v[212:215], v[74:77]
	v_mfma_f32_16x16x32_bf16 v[126:129], v[150:153], v[182:185], v[126:129]
	v_mfma_f32_16x16x32_bf16 v[122:125], v[158:161], v[182:185], v[122:125]
	v_mfma_f32_16x16x32_bf16 v[110:113], v[150:153], v[200:203], v[110:113]
	v_mfma_f32_16x16x32_bf16 v[106:109], v[158:161], v[200:203], v[106:109]
	v_mfma_f32_16x16x32_bf16 v[94:97], v[150:153], v[208:211], v[94:97]
	v_mfma_f32_16x16x32_bf16 v[90:93], v[158:161], v[208:211], v[90:93]
	v_mfma_f32_16x16x32_bf16 v[78:81], v[150:153], v[216:219], v[78:81]
	v_mfma_f32_16x16x32_bf16 v[74:77], v[158:161], v[216:219], v[74:77]
	s_setprio 0
	s_setprio 1
	v_mfma_f32_16x16x32_bf16 v[118:121], v[162:165], v[178:181], v[118:121]
	v_mfma_f32_16x16x32_bf16 v[114:117], v[170:173], v[178:181], v[114:117]
	v_mfma_f32_16x16x32_bf16 v[102:105], v[162:165], v[196:199], v[102:105]
	v_mfma_f32_16x16x32_bf16 v[98:101], v[170:173], v[196:199], v[98:101]
	v_mfma_f32_16x16x32_bf16 v[86:89], v[162:165], v[204:207], v[86:89]
	v_mfma_f32_16x16x32_bf16 v[82:85], v[170:173], v[204:207], v[82:85]
	v_mfma_f32_16x16x32_bf16 v[70:73], v[162:165], v[212:215], v[70:73]
	v_mfma_f32_16x16x32_bf16 v[66:69], v[170:173], v[212:215], v[66:69]
	v_mfma_f32_16x16x32_bf16 v[118:121], v[166:169], v[182:185], v[118:121]
	v_mfma_f32_16x16x32_bf16 v[114:117], v[174:177], v[182:185], v[114:117]
	v_mfma_f32_16x16x32_bf16 v[102:105], v[166:169], v[200:203], v[102:105]
	v_mfma_f32_16x16x32_bf16 v[98:101], v[174:177], v[200:203], v[98:101]
	v_mfma_f32_16x16x32_bf16 v[86:89], v[166:169], v[208:211], v[86:89]
	v_mfma_f32_16x16x32_bf16 v[82:85], v[174:177], v[208:211], v[82:85]
	v_mfma_f32_16x16x32_bf16 v[70:73], v[166:169], v[216:219], v[70:73]
	v_mfma_f32_16x16x32_bf16 v[66:69], v[174:177], v[216:219], v[66:69]
	s_setprio 0
	s_barrier
; #define PG8_STAGE(bufoff, gbase, voff) do { _Pragma("unroll") for (int _i = 0; _i < 2; ++_i) \
;         __builtin_amdgcn_global_load_lds((const unsigned*)((const char*)(gbase) + (voff)[_i]), (PG8_LAS unsigned*)(lds + (bufoff) + ldsw + _i * 8192), 16, 0, 0); } while (0)
; #define PG8_LDA(dst, b, h) do { _Pragma("unroll") for (int m = 0; m < 4; ++m) _Pragma("unroll") for (int k = 0; k < 2; ++k) dst[m][k] = *(const PG8_LAS bf16x8*)(lds + PG8_SA(b, h) + aoff + m * 2048 + k * 1024); } while (0)
; #define PG8_LDB(dst, b, h) do { _Pragma("unroll") for (int n = 0; n < 2; ++n) _Pragma("unroll") for (int k = 0; k < 2; ++k) dst[n][k] = *(const PG8_LAS bf16x8*)(lds + PG8_SB(b, h) + boff + n * 2048 + k * 1024); } while (0)
; #define PG8_MMA(ai, bj, At, Bt) do { __builtin_amdgcn_s_setprio(1); _Pragma("unroll") for (int k = 0; k < 2; ++k) _Pragma("unroll") for (int m = 0; m < 4; ++m) _Pragma("unroll") for (int n = 0; n < 2; ++n) \
;         acc[ai][bj][m][n] = __builtin_amdgcn_mfma_f32_16x16x32_bf16(Bt[n][k], At[m][k], acc[ai][bj][m][n], 0, 0, 0); __builtin_amdgcn_s_setprio(0); } while (0)
; #define PG8_WAIT_V(n) asm volatile("s_waitcnt vmcnt(" #n ")" ::: "memory")
; #define PG8_BAR __builtin_amdgcn_s_barrier()
; template <class Epi, class Sched, bool ALIGN_EPI = false, bool SP2 = false>
; __device__ __forceinline__ void gemm_phase(PG8_LAS unsigned char* lds, const Gemm g, const Sched& S, const Epi& E, int tid_in) {
;     ...
;         for (int t = 0; t < nt; t += 2) {
;             const bool last = (t == nt - 2);
;             const char* a1 = cA + (size_t)(t + 1) * kstep;
;             const char* a2 = last ? nA : cA + (size_t)(t + 2) * kstep; const char* b2 = last ? nB : cB + (size_t)(t + 2) * kstep;
;             const char* a3 = a2 + kstep; const char* b3 = b2 + kstep;
;             if (last && has_next) S.a_ready(nxt);
;             if constexpr (SP2) {
;             PG8_LDB(B0, 0, 0); PG8_LDB(B1, 0, 1); PG8_SCHED; PG8_LDA(At, 0, 0); PG8_STAGE(PG8_SA(1, 1), a1 + hstep, voffA);
;             PG8_WAIT_V(8); PG8_WAIT_L(0); PG8_BAR; PG8_MMA(0, 0, At, B0); PG8_MMA(0, 1, At, B1); PG8_BAR; PG8_SCHED;
;     ...
;             PG8_LDA(At, 1, 1); PG8_STAGE(PG8_SB(1, 0), b3, voffB); PG8_STAGE(PG8_SB(1, 1), b3 + hstep, voffB); PG8_STAGE(PG8_SA(1, 0), a3, voffA);
;             PG8_WAIT_V(8); PG8_WAIT_L(0); PG8_BAR; PG8_MMA(1, 0, At, B0); PG8_MMA(1, 1, At, B1); PG8_BAR; PG8_SCHED;
	s_add_i32 s54, s84, s57
	v_lshl_add_u64 v[220:221], v[220:221], 0, s[26:27]
	s_mov_b32 m0, s54
	ds_read_b128 v[178:181], v148 offset:49152
	ds_read_b128 v[182:185], v148 offset:50176
	ds_read_b128 v[196:199], v148 offset:51200
	ds_read_b128 v[200:203], v148 offset:52224
	ds_read_b128 v[204:207], v148 offset:53248
	ds_read_b128 v[208:211], v148 offset:54272
	ds_read_b128 v[212:215], v148 offset:55296
	ds_read_b128 v[216:219], v148 offset:56320
	global_load_lds_dwordx4 v[220:221], off
	s_add_i32 m0, s54, 0x2000
	s_add_u32 s52, s52, 0x40080
	v_lshl_add_u64 v[220:221], v[222:223], 0, s[26:27]
	s_addc_u32 s53, s53, 0
	s_add_i32 s54, s85, s57
	global_load_lds_dwordx4 v[220:221], off
	v_lshl_add_u64 v[220:221], s[52:53], 0, v[0:1]
	s_mov_b32 m0, s54
	s_nop 0
	global_load_lds_dwordx4 v[220:221], off
	v_lshl_add_u64 v[220:221], s[52:53], 0, v[132:133]
	s_add_i32 m0, s54, 0x2000
	s_nop 0
	global_load_lds_dwordx4 v[220:221], off
	v_lshl_add_u64 v[220:221], v[224:225], 0, s[26:27]
	s_mov_b32 m0, s69
	s_nop 0
	global_load_lds_dwordx4 v[220:221], off
	v_lshl_add_u64 v[220:221], v[226:227], 0, s[26:27]
	s_mov_b32 m0, s70
	s_nop 0
	global_load_lds_dwordx4 v[220:221], off
	s_waitcnt vmcnt(8)
	s_waitcnt lgkmcnt(0)
	s_barrier
	s_setprio 1
	s_waitcnt lgkmcnt(0)
	v_mfma_f32_16x16x32_bf16 v[62:65], v[142:145], v[178:181], v[62:65]
	v_mfma_f32_16x16x32_bf16 v[58:61], v[154:157], v[178:181], v[58:61]
	v_mfma_f32_16x16x32_bf16 v[46:49], v[142:145], v[196:199], v[46:49]
	v_mfma_f32_16x16x32_bf16 v[42:45], v[154:157], v[196:199], v[42:45]
	v_mfma_f32_16x16x32_bf16 v[30:33], v[142:145], v[204:207], v[30:33]
	v_mfma_f32_16x16x32_bf16 v[26:29], v[154:157], v[204:207], v[26:29]
	v_mfma_f32_16x16x32_bf16 v[14:17], v[142:145], v[212:215], v[14:17]
	v_mfma_f32_16x16x32_bf16 v[10:13], v[154:157], v[212:215], v[10:13]
	v_mfma_f32_16x16x32_bf16 v[62:65], v[150:153], v[182:185], v[62:65]
	v_mfma_f32_16x16x32_bf16 v[58:61], v[158:161], v[182:185], v[58:61]
	v_mfma_f32_16x16x32_bf16 v[46:49], v[150:153], v[200:203], v[46:49]
	v_mfma_f32_16x16x32_bf16 v[42:45], v[158:161], v[200:203], v[42:45]
	v_mfma_f32_16x16x32_bf16 v[30:33], v[150:153], v[208:211], v[30:33]
	v_mfma_f32_16x16x32_bf16 v[26:29], v[158:161], v[208:211], v[26:29]
	v_mfma_f32_16x16x32_bf16 v[14:17], v[150:153], v[216:219], v[14:17]
	v_mfma_f32_16x16x32_bf16 v[10:13], v[158:161], v[216:219], v[10:13]
	s_setprio 0
	s_setprio 1
	v_mfma_f32_16x16x32_bf16 v[54:57], v[162:165], v[178:181], v[54:57]
	v_mfma_f32_16x16x32_bf16 v[50:53], v[170:173], v[178:181], v[50:53]
	v_mfma_f32_16x16x32_bf16 v[38:41], v[162:165], v[196:199], v[38:41]
	v_mfma_f32_16x16x32_bf16 v[34:37], v[170:173], v[196:199], v[34:37]
	v_mfma_f32_16x16x32_bf16 v[22:25], v[162:165], v[204:207], v[22:25]
	v_mfma_f32_16x16x32_bf16 v[18:21], v[170:173], v[204:207], v[18:21]
	v_mfma_f32_16x16x32_bf16 v[6:9], v[162:165], v[212:215], v[6:9]
	v_mfma_f32_16x16x32_bf16 v[2:5], v[170:173], v[212:215], v[2:5]
	v_mfma_f32_16x16x32_bf16 v[54:57], v[166:169], v[182:185], v[54:57]
	v_mfma_f32_16x16x32_bf16 v[50:53], v[174:177], v[182:185], v[50:53]
	v_mfma_f32_16x16x32_bf16 v[38:41], v[166:169], v[200:203], v[38:41]
	v_mfma_f32_16x16x32_bf16 v[34:37], v[174:177], v[200:203], v[34:37]
	v_mfma_f32_16x16x32_bf16 v[22:25], v[166:169], v[208:211], v[22:25]
	v_mfma_f32_16x16x32_bf16 v[18:21], v[174:177], v[208:211], v[18:21]
	v_mfma_f32_16x16x32_bf16 v[6:9], v[166:169], v[216:219], v[6:9]
	v_mfma_f32_16x16x32_bf16 v[2:5], v[174:177], v[216:219], v[2:5]
	s_setprio 0
	s_add_i32 s83, s83, 2
	s_add_u32 s50, s50, 0x100
	s_addc_u32 s51, s51, 0
	s_add_u32 s81, s81, 0x100
	s_addc_u32 s82, s82, 0
	s_cmp_gt_u32 s83, 13
	s_barrier
.LBB0_191:
	s_add_i32 s84, 0, 0x10000
	v_add_u32_e32 v149, s84, v147
	s_add_i32 s86, 0, 0x14000
	ds_read_b128 v[142:145], v149
	ds_read_b128 v[150:153], v149 offset:1024
	ds_read_b128 v[154:157], v149 offset:2048
	ds_read_b128 v[158:161], v149 offset:3072
	v_add_u32_e32 v149, s86, v147
	ds_read_b128 v[162:165], v149
	ds_read_b128 v[166:169], v149 offset:1024
	ds_read_b128 v[170:173], v149 offset:2048
	ds_read_b128 v[174:177], v149 offset:3072
	s_add_u32 s52, s50, 0xfffc0080
	s_addc_u32 s53, s51, -1
	s_cmp_eq_u32 s83, 12
	s_cselect_b32 s55, s41, s53
	s_cselect_b32 s54, s79, s52
	s_cselect_b32 s53, s43, s82
	s_cselect_b32 s52, s80, s81
	v_lshl_add_u64 v[220:221], s[50:51], 0, v[138:139]
	s_add_i32 m0, s61, 0xc000
	ds_read_b128 v[178:181], v148
	ds_read_b128 v[182:185], v148 offset:1024
	ds_read_b128 v[196:199], v148 offset:2048
	ds_read_b128 v[200:203], v148 offset:3072
	ds_read_b128 v[204:207], v148 offset:4096
	ds_read_b128 v[208:211], v148 offset:5120
	ds_read_b128 v[212:215], v148 offset:6144
	ds_read_b128 v[216:219], v148 offset:7168
	global_load_lds_dwordx4 v[220:221], off
	v_lshl_add_u64 v[220:221], s[50:51], 0, v[140:141]
	s_add_i32 m0, s61, 0xe000
	s_nop 0
	global_load_lds_dwordx4 v[220:221], off
	s_waitcnt vmcnt(8)
	s_waitcnt lgkmcnt(0)
	s_barrier
; #define PG8_STAGE(bufoff, gbase, voff) do { _Pragma("unroll") for (int _i = 0; _i < 2; ++_i) \
;         __builtin_amdgcn_global_load_lds((const unsigned*)((const char*)(gbase) + (voff)[_i]), (PG8_LAS unsigned*)(lds + (bufoff) + ldsw + _i * 8192), 16, 0, 0); } while (0)
; #define PG8_LDA(dst, b, h) do { _Pragma("unroll") for (int m = 0; m < 4; ++m) _Pragma("unroll") for (int k = 0; k < 2; ++k) dst[m][k] = *(const PG8_LAS bf16x8*)(lds + PG8_SA(b, h) + aoff + m * 2048 + k * 1024); } while (0)
; #define PG8_LDB(dst, b, h) do { _Pragma("unroll") for (int n = 0; n < 2; ++n) _Pragma("unroll") for (int k = 0; k < 2; ++k) dst[n][k] = *(const PG8_LAS bf16x8*)(lds + PG8_SB(b, h) + boff + n * 2048 + k * 1024); } while (0)
; #define PG8_MMA(ai, bj, At, Bt) do { __builtin_amdgcn_s_setprio(1); _Pragma("unroll") for (int k = 0; k < 2; ++k) _Pragma("unroll") for (int m = 0; m < 4; ++m) _Pragma("unroll") for (int n = 0; n < 2; ++n) \
;         acc[ai][bj][m][n] = __builtin_amdgcn_mfma_f32_16x16x32_bf16(Bt[n][k], At[m][k], acc[ai][bj][m][n], 0, 0, 0); __builtin_amdgcn_s_setprio(0); } while (0)
; #define PG8_WAIT_V(n) asm volatile("s_waitcnt vmcnt(" #n ")" ::: "memory")
; #define PG8_WAIT_L(n) asm volatile("s_waitcnt lgkmcnt(" #n ")" ::: "memory")
; #define PG8_BAR __builtin_amdgcn_s_barrier()
; #define PG8_SCHED __builtin_amdgcn_sched_barrier(0)
; template <class Epi, class Sched, bool ALIGN_EPI = false, bool SP2 = false>
; __device__ __forceinline__ void gemm_phase(PG8_LAS unsigned char* lds, const Gemm g, const Sched& S, const Epi& E, int tid_in) {
;     ...
;             PG8_LDB(B0, 0, 0); PG8_LDB(B1, 0, 1); PG8_SCHED; PG8_LDA(At, 0, 0); PG8_STAGE(PG8_SA(1, 1), a1 + hstep, voffA);
;             PG8_WAIT_V(8); PG8_WAIT_L(0); PG8_BAR; PG8_MMA(0, 0, At, B0); PG8_MMA(0, 1, At, B1); PG8_BAR; PG8_SCHED;
;             PG8_LDA(At, 0, 1); PG8_STAGE(PG8_SB(0, 0), b2, voffB); PG8_STAGE(PG8_SB(0, 1), b2 + hstep, voffB); PG8_STAGE(PG8_SA(0, 0), a2, voffA);
;             PG8_WAIT_V(8); PG8_WAIT_L(0); PG8_BAR; PG8_MMA(1, 0, At, B0); PG8_MMA(1, 1, At, B1); PG8_BAR; PG8_SCHED;
	s_setprio 1
	s_waitcnt lgkmcnt(0)
	v_mfma_f32_16x16x32_bf16 v[126:129], v[142:145], v[178:181], v[126:129]
	v_mfma_f32_16x16x32_bf16 v[122:125], v[154:157], v[178:181], v[122:125]
	v_mfma_f32_16x16x32_bf16 v[110:113], v[142:145], v[196:199], v[110:113]
	v_mfma_f32_16x16x32_bf16 v[106:109], v[154:157], v[196:199], v[106:109]
	v_mfma_f32_16x16x32_bf16 v[94:97], v[142:145], v[204:207], v[94:97]
	v_mfma_f32_16x16x32_bf16 v[90:93], v[154:157], v[204:207], v[90:93]
	v_mfma_f32_16x16x32_bf16 v[78:81], v[142:145], v[212:215], v[78:81]
	v_mfma_f32_16x16x32_bf16 v[74:77], v[154:157], v[212:215], v[74:77]
	v_mfma_f32_16x16x32_bf16 v[126:129], v[150:153], v[182:185], v[126:129]
	v_mfma_f32_16x16x32_bf16 v[122:125], v[158:161], v[182:185], v[122:125]
	v_mfma_f32_16x16x32_bf16 v[110:113], v[150:153], v[200:203], v[110:113]
	v_mfma_f32_16x16x32_bf16 v[106:109], v[158:161], v[200:203], v[106:109]
	v_mfma_f32_16x16x32_bf16 v[94:97], v[150:153], v[208:211], v[94:97]
	v_mfma_f32_16x16x32_bf16 v[90:93], v[158:161], v[208:211], v[90:93]
	v_mfma_f32_16x16x32_bf16 v[78:81], v[150:153], v[216:219], v[78:81]
	v_mfma_f32_16x16x32_bf16 v[74:77], v[158:161], v[216:219], v[74:77]
	s_setprio 0
	s_setprio 1
	v_mfma_f32_16x16x32_bf16 v[118:121], v[162:165], v[178:181], v[118:121]
	v_mfma_f32_16x16x32_bf16 v[114:117], v[170:173], v[178:181], v[114:117]
	v_mfma_f32_16x16x32_bf16 v[102:105], v[162:165], v[196:199], v[102:105]
	v_mfma_f32_16x16x32_bf16 v[98:101], v[170:173], v[196:199], v[98:101]
	v_mfma_f32_16x16x32_bf16 v[86:89], v[162:165], v[204:207], v[86:89]
	v_mfma_f32_16x16x32_bf16 v[82:85], v[170:173], v[204:207], v[82:85]
	v_mfma_f32_16x16x32_bf16 v[70:73], v[162:165], v[212:215], v[70:73]
	v_mfma_f32_16x16x32_bf16 v[66:69], v[170:173], v[212:215], v[66:69]
	v_mfma_f32_16x16x32_bf16 v[118:121], v[166:169], v[182:185], v[118:121]
	v_mfma_f32_16x16x32_bf16 v[114:117], v[174:177], v[182:185], v[114:117]
	v_mfma_f32_16x16x32_bf16 v[102:105], v[166:169], v[200:203], v[102:105]
	v_mfma_f32_16x16x32_bf16 v[98:101], v[174:177], v[200:203], v[98:101]
	v_mfma_f32_16x16x32_bf16 v[86:89], v[166:169], v[208:211], v[86:89]
	v_mfma_f32_16x16x32_bf16 v[82:85], v[174:177], v[208:211], v[82:85]
	v_mfma_f32_16x16x32_bf16 v[70:73], v[166:169], v[216:219], v[70:73]
	v_mfma_f32_16x16x32_bf16 v[66:69], v[174:177], v[216:219], v[66:69]
	s_setprio 0
	s_barrier
	s_add_i32 s84, s84, s57
	v_lshl_add_u64 v[220:221], s[52:53], 0, v[0:1]
	s_mov_b32 m0, s84
	ds_read_b128 v[178:181], v148 offset:16384
	ds_read_b128 v[182:185], v148 offset:17408
	ds_read_b128 v[196:199], v148 offset:18432
	ds_read_b128 v[200:203], v148 offset:19456
	ds_read_b128 v[204:207], v148 offset:20480
	ds_read_b128 v[208:211], v148 offset:21504
	ds_read_b128 v[212:215], v148 offset:22528
	ds_read_b128 v[216:219], v148 offset:23552
	global_load_lds_dwordx4 v[220:221], off
	s_add_i32 m0, s84, 0x2000
	s_add_u32 s84, s52, 0x40000
	v_lshl_add_u64 v[222:223], s[52:53], 0, v[132:133]
	s_addc_u32 s85, s53, 0
	s_add_i32 s86, s86, s57
	global_load_lds_dwordx4 v[222:223], off
	v_lshl_add_u64 v[224:225], s[84:85], 0, v[0:1]
	s_mov_b32 m0, s86
	v_lshl_add_u64 v[226:227], s[54:55], 0, v[134:135]
	global_load_lds_dwordx4 v[224:225], off
	v_lshl_add_u64 v[224:225], s[84:85], 0, v[132:133]
	s_add_i32 m0, s86, 0x2000
	s_nop 0
	global_load_lds_dwordx4 v[224:225], off
	v_lshl_add_u64 v[224:225], s[54:55], 0, v[136:137]
	s_mov_b32 m0, s61
	s_nop 0
	global_load_lds_dwordx4 v[224:225], off
	s_mov_b32 m0, s62
	s_nop 0
	global_load_lds_dwordx4 v[226:227], off
	s_waitcnt vmcnt(8)
	s_waitcnt lgkmcnt(0)
	s_barrier
	s_setprio 1
	s_waitcnt lgkmcnt(0)
	v_mfma_f32_16x16x32_bf16 v[62:65], v[142:145], v[178:181], v[62:65]
	v_mfma_f32_16x16x32_bf16 v[58:61], v[154:157], v[178:181], v[58:61]
	v_mfma_f32_16x16x32_bf16 v[46:49], v[142:145], v[196:199], v[46:49]
	v_mfma_f32_16x16x32_bf16 v[42:45], v[154:157], v[196:199], v[42:45]
	v_mfma_f32_16x16x32_bf16 v[30:33], v[142:145], v[204:207], v[30:33]
	v_mfma_f32_16x16x32_bf16 v[26:29], v[154:157], v[204:207], v[26:29]
	v_mfma_f32_16x16x32_bf16 v[14:17], v[142:145], v[212:215], v[14:17]
	v_mfma_f32_16x16x32_bf16 v[10:13], v[154:157], v[212:215], v[10:13]
	v_mfma_f32_16x16x32_bf16 v[62:65], v[150:153], v[182:185], v[62:65]
	v_mfma_f32_16x16x32_bf16 v[58:61], v[158:161], v[182:185], v[58:61]
	v_mfma_f32_16x16x32_bf16 v[46:49], v[150:153], v[200:203], v[46:49]
	v_mfma_f32_16x16x32_bf16 v[42:45], v[158:161], v[200:203], v[42:45]
	v_mfma_f32_16x16x32_bf16 v[30:33], v[150:153], v[208:211], v[30:33]
	v_mfma_f32_16x16x32_bf16 v[26:29], v[158:161], v[208:211], v[26:29]
	v_mfma_f32_16x16x32_bf16 v[14:17], v[150:153], v[216:219], v[14:17]
	v_mfma_f32_16x16x32_bf16 v[10:13], v[158:161], v[216:219], v[10:13]
	s_setprio 0
	s_setprio 1
	v_mfma_f32_16x16x32_bf16 v[54:57], v[162:165], v[178:181], v[54:57]
	v_mfma_f32_16x16x32_bf16 v[50:53], v[170:173], v[178:181], v[50:53]
	v_mfma_f32_16x16x32_bf16 v[38:41], v[162:165], v[196:199], v[38:41]
	v_mfma_f32_16x16x32_bf16 v[34:37], v[170:173], v[196:199], v[34:37]
	v_mfma_f32_16x16x32_bf16 v[22:25], v[162:165], v[204:207], v[22:25]
	v_mfma_f32_16x16x32_bf16 v[18:21], v[170:173], v[204:207], v[18:21]
	v_mfma_f32_16x16x32_bf16 v[6:9], v[162:165], v[212:215], v[6:9]
	v_mfma_f32_16x16x32_bf16 v[2:5], v[170:173], v[212:215], v[2:5]
	v_mfma_f32_16x16x32_bf16 v[54:57], v[166:169], v[182:185], v[54:57]
	v_mfma_f32_16x16x32_bf16 v[50:53], v[174:177], v[182:185], v[50:53]
	v_mfma_f32_16x16x32_bf16 v[38:41], v[166:169], v[200:203], v[38:41]
	v_mfma_f32_16x16x32_bf16 v[34:37], v[174:177], v[200:203], v[34:37]
	v_mfma_f32_16x16x32_bf16 v[22:25], v[166:169], v[208:211], v[22:25]
	v_mfma_f32_16x16x32_bf16 v[18:21], v[174:177], v[208:211], v[18:21]
	v_mfma_f32_16x16x32_bf16 v[6:9], v[166:169], v[216:219], v[6:9]
	v_mfma_f32_16x16x32_bf16 v[2:5], v[174:177], v[216:219], v[2:5]
	s_setprio 0
	s_barrier
; #define PG8_STAGE(bufoff, gbase, voff) do { _Pragma("unroll") for (int _i = 0; _i < 2; ++_i) \
;         __builtin_amdgcn_global_load_lds((const unsigned*)((const char*)(gbase) + (voff)[_i]), (PG8_LAS unsigned*)(lds + (bufoff) + ldsw + _i * 8192), 16, 0, 0); } while (0)
; #define PG8_LDA(dst, b, h) do { _Pragma("unroll") for (int m = 0; m < 4; ++m) _Pragma("unroll") for (int k = 0; k < 2; ++k) dst[m][k] = *(const PG8_LAS bf16x8*)(lds + PG8_SA(b, h) + aoff + m * 2048 + k * 1024); } while (0)
; #define PG8_LDB(dst, b, h) do { _Pragma("unroll") for (int n = 0; n < 2; ++n) _Pragma("unroll") for (int k = 0; k < 2; ++k) dst[n][k] = *(const PG8_LAS bf16x8*)(lds + PG8_SB(b, h) + boff + n * 2048 + k * 1024); } while (0)
; #define PG8_MMA(ai, bj, At, Bt) do { __builtin_amdgcn_s_setprio(1); _Pragma("unroll") for (int k = 0; k < 2; ++k) _Pragma("unroll") for (int m = 0; m < 4; ++m) _Pragma("unroll") for (int n = 0; n < 2; ++n) \
;         acc[ai][bj][m][n] = __builtin_amdgcn_mfma_f32_16x16x32_bf16(Bt[n][k], At[m][k], acc[ai][bj][m][n], 0, 0, 0); __builtin_amdgcn_s_setprio(0); } while (0)
; #define PG8_WAIT_V(n) asm volatile("s_waitcnt vmcnt(" #n ")" ::: "memory")
; #define PG8_WAIT_L(n) asm volatile("s_waitcnt lgkmcnt(" #n ")" ::: "memory")
; #define PG8_BAR __builtin_amdgcn_s_barrier()
; #define PG8_SCHED __builtin_amdgcn_sched_barrier(0)
; template <class Epi, class Sched, bool ALIGN_EPI = false, bool SP2 = false>
; __device__ __forceinline__ void gemm_phase(PG8_LAS unsigned char* lds, const Gemm g, const Sched& S, const Epi& E, int tid_in) {
;     ...
;             PG8_LDB(B0, 1, 0); PG8_LDB(B1, 1, 1); PG8_SCHED; PG8_LDA(At, 1, 0); PG8_STAGE(PG8_SA(0, 1), a2 + hstep, voffA);
;             PG8_WAIT_V(8); PG8_WAIT_L(0); PG8_BAR; PG8_MMA(0, 0, At, B0); PG8_MMA(0, 1, At, B1); PG8_BAR; PG8_SCHED;
	s_add_i32 s84, 0, 0x18000
	v_add_u32_e32 v149, s84, v147
	s_add_i32 s85, 0, 0x1c000
	ds_read_b128 v[142:145], v149
	ds_read_b128 v[150:153], v149 offset:1024
	ds_read_b128 v[154:157], v149 offset:2048
	ds_read_b128 v[158:161], v149 offset:3072
	v_add_u32_e32 v149, s85, v147
	ds_read_b128 v[162:165], v149
	ds_read_b128 v[166:169], v149 offset:1024
	ds_read_b128 v[170:173], v149 offset:2048
	ds_read_b128 v[174:177], v149 offset:3072
	s_add_u32 s54, s54, 0x40000
	s_addc_u32 s55, s55, 0
	s_mov_b32 m0, s63
	v_lshl_add_u64 v[228:229], s[54:55], 0, v[136:137]
	ds_read_b128 v[178:181], v148 offset:32768
	ds_read_b128 v[182:185], v148 offset:33792
	ds_read_b128 v[196:199], v148 offset:34816
	ds_read_b128 v[200:203], v148 offset:35840
	ds_read_b128 v[204:207], v148 offset:36864
	ds_read_b128 v[208:211], v148 offset:37888
	ds_read_b128 v[212:215], v148 offset:38912
	ds_read_b128 v[216:219], v148 offset:39936
	global_load_lds_dwordx4 v[228:229], off
	v_lshl_add_u64 v[228:229], s[54:55], 0, v[134:135]
	s_mov_b32 m0, s64
	s_nop 0
	global_load_lds_dwordx4 v[228:229], off
	s_waitcnt vmcnt(8)
	s_waitcnt lgkmcnt(0)
	s_barrier
	s_setprio 1
	s_waitcnt lgkmcnt(0)
	v_mfma_f32_16x16x32_bf16 v[126:129], v[142:145], v[178:181], v[126:129]
	v_mfma_f32_16x16x32_bf16 v[122:125], v[154:157], v[178:181], v[122:125]
	v_mfma_f32_16x16x32_bf16 v[110:113], v[142:145], v[196:199], v[110:113]
	v_mfma_f32_16x16x32_bf16 v[106:109], v[154:157], v[196:199], v[106:109]
	v_mfma_f32_16x16x32_bf16 v[94:97], v[142:145], v[204:207], v[94:97]
	v_mfma_f32_16x16x32_bf16 v[90:93], v[154:157], v[204:207], v[90:93]
	v_mfma_f32_16x16x32_bf16 v[78:81], v[142:145], v[212:215], v[78:81]
	v_mfma_f32_16x16x32_bf16 v[74:77], v[154:157], v[212:215], v[74:77]
	v_mfma_f32_16x16x32_bf16 v[126:129], v[150:153], v[182:185], v[126:129]
	v_mfma_f32_16x16x32_bf16 v[122:125], v[158:161], v[182:185], v[122:125]
	v_mfma_f32_16x16x32_bf16 v[110:113], v[150:153], v[200:203], v[110:113]
	v_mfma_f32_16x16x32_bf16 v[106:109], v[158:161], v[200:203], v[106:109]
	v_mfma_f32_16x16x32_bf16 v[94:97], v[150:153], v[208:211], v[94:97]
	v_mfma_f32_16x16x32_bf16 v[90:93], v[158:161], v[208:211], v[90:93]
	v_mfma_f32_16x16x32_bf16 v[78:81], v[150:153], v[216:219], v[78:81]
	v_mfma_f32_16x16x32_bf16 v[74:77], v[158:161], v[216:219], v[74:77]
	s_setprio 0
	s_setprio 1
	v_mfma_f32_16x16x32_bf16 v[118:121], v[162:165], v[178:181], v[118:121]
	v_mfma_f32_16x16x32_bf16 v[114:117], v[170:173], v[178:181], v[114:117]
	v_mfma_f32_16x16x32_bf16 v[102:105], v[162:165], v[196:199], v[102:105]
	v_mfma_f32_16x16x32_bf16 v[98:101], v[170:173], v[196:199], v[98:101]
	v_mfma_f32_16x16x32_bf16 v[86:89], v[162:165], v[204:207], v[86:89]
	v_mfma_f32_16x16x32_bf16 v[82:85], v[170:173], v[204:207], v[82:85]
	v_mfma_f32_16x16x32_bf16 v[70:73], v[162:165], v[212:215], v[70:73]
	v_mfma_f32_16x16x32_bf16 v[66:69], v[170:173], v[212:215], v[66:69]
	v_mfma_f32_16x16x32_bf16 v[118:121], v[166:169], v[182:185], v[118:121]
	v_mfma_f32_16x16x32_bf16 v[114:117], v[174:177], v[182:185], v[114:117]
	v_mfma_f32_16x16x32_bf16 v[102:105], v[166:169], v[200:203], v[102:105]
	v_mfma_f32_16x16x32_bf16 v[98:101], v[174:177], v[200:203], v[98:101]
	v_mfma_f32_16x16x32_bf16 v[86:89], v[166:169], v[208:211], v[86:89]
	v_mfma_f32_16x16x32_bf16 v[82:85], v[174:177], v[208:211], v[82:85]
	v_mfma_f32_16x16x32_bf16 v[70:73], v[166:169], v[216:219], v[70:73]
	v_mfma_f32_16x16x32_bf16 v[66:69], v[174:177], v[216:219], v[66:69]
	s_setprio 0
	s_barrier
; #define PG8_STAGE(bufoff, gbase, voff) do { _Pragma("unroll") for (int _i = 0; _i < 2; ++_i) \
;         __builtin_amdgcn_global_load_lds((const unsigned*)((const char*)(gbase) + (voff)[_i]), (PG8_LAS unsigned*)(lds + (bufoff) + ldsw + _i * 8192), 16, 0, 0); } while (0)
; #define PG8_LDA(dst, b, h) do { _Pragma("unroll") for (int m = 0; m < 4; ++m) _Pragma("unroll") for (int k = 0; k < 2; ++k) dst[m][k] = *(const PG8_LAS bf16x8*)(lds + PG8_SA(b, h) + aoff + m * 2048 + k * 1024); } while (0)
; #define PG8_MMA(ai, bj, At, Bt) do { __builtin_amdgcn_s_setprio(1); _Pragma("unroll") for (int k = 0; k < 2; ++k) _Pragma("unroll") for (int m = 0; m < 4; ++m) _Pragma("unroll") for (int n = 0; n < 2; ++n) \
;         acc[ai][bj][m][n] = __builtin_amdgcn_mfma_f32_16x16x32_bf16(Bt[n][k], At[m][k], acc[ai][bj][m][n], 0, 0, 0); __builtin_amdgcn_s_setprio(0); } while (0)
; #define PG8_WAIT_V(n) asm volatile("s_waitcnt vmcnt(" #n ")" ::: "memory")
; #define PG8_WAIT_L(n) asm volatile("s_waitcnt lgkmcnt(" #n ")" ::: "memory")
; #define PG8_BAR __builtin_amdgcn_s_barrier()
; #define PG8_SCHED __builtin_amdgcn_sched_barrier(0)
; template <class Epi, class Sched, bool ALIGN_EPI = false, bool SP2 = false>
; __device__ __forceinline__ void gemm_phase(PG8_LAS unsigned char* lds, const Gemm g, const Sched& S, const Epi& E, int tid_in) {
;     ...
;             PG8_LDA(At, 1, 1); PG8_STAGE(PG8_SB(1, 0), b3, voffB); PG8_STAGE(PG8_SB(1, 1), b3 + hstep, voffB); PG8_STAGE(PG8_SA(1, 0), a3, voffA);
;             PG8_WAIT_V(8); PG8_WAIT_L(0); PG8_BAR; PG8_MMA(1, 0, At, B0); PG8_MMA(1, 1, At, B1); PG8_BAR; PG8_SCHED;
;     ...
;         if constexpr (ALIGN_EPI) { if (wr == 0) PG8_BAR; }
	s_add_i32 s54, s84, s57
	v_lshl_add_u64 v[220:221], v[220:221], 0, s[26:27]
	s_mov_b32 m0, s54
	ds_read_b128 v[178:181], v148 offset:49152
	ds_read_b128 v[182:185], v148 offset:50176
	ds_read_b128 v[196:199], v148 offset:51200
	ds_read_b128 v[200:203], v148 offset:52224
	ds_read_b128 v[204:207], v148 offset:53248
	ds_read_b128 v[208:211], v148 offset:54272
	ds_read_b128 v[212:215], v148 offset:55296
	ds_read_b128 v[216:219], v148 offset:56320
	global_load_lds_dwordx4 v[220:221], off
	s_add_i32 m0, s54, 0x2000
	s_add_u32 s52, s52, 0x40080
	v_lshl_add_u64 v[220:221], v[222:223], 0, s[26:27]
	s_addc_u32 s53, s53, 0
	s_add_i32 s54, s85, s57
	global_load_lds_dwordx4 v[220:221], off
	v_lshl_add_u64 v[220:221], s[52:53], 0, v[0:1]
	s_mov_b32 m0, s54
	s_nop 0
	global_load_lds_dwordx4 v[220:221], off
	v_lshl_add_u64 v[220:221], s[52:53], 0, v[132:133]
	s_add_i32 m0, s54, 0x2000
	s_nop 0
	global_load_lds_dwordx4 v[220:221], off
	v_lshl_add_u64 v[220:221], v[224:225], 0, s[26:27]
	s_mov_b32 m0, s69
	s_nop 0
	global_load_lds_dwordx4 v[220:221], off
	v_lshl_add_u64 v[220:221], v[226:227], 0, s[26:27]
	s_mov_b32 m0, s70
	s_nop 0
	global_load_lds_dwordx4 v[220:221], off
	s_waitcnt vmcnt(8)
	s_waitcnt lgkmcnt(0)
	s_barrier
	s_setprio 1
	s_waitcnt lgkmcnt(0)
	v_mfma_f32_16x16x32_bf16 v[62:65], v[142:145], v[178:181], v[62:65]
	v_mfma_f32_16x16x32_bf16 v[58:61], v[154:157], v[178:181], v[58:61]
	v_mfma_f32_16x16x32_bf16 v[46:49], v[142:145], v[196:199], v[46:49]
	v_mfma_f32_16x16x32_bf16 v[42:45], v[154:157], v[196:199], v[42:45]
	v_mfma_f32_16x16x32_bf16 v[30:33], v[142:145], v[204:207], v[30:33]
	v_mfma_f32_16x16x32_bf16 v[26:29], v[154:157], v[204:207], v[26:29]
	v_mfma_f32_16x16x32_bf16 v[14:17], v[142:145], v[212:215], v[14:17]
	v_mfma_f32_16x16x32_bf16 v[10:13], v[154:157], v[212:215], v[10:13]
	v_mfma_f32_16x16x32_bf16 v[62:65], v[150:153], v[182:185], v[62:65]
	v_mfma_f32_16x16x32_bf16 v[58:61], v[158:161], v[182:185], v[58:61]
	v_mfma_f32_16x16x32_bf16 v[46:49], v[150:153], v[200:203], v[46:49]
	v_mfma_f32_16x16x32_bf16 v[42:45], v[158:161], v[200:203], v[42:45]
	v_mfma_f32_16x16x32_bf16 v[30:33], v[150:153], v[208:211], v[30:33]
	v_mfma_f32_16x16x32_bf16 v[26:29], v[158:161], v[208:211], v[26:29]
	v_mfma_f32_16x16x32_bf16 v[14:17], v[150:153], v[216:219], v[14:17]
	v_mfma_f32_16x16x32_bf16 v[10:13], v[158:161], v[216:219], v[10:13]
	s_setprio 0
	s_setprio 1
	v_mfma_f32_16x16x32_bf16 v[54:57], v[162:165], v[178:181], v[54:57]
	v_mfma_f32_16x16x32_bf16 v[50:53], v[170:173], v[178:181], v[50:53]
	v_mfma_f32_16x16x32_bf16 v[38:41], v[162:165], v[196:199], v[38:41]
	v_mfma_f32_16x16x32_bf16 v[34:37], v[170:173], v[196:199], v[34:37]
	v_mfma_f32_16x16x32_bf16 v[22:25], v[162:165], v[204:207], v[22:25]
	v_mfma_f32_16x16x32_bf16 v[18:21], v[170:173], v[204:207], v[18:21]
	v_mfma_f32_16x16x32_bf16 v[6:9], v[162:165], v[212:215], v[6:9]
	v_mfma_f32_16x16x32_bf16 v[2:5], v[170:173], v[212:215], v[2:5]
	v_mfma_f32_16x16x32_bf16 v[54:57], v[166:169], v[182:185], v[54:57]
	v_mfma_f32_16x16x32_bf16 v[50:53], v[174:177], v[182:185], v[50:53]
	v_mfma_f32_16x16x32_bf16 v[38:41], v[166:169], v[200:203], v[38:41]
	v_mfma_f32_16x16x32_bf16 v[34:37], v[174:177], v[200:203], v[34:37]
	v_mfma_f32_16x16x32_bf16 v[22:25], v[166:169], v[208:211], v[22:25]
	v_mfma_f32_16x16x32_bf16 v[18:21], v[174:177], v[208:211], v[18:21]
	v_mfma_f32_16x16x32_bf16 v[6:9], v[166:169], v[216:219], v[6:9]
	v_mfma_f32_16x16x32_bf16 v[2:5], v[174:177], v[216:219], v[2:5]
	s_setprio 0
	s_add_i32 s83, s83, 2
	s_add_u32 s50, s50, 0x100
	s_addc_u32 s51, s51, 0
	s_add_u32 s81, s81, 0x100
	s_addc_u32 s82, s82, 0
	s_cmp_gt_u32 s83, 13
	s_barrier
	s_cbranch_scc0 .LBB0_191
	s_and_b64 vcc, exec, s[38:39]
	s_cbranch_vccz .LBB0_194
	s_barrier

;     __device__ __forceinline__ bool next(int i, Unit& u) const { if (i >= n) return false; int o = own; asm volatile("" : "+s"(o)); u.pm = swap ? i : o; u.pn = swap ? o : i; u.idx = i; return true; }
; #define PG8_STAGE(bufoff, gbase, voff) do { _Pragma("unroll") for (int _i = 0; _i < 2; ++_i) \
;         __builtin_amdgcn_global_load_lds((const unsigned*)((const char*)(gbase) + (voff)[_i]), (PG8_LAS unsigned*)(lds + (bufoff) + ldsw + _i * 8192), 16, 0, 0); } while (0)
; #define PG8_LDA(dst, b, h) do { _Pragma("unroll") for (int m = 0; m < 4; ++m) _Pragma("unroll") for (int k = 0; k < 2; ++k) dst[m][k] = *(const PG8_LAS bf16x8*)(lds + PG8_SA(b, h) + aoff + m * 2048 + k * 1024); } while (0)
; #define PG8_LDB(dst, b, h) do { _Pragma("unroll") for (int n = 0; n < 2; ++n) _Pragma("unroll") for (int k = 0; k < 2; ++k) dst[n][k] = *(const PG8_LAS bf16x8*)(lds + PG8_SB(b, h) + boff + n * 2048 + k * 1024); } while (0)
; #define PG8_WAIT_V(n) asm volatile("s_waitcnt vmcnt(" #n ")" ::: "memory")
; template <class Epi, class Sched, bool ALIGN_EPI = false, bool SP2 = false>
; __device__ __forceinline__ void gemm_phase(PG8_LAS unsigned char* lds, const Gemm g, const Sched& S, const Epi& E, int tid_in) {
;     ...
;         const bool has_next = S.next(ui + 1, nxt);
;         const char* nA = has_next ? (const char*)g.A + (size_t)nxt.pm * tstep : cA; const char* nB = has_next ? (const char*)g.Bt + (size_t)nxt.pn * tstep : cB;
;         for (int t = 0; t < nt; t += 2) {
;             const bool last = (t == nt - 2);
;             const char* a1 = cA + (size_t)(t + 1) * kstep;
;             const char* a2 = last ? nA : cA + (size_t)(t + 2) * kstep; const char* b2 = last ? nB : cB + (size_t)(t + 2) * kstep;
;             const char* a3 = a2 + kstep; const char* b3 = b2 + kstep;
;             if (last && has_next) S.a_ready(nxt);
;             if constexpr (SP2) {
;             PG8_LDB(B0, 0, 0); PG8_LDB(B1, 0, 1); PG8_SCHED; PG8_LDA(At, 0, 0); PG8_STAGE(PG8_SA(1, 1), a1 + hstep, voffA);
;             PG8_WAIT_V(8); PG8_WAIT_L(0); PG8_BAR; PG8_MMA(0, 0, At, B0); PG8_MMA(0, 1, At, B1); PG8_BAR; PG8_SCHED;
;             PG8_LDA(At, 0, 1); PG8_STAGE(PG8_SB(0, 0), b2, voffB); PG8_STAGE(PG8_SB(0, 1), b2 + hstep, voffB); PG8_STAGE(PG8_SA(0, 0), a2, voffA);
;             PG8_WAIT_V(8); PG8_WAIT_L(0); PG8_BAR; PG8_MMA(1, 0, At, B0); PG8_MMA(1, 1, At, B1); PG8_BAR; PG8_SCHED;
.LBB0_205:
	s_ashr_i32 s45, s44, 31
	s_lshl_b64 s[46:47], s[44:45], 19
	s_add_u32 s46, s28, s46
	s_addc_u32 s47, s29, s47
	s_and_b64 s[48:49], s[52:53], exec
	s_cselect_b32 s45, s47, s57
	s_cselect_b32 s76, s46, s56
	s_ashr_i32 s43, s42, 31
	s_lshl_b64 s[48:49], s[42:43], 19
	s_add_u32 s48, s59, s48
	s_addc_u32 s49, s60, s49
	s_and_b64 s[52:53], s[52:53], exec
	s_cselect_b32 s43, s49, s55
	s_cselect_b32 s77, s48, s54
	s_add_u32 s52, s56, 0x40080
	s_addc_u32 s53, s57, 0
	s_add_u32 s78, s54, 0x100
	s_addc_u32 s79, s55, 0
	s_mov_b32 s80, -2
	s_add_i32 s84, 0, 0x10000
	s_add_i32 s85, 0, 0x14000
	v_add_u32_e32 v142, s84, v162
	v_add_u32_e32 v172, s85, v162
	ds_read_b128 v[130:133], v142
	ds_read_b128 v[134:137], v142 offset:1024
	ds_read_b128 v[138:141], v142 offset:2048
	ds_read_b128 v[142:145], v142 offset:3072
	ds_read_b128 v[156:159], v172
	ds_read_b128 v[164:167], v172 offset:1024
	ds_read_b128 v[168:171], v172 offset:2048
	ds_read_b128 v[172:175], v172 offset:3072
	s_add_u32 s33, s52, 0xfffc0080
	s_addc_u32 s54, s53, -1
	s_cmp_eq_u32 s80, 12
	s_cselect_b32 s57, s45, s54
	s_cselect_b32 s56, s76, s33
	s_cselect_b32 s55, s43, s79
	s_cselect_b32 s54, s77, s78
	v_lshl_add_u64 v[184:185], s[52:53], 0, v[152:153]
	s_add_i32 m0, s62, 0xc000
	ds_read_b128 v[176:179], v163
	ds_read_b128 v[180:183], v163 offset:1024
	ds_read_b128 v[196:199], v163 offset:2048
	ds_read_b128 v[200:203], v163 offset:3072
	ds_read_b128 v[204:207], v163 offset:4096
	ds_read_b128 v[208:211], v163 offset:5120
	ds_read_b128 v[212:215], v163 offset:6144
	ds_read_b128 v[216:219], v163 offset:7168
	global_load_lds_dwordx4 v[184:185], off
	v_lshl_add_u64 v[184:185], s[52:53], 0, v[154:155]
	s_add_i32 m0, s62, 0xe000
	s_nop 0
	global_load_lds_dwordx4 v[184:185], off
	s_waitcnt vmcnt(8)
	s_waitcnt lgkmcnt(0)
	s_barrier
	s_setprio 1
	s_waitcnt lgkmcnt(0)
	v_mfma_f32_16x16x32_bf16 v[126:129], v[130:133], v[176:179], 0
	v_mfma_f32_16x16x32_bf16 v[122:125], v[138:141], v[176:179], 0
	v_mfma_f32_16x16x32_bf16 v[110:113], v[130:133], v[196:199], 0
	v_mfma_f32_16x16x32_bf16 v[106:109], v[138:141], v[196:199], 0
	v_mfma_f32_16x16x32_bf16 v[94:97], v[130:133], v[204:207], 0
	v_mfma_f32_16x16x32_bf16 v[90:93], v[138:141], v[204:207], 0
	v_mfma_f32_16x16x32_bf16 v[78:81], v[130:133], v[212:215], 0
	v_mfma_f32_16x16x32_bf16 v[74:77], v[138:141], v[212:215], 0
	v_mfma_f32_16x16x32_bf16 v[126:129], v[134:137], v[180:183], v[126:129]
	v_mfma_f32_16x16x32_bf16 v[122:125], v[142:145], v[180:183], v[122:125]
	v_mfma_f32_16x16x32_bf16 v[110:113], v[134:137], v[200:203], v[110:113]
	v_mfma_f32_16x16x32_bf16 v[106:109], v[142:145], v[200:203], v[106:109]
	v_mfma_f32_16x16x32_bf16 v[94:97], v[134:137], v[208:211], v[94:97]
	v_mfma_f32_16x16x32_bf16 v[90:93], v[142:145], v[208:211], v[90:93]
	v_mfma_f32_16x16x32_bf16 v[78:81], v[134:137], v[216:219], v[78:81]
	v_mfma_f32_16x16x32_bf16 v[74:77], v[142:145], v[216:219], v[74:77]
	s_setprio 0
	s_setprio 1
	v_mfma_f32_16x16x32_bf16 v[118:121], v[156:159], v[176:179], 0
	v_mfma_f32_16x16x32_bf16 v[114:117], v[168:171], v[176:179], 0
	v_mfma_f32_16x16x32_bf16 v[102:105], v[156:159], v[196:199], 0
	v_mfma_f32_16x16x32_bf16 v[98:101], v[168:171], v[196:199], 0
	v_mfma_f32_16x16x32_bf16 v[86:89], v[156:159], v[204:207], 0
	v_mfma_f32_16x16x32_bf16 v[82:85], v[168:171], v[204:207], 0
	v_mfma_f32_16x16x32_bf16 v[70:73], v[156:159], v[212:215], 0
	v_mfma_f32_16x16x32_bf16 v[66:69], v[168:171], v[212:215], 0
	v_mfma_f32_16x16x32_bf16 v[118:121], v[164:167], v[180:183], v[118:121]
	v_mfma_f32_16x16x32_bf16 v[114:117], v[172:175], v[180:183], v[114:117]
	v_mfma_f32_16x16x32_bf16 v[102:105], v[164:167], v[200:203], v[102:105]
	v_mfma_f32_16x16x32_bf16 v[98:101], v[172:175], v[200:203], v[98:101]
	v_mfma_f32_16x16x32_bf16 v[86:89], v[164:167], v[208:211], v[86:89]
	v_mfma_f32_16x16x32_bf16 v[82:85], v[172:175], v[208:211], v[82:85]
	v_mfma_f32_16x16x32_bf16 v[70:73], v[164:167], v[216:219], v[70:73]
	v_mfma_f32_16x16x32_bf16 v[66:69], v[172:175], v[216:219], v[66:69]
	s_setprio 0
	s_barrier
	s_add_i32 s33, s84, s61
	v_lshl_add_u64 v[184:185], s[54:55], 0, v[0:1]
	s_mov_b32 m0, s33
	ds_read_b128 v[176:179], v163 offset:16384
	ds_read_b128 v[180:183], v163 offset:17408
	ds_read_b128 v[196:199], v163 offset:18432
	ds_read_b128 v[200:203], v163 offset:19456
	ds_read_b128 v[204:207], v163 offset:20480
	ds_read_b128 v[208:211], v163 offset:21504
	ds_read_b128 v[212:215], v163 offset:22528
	ds_read_b128 v[216:219], v163 offset:23552
	global_load_lds_dwordx4 v[184:185], off
	s_add_i32 m0, s33, 0x2000
	s_add_u32 s82, s54, 0x40000
	v_lshl_add_u64 v[220:221], s[54:55], 0, v[146:147]
	s_addc_u32 s83, s55, 0
	s_add_i32 s33, s85, s61
	global_load_lds_dwordx4 v[220:221], off
	v_lshl_add_u64 v[222:223], s[82:83], 0, v[0:1]
	s_mov_b32 m0, s33
	v_lshl_add_u64 v[224:225], s[56:57], 0, v[148:149]
	global_load_lds_dwordx4 v[222:223], off
	v_lshl_add_u64 v[222:223], s[82:83], 0, v[146:147]
	s_add_i32 m0, s33, 0x2000
	s_nop 0
	global_load_lds_dwordx4 v[222:223], off
	v_lshl_add_u64 v[222:223], s[56:57], 0, v[150:151]
	s_mov_b32 m0, s62
	s_nop 0
	global_load_lds_dwordx4 v[222:223], off
	s_mov_b32 m0, s63
	s_nop 0
	global_load_lds_dwordx4 v[224:225], off
	s_waitcnt vmcnt(8)
	s_waitcnt lgkmcnt(0)
	s_barrier
; #define PG8_STAGE(bufoff, gbase, voff) do { _Pragma("unroll") for (int _i = 0; _i < 2; ++_i) \
;         __builtin_amdgcn_global_load_lds((const unsigned*)((const char*)(gbase) + (voff)[_i]), (PG8_LAS unsigned*)(lds + (bufoff) + ldsw + _i * 8192), 16, 0, 0); } while (0)
; #define PG8_LDA(dst, b, h) do { _Pragma("unroll") for (int m = 0; m < 4; ++m) _Pragma("unroll") for (int k = 0; k < 2; ++k) dst[m][k] = *(const PG8_LAS bf16x8*)(lds + PG8_SA(b, h) + aoff + m * 2048 + k * 1024); } while (0)
; #define PG8_LDB(dst, b, h) do { _Pragma("unroll") for (int n = 0; n < 2; ++n) _Pragma("unroll") for (int k = 0; k < 2; ++k) dst[n][k] = *(const PG8_LAS bf16x8*)(lds + PG8_SB(b, h) + boff + n * 2048 + k * 1024); } while (0)
; #define PG8_MMA(ai, bj, At, Bt) do { __builtin_amdgcn_s_setprio(1); _Pragma("unroll") for (int k = 0; k < 2; ++k) _Pragma("unroll") for (int m = 0; m < 4; ++m) _Pragma("unroll") for (int n = 0; n < 2; ++n) \
;         acc[ai][bj][m][n] = __builtin_amdgcn_mfma_f32_16x16x32_bf16(Bt[n][k], At[m][k], acc[ai][bj][m][n], 0, 0, 0); __builtin_amdgcn_s_setprio(0); } while (0)
; #define PG8_WAIT_V(n) asm volatile("s_waitcnt vmcnt(" #n ")" ::: "memory")
; #define PG8_WAIT_L(n) asm volatile("s_waitcnt lgkmcnt(" #n ")" ::: "memory")
; #define PG8_BAR __builtin_amdgcn_s_barrier()
; #define PG8_SCHED __builtin_amdgcn_sched_barrier(0)
; template <class Epi, class Sched, bool ALIGN_EPI = false, bool SP2 = false>
; __device__ __forceinline__ void gemm_phase(PG8_LAS unsigned char* lds, const Gemm g, const Sched& S, const Epi& E, int tid_in) {
;     ...
;             PG8_WAIT_V(8); PG8_WAIT_L(0); PG8_BAR; PG8_MMA(1, 0, At, B0); PG8_MMA(1, 1, At, B1); PG8_BAR; PG8_SCHED;
;             PG8_LDB(B0, 1, 0); PG8_LDB(B1, 1, 1); PG8_SCHED; PG8_LDA(At, 1, 0); PG8_STAGE(PG8_SA(0, 1), a2 + hstep, voffA);
;             PG8_WAIT_V(8); PG8_WAIT_L(0); PG8_BAR; PG8_MMA(0, 0, At, B0); PG8_MMA(0, 1, At, B1); PG8_BAR; PG8_SCHED;
	s_setprio 1
	s_waitcnt lgkmcnt(0)
	v_mfma_f32_16x16x32_bf16 v[62:65], v[130:133], v[176:179], 0
	v_mfma_f32_16x16x32_bf16 v[58:61], v[138:141], v[176:179], 0
	v_mfma_f32_16x16x32_bf16 v[46:49], v[130:133], v[196:199], 0
	v_mfma_f32_16x16x32_bf16 v[42:45], v[138:141], v[196:199], 0
	v_mfma_f32_16x16x32_bf16 v[30:33], v[130:133], v[204:207], 0
	v_mfma_f32_16x16x32_bf16 v[26:29], v[138:141], v[204:207], 0
	v_mfma_f32_16x16x32_bf16 v[14:17], v[130:133], v[212:215], 0
	v_mfma_f32_16x16x32_bf16 v[10:13], v[138:141], v[212:215], 0
	v_mfma_f32_16x16x32_bf16 v[62:65], v[134:137], v[180:183], v[62:65]
	v_mfma_f32_16x16x32_bf16 v[58:61], v[142:145], v[180:183], v[58:61]
	v_mfma_f32_16x16x32_bf16 v[46:49], v[134:137], v[200:203], v[46:49]
	v_mfma_f32_16x16x32_bf16 v[42:45], v[142:145], v[200:203], v[42:45]
	v_mfma_f32_16x16x32_bf16 v[30:33], v[134:137], v[208:211], v[30:33]
	v_mfma_f32_16x16x32_bf16 v[26:29], v[142:145], v[208:211], v[26:29]
	v_mfma_f32_16x16x32_bf16 v[14:17], v[134:137], v[216:219], v[14:17]
	v_mfma_f32_16x16x32_bf16 v[10:13], v[142:145], v[216:219], v[10:13]
	s_setprio 0
	s_setprio 1
	v_mfma_f32_16x16x32_bf16 v[54:57], v[156:159], v[176:179], 0
	v_mfma_f32_16x16x32_bf16 v[50:53], v[168:171], v[176:179], 0
	v_mfma_f32_16x16x32_bf16 v[38:41], v[156:159], v[196:199], 0
	v_mfma_f32_16x16x32_bf16 v[34:37], v[168:171], v[196:199], 0
	v_mfma_f32_16x16x32_bf16 v[22:25], v[156:159], v[204:207], 0
	v_mfma_f32_16x16x32_bf16 v[18:21], v[168:171], v[204:207], 0
	v_mfma_f32_16x16x32_bf16 v[6:9], v[156:159], v[212:215], 0
	v_mfma_f32_16x16x32_bf16 v[2:5], v[168:171], v[212:215], 0
	v_mfma_f32_16x16x32_bf16 v[54:57], v[164:167], v[180:183], v[54:57]
	v_mfma_f32_16x16x32_bf16 v[50:53], v[172:175], v[180:183], v[50:53]
	v_mfma_f32_16x16x32_bf16 v[38:41], v[164:167], v[200:203], v[38:41]
	v_mfma_f32_16x16x32_bf16 v[34:37], v[172:175], v[200:203], v[34:37]
	v_mfma_f32_16x16x32_bf16 v[22:25], v[164:167], v[208:211], v[22:25]
	v_mfma_f32_16x16x32_bf16 v[18:21], v[172:175], v[208:211], v[18:21]
	v_mfma_f32_16x16x32_bf16 v[6:9], v[164:167], v[216:219], v[6:9]
	v_mfma_f32_16x16x32_bf16 v[2:5], v[172:175], v[216:219], v[2:5]
	s_setprio 0
	s_barrier
	s_add_i32 s33, 0, 0x18000
	s_add_i32 s74, 0, 0x1c000
	v_add_u32_e32 v142, s33, v162
	v_add_u32_e32 v172, s74, v162
	ds_read_b128 v[130:133], v142
	ds_read_b128 v[134:137], v142 offset:1024
	ds_read_b128 v[138:141], v142 offset:2048
	ds_read_b128 v[142:145], v142 offset:3072
	ds_read_b128 v[156:159], v172
	ds_read_b128 v[164:167], v172 offset:1024
	ds_read_b128 v[168:171], v172 offset:2048
	ds_read_b128 v[172:175], v172 offset:3072
	s_add_u32 s56, s56, 0x40000
	s_addc_u32 s57, s57, 0
	s_mov_b32 m0, s64
	v_lshl_add_u64 v[226:227], s[56:57], 0, v[150:151]
	ds_read_b128 v[176:179], v163 offset:32768
	ds_read_b128 v[180:183], v163 offset:33792
	ds_read_b128 v[196:199], v163 offset:34816
	ds_read_b128 v[200:203], v163 offset:35840
	ds_read_b128 v[204:207], v163 offset:36864
	ds_read_b128 v[208:211], v163 offset:37888
	ds_read_b128 v[212:215], v163 offset:38912
	ds_read_b128 v[216:219], v163 offset:39936
	global_load_lds_dwordx4 v[226:227], off
	v_lshl_add_u64 v[226:227], s[56:57], 0, v[148:149]
	s_mov_b32 m0, s65
	s_nop 0
	global_load_lds_dwordx4 v[226:227], off
	s_waitcnt vmcnt(8)
	s_waitcnt lgkmcnt(0)
	s_barrier
	s_setprio 1
	s_waitcnt lgkmcnt(0)
	v_mfma_f32_16x16x32_bf16 v[126:129], v[130:133], v[176:179], v[126:129]
	v_mfma_f32_16x16x32_bf16 v[122:125], v[138:141], v[176:179], v[122:125]
	v_mfma_f32_16x16x32_bf16 v[110:113], v[130:133], v[196:199], v[110:113]
	v_mfma_f32_16x16x32_bf16 v[106:109], v[138:141], v[196:199], v[106:109]
	v_mfma_f32_16x16x32_bf16 v[94:97], v[130:133], v[204:207], v[94:97]
	v_mfma_f32_16x16x32_bf16 v[90:93], v[138:141], v[204:207], v[90:93]
	v_mfma_f32_16x16x32_bf16 v[78:81], v[130:133], v[212:215], v[78:81]
	v_mfma_f32_16x16x32_bf16 v[74:77], v[138:141], v[212:215], v[74:77]
	v_mfma_f32_16x16x32_bf16 v[126:129], v[134:137], v[180:183], v[126:129]
	v_mfma_f32_16x16x32_bf16 v[122:125], v[142:145], v[180:183], v[122:125]
	v_mfma_f32_16x16x32_bf16 v[110:113], v[134:137], v[200:203], v[110:113]
	v_mfma_f32_16x16x32_bf16 v[106:109], v[142:145], v[200:203], v[106:109]
	v_mfma_f32_16x16x32_bf16 v[94:97], v[134:137], v[208:211], v[94:97]
	v_mfma_f32_16x16x32_bf16 v[90:93], v[142:145], v[208:211], v[90:93]
	v_mfma_f32_16x16x32_bf16 v[78:81], v[134:137], v[216:219], v[78:81]
	v_mfma_f32_16x16x32_bf16 v[74:77], v[142:145], v[216:219], v[74:77]
	s_setprio 0
	s_setprio 1
	v_mfma_f32_16x16x32_bf16 v[118:121], v[156:159], v[176:179], v[118:121]
	v_mfma_f32_16x16x32_bf16 v[114:117], v[168:171], v[176:179], v[114:117]
	v_mfma_f32_16x16x32_bf16 v[102:105], v[156:159], v[196:199], v[102:105]
	v_mfma_f32_16x16x32_bf16 v[98:101], v[168:171], v[196:199], v[98:101]
	v_mfma_f32_16x16x32_bf16 v[86:89], v[156:159], v[204:207], v[86:89]
	v_mfma_f32_16x16x32_bf16 v[82:85], v[168:171], v[204:207], v[82:85]
	v_mfma_f32_16x16x32_bf16 v[70:73], v[156:159], v[212:215], v[70:73]
	v_mfma_f32_16x16x32_bf16 v[66:69], v[168:171], v[212:215], v[66:69]
	v_mfma_f32_16x16x32_bf16 v[118:121], v[164:167], v[180:183], v[118:121]
	v_mfma_f32_16x16x32_bf16 v[114:117], v[172:175], v[180:183], v[114:117]
	v_mfma_f32_16x16x32_bf16 v[102:105], v[164:167], v[200:203], v[102:105]
	v_mfma_f32_16x16x32_bf16 v[98:101], v[172:175], v[200:203], v[98:101]
	v_mfma_f32_16x16x32_bf16 v[86:89], v[164:167], v[208:211], v[86:89]
	v_mfma_f32_16x16x32_bf16 v[82:85], v[172:175], v[208:211], v[82:85]
	v_mfma_f32_16x16x32_bf16 v[70:73], v[164:167], v[216:219], v[70:73]
	v_mfma_f32_16x16x32_bf16 v[66:69], v[172:175], v[216:219], v[66:69]
	s_setprio 0
	s_barrier
; #define PG8_STAGE(bufoff, gbase, voff) do { _Pragma("unroll") for (int _i = 0; _i < 2; ++_i) \
;         __builtin_amdgcn_global_load_lds((const unsigned*)((const char*)(gbase) + (voff)[_i]), (PG8_LAS unsigned*)(lds + (bufoff) + ldsw + _i * 8192), 16, 0, 0); } while (0)
; #define PG8_LDA(dst, b, h) do { _Pragma("unroll") for (int m = 0; m < 4; ++m) _Pragma("unroll") for (int k = 0; k < 2; ++k) dst[m][k] = *(const PG8_LAS bf16x8*)(lds + PG8_SA(b, h) + aoff + m * 2048 + k * 1024); } while (0)
; #define PG8_LDB(dst, b, h) do { _Pragma("unroll") for (int n = 0; n < 2; ++n) _Pragma("unroll") for (int k = 0; k < 2; ++k) dst[n][k] = *(const PG8_LAS bf16x8*)(lds + PG8_SB(b, h) + boff + n * 2048 + k * 1024); } while (0)
; #define PG8_MMA(ai, bj, At, Bt) do { __builtin_amdgcn_s_setprio(1); _Pragma("unroll") for (int k = 0; k < 2; ++k) _Pragma("unroll") for (int m = 0; m < 4; ++m) _Pragma("unroll") for (int n = 0; n < 2; ++n) \
;         acc[ai][bj][m][n] = __builtin_amdgcn_mfma_f32_16x16x32_bf16(Bt[n][k], At[m][k], acc[ai][bj][m][n], 0, 0, 0); __builtin_amdgcn_s_setprio(0); } while (0)
; #define PG8_WAIT_V(n) asm volatile("s_waitcnt vmcnt(" #n ")" ::: "memory")
; #define PG8_BAR __builtin_amdgcn_s_barrier()
; template <class Epi, class Sched, bool ALIGN_EPI = false, bool SP2 = false>
; __device__ __forceinline__ void gemm_phase(PG8_LAS unsigned char* lds, const Gemm g, const Sched& S, const Epi& E, int tid_in) {
;     ...
;         for (int t = 0; t < nt; t += 2) {
;             const bool last = (t == nt - 2);
;             const char* a1 = cA + (size_t)(t + 1) * kstep;
;             const char* a2 = last ? nA : cA + (size_t)(t + 2) * kstep; const char* b2 = last ? nB : cB + (size_t)(t + 2) * kstep;
;             const char* a3 = a2 + kstep; const char* b3 = b2 + kstep;
;             if (last && has_next) S.a_ready(nxt);
;             if constexpr (SP2) {
;             PG8_LDB(B0, 0, 0); PG8_LDB(B1, 0, 1); PG8_SCHED; PG8_LDA(At, 0, 0); PG8_STAGE(PG8_SA(1, 1), a1 + hstep, voffA);
;             PG8_WAIT_V(8); PG8_WAIT_L(0); PG8_BAR; PG8_MMA(0, 0, At, B0); PG8_MMA(0, 1, At, B1); PG8_BAR; PG8_SCHED;
;     ...
;             PG8_LDA(At, 1, 1); PG8_STAGE(PG8_SB(1, 0), b3, voffB); PG8_STAGE(PG8_SB(1, 1), b3 + hstep, voffB); PG8_STAGE(PG8_SA(1, 0), a3, voffA);
;             PG8_WAIT_V(8); PG8_WAIT_L(0); PG8_BAR; PG8_MMA(1, 0, At, B0); PG8_MMA(1, 1, At, B1); PG8_BAR; PG8_SCHED;
	s_add_i32 s56, s33, s61
	v_lshl_add_u64 v[184:185], v[184:185], 0, s[26:27]
	s_mov_b32 m0, s56
	ds_read_b128 v[176:179], v163 offset:49152
	ds_read_b128 v[180:183], v163 offset:50176
	ds_read_b128 v[196:199], v163 offset:51200
	ds_read_b128 v[200:203], v163 offset:52224
	ds_read_b128 v[204:207], v163 offset:53248
	ds_read_b128 v[208:211], v163 offset:54272
	ds_read_b128 v[212:215], v163 offset:55296
	ds_read_b128 v[216:219], v163 offset:56320
	global_load_lds_dwordx4 v[184:185], off
	s_add_i32 m0, s56, 0x2000
	s_add_u32 s54, s54, 0x40080
	v_lshl_add_u64 v[184:185], v[220:221], 0, s[26:27]
	s_addc_u32 s55, s55, 0
	s_add_i32 s56, s74, s61
	global_load_lds_dwordx4 v[184:185], off
	v_lshl_add_u64 v[184:185], s[54:55], 0, v[0:1]
	s_mov_b32 m0, s56
	s_nop 0
	global_load_lds_dwordx4 v[184:185], off
	v_lshl_add_u64 v[184:185], s[54:55], 0, v[146:147]
	s_add_i32 m0, s56, 0x2000
	s_nop 0
	global_load_lds_dwordx4 v[184:185], off
	v_lshl_add_u64 v[184:185], v[222:223], 0, s[26:27]
	s_mov_b32 m0, s70
	s_nop 0
	global_load_lds_dwordx4 v[184:185], off
	v_lshl_add_u64 v[184:185], v[224:225], 0, s[26:27]
	s_mov_b32 m0, s75
	s_nop 0
	global_load_lds_dwordx4 v[184:185], off
	s_waitcnt vmcnt(8)
	s_waitcnt lgkmcnt(0)
	s_barrier
	s_setprio 1
	s_waitcnt lgkmcnt(0)
	v_mfma_f32_16x16x32_bf16 v[62:65], v[130:133], v[176:179], v[62:65]
	v_mfma_f32_16x16x32_bf16 v[58:61], v[138:141], v[176:179], v[58:61]
	v_mfma_f32_16x16x32_bf16 v[46:49], v[130:133], v[196:199], v[46:49]
	v_mfma_f32_16x16x32_bf16 v[42:45], v[138:141], v[196:199], v[42:45]
	v_mfma_f32_16x16x32_bf16 v[30:33], v[130:133], v[204:207], v[30:33]
	v_mfma_f32_16x16x32_bf16 v[26:29], v[138:141], v[204:207], v[26:29]
	v_mfma_f32_16x16x32_bf16 v[14:17], v[130:133], v[212:215], v[14:17]
	v_mfma_f32_16x16x32_bf16 v[10:13], v[138:141], v[212:215], v[10:13]
	v_mfma_f32_16x16x32_bf16 v[62:65], v[134:137], v[180:183], v[62:65]
	v_mfma_f32_16x16x32_bf16 v[58:61], v[142:145], v[180:183], v[58:61]
	v_mfma_f32_16x16x32_bf16 v[46:49], v[134:137], v[200:203], v[46:49]
	v_mfma_f32_16x16x32_bf16 v[42:45], v[142:145], v[200:203], v[42:45]
	v_mfma_f32_16x16x32_bf16 v[30:33], v[134:137], v[208:211], v[30:33]
	v_mfma_f32_16x16x32_bf16 v[26:29], v[142:145], v[208:211], v[26:29]
	v_mfma_f32_16x16x32_bf16 v[14:17], v[134:137], v[216:219], v[14:17]
	v_mfma_f32_16x16x32_bf16 v[10:13], v[142:145], v[216:219], v[10:13]
	s_setprio 0
	s_setprio 1
	v_mfma_f32_16x16x32_bf16 v[54:57], v[156:159], v[176:179], v[54:57]
	v_mfma_f32_16x16x32_bf16 v[50:53], v[168:171], v[176:179], v[50:53]
	v_mfma_f32_16x16x32_bf16 v[38:41], v[156:159], v[196:199], v[38:41]
	v_mfma_f32_16x16x32_bf16 v[34:37], v[168:171], v[196:199], v[34:37]
	v_mfma_f32_16x16x32_bf16 v[22:25], v[156:159], v[204:207], v[22:25]
	v_mfma_f32_16x16x32_bf16 v[18:21], v[168:171], v[204:207], v[18:21]
	v_mfma_f32_16x16x32_bf16 v[6:9], v[156:159], v[212:215], v[6:9]
	v_mfma_f32_16x16x32_bf16 v[2:5], v[168:171], v[212:215], v[2:5]
	v_mfma_f32_16x16x32_bf16 v[54:57], v[164:167], v[180:183], v[54:57]
	v_mfma_f32_16x16x32_bf16 v[50:53], v[172:175], v[180:183], v[50:53]
	v_mfma_f32_16x16x32_bf16 v[38:41], v[164:167], v[200:203], v[38:41]
	v_mfma_f32_16x16x32_bf16 v[34:37], v[172:175], v[200:203], v[34:37]
	v_mfma_f32_16x16x32_bf16 v[22:25], v[164:167], v[208:211], v[22:25]
	v_mfma_f32_16x16x32_bf16 v[18:21], v[172:175], v[208:211], v[18:21]
	v_mfma_f32_16x16x32_bf16 v[6:9], v[164:167], v[216:219], v[6:9]
	v_mfma_f32_16x16x32_bf16 v[2:5], v[172:175], v[216:219], v[2:5]
	s_setprio 0
	s_add_i32 s80, s80, 2
	s_add_u32 s52, s52, 0x100
	s_addc_u32 s53, s53, 0
	s_add_u32 s78, s78, 0x100
	s_addc_u32 s79, s79, 0
	s_cmp_gt_u32 s80, 13
	s_barrier
.LBB0_206:
	s_add_i32 s84, 0, 0x10000
	s_add_i32 s85, 0, 0x14000
	v_add_u32_e32 v142, s84, v162
	v_add_u32_e32 v172, s85, v162
	ds_read_b128 v[130:133], v142
	ds_read_b128 v[134:137], v142 offset:1024
	ds_read_b128 v[138:141], v142 offset:2048
	ds_read_b128 v[142:145], v142 offset:3072
	ds_read_b128 v[156:159], v172
	ds_read_b128 v[164:167], v172 offset:1024
	ds_read_b128 v[168:171], v172 offset:2048
	ds_read_b128 v[172:175], v172 offset:3072
	s_add_u32 s33, s52, 0xfffc0080
	s_addc_u32 s54, s53, -1
	s_cmp_eq_u32 s80, 12
	s_cselect_b32 s57, s45, s54
	s_cselect_b32 s56, s76, s33
	s_cselect_b32 s55, s43, s79
	s_cselect_b32 s54, s77, s78
	v_lshl_add_u64 v[184:185], s[52:53], 0, v[152:153]
	s_add_i32 m0, s62, 0xc000
	ds_read_b128 v[176:179], v163
	ds_read_b128 v[180:183], v163 offset:1024
	ds_read_b128 v[196:199], v163 offset:2048
	ds_read_b128 v[200:203], v163 offset:3072
	ds_read_b128 v[204:207], v163 offset:4096
	ds_read_b128 v[208:211], v163 offset:5120
	ds_read_b128 v[212:215], v163 offset:6144
	ds_read_b128 v[216:219], v163 offset:7168
	global_load_lds_dwordx4 v[184:185], off
	v_lshl_add_u64 v[184:185], s[52:53], 0, v[154:155]
	s_add_i32 m0, s62, 0xe000
	s_nop 0
	global_load_lds_dwordx4 v[184:185], off
	s_waitcnt vmcnt(8)
	s_waitcnt lgkmcnt(0)
	s_barrier
; #define PG8_STAGE(bufoff, gbase, voff) do { _Pragma("unroll") for (int _i = 0; _i < 2; ++_i) \
;         __builtin_amdgcn_global_load_lds((const unsigned*)((const char*)(gbase) + (voff)[_i]), (PG8_LAS unsigned*)(lds + (bufoff) + ldsw + _i * 8192), 16, 0, 0); } while (0)
; #define PG8_LDA(dst, b, h) do { _Pragma("unroll") for (int m = 0; m < 4; ++m) _Pragma("unroll") for (int k = 0; k < 2; ++k) dst[m][k] = *(const PG8_LAS bf16x8*)(lds + PG8_SA(b, h) + aoff + m * 2048 + k * 1024); } while (0)
; #define PG8_LDB(dst, b, h) do { _Pragma("unroll") for (int n = 0; n < 2; ++n) _Pragma("unroll") for (int k = 0; k < 2; ++k) dst[n][k] = *(const PG8_LAS bf16x8*)(lds + PG8_SB(b, h) + boff + n * 2048 + k * 1024); } while (0)
; #define PG8_MMA(ai, bj, At, Bt) do { __builtin_amdgcn_s_setprio(1); _Pragma("unroll") for (int k = 0; k < 2; ++k) _Pragma("unroll") for (int m = 0; m < 4; ++m) _Pragma("unroll") for (int n = 0; n < 2; ++n) \
;         acc[ai][bj][m][n] = __builtin_amdgcn_mfma_f32_16x16x32_bf16(Bt[n][k], At[m][k], acc[ai][bj][m][n], 0, 0, 0); __builtin_amdgcn_s_setprio(0); } while (0)
; #define PG8_WAIT_V(n) asm volatile("s_waitcnt vmcnt(" #n ")" ::: "memory")
; #define PG8_WAIT_L(n) asm volatile("s_waitcnt lgkmcnt(" #n ")" ::: "memory")
; #define PG8_BAR __builtin_amdgcn_s_barrier()
; #define PG8_SCHED __builtin_amdgcn_sched_barrier(0)
; template <class Epi, class Sched, bool ALIGN_EPI = false, bool SP2 = false>
; __device__ __forceinline__ void gemm_phase(PG8_LAS unsigned char* lds, const Gemm g, const Sched& S, const Epi& E, int tid_in) {
;     ...
;             PG8_LDB(B0, 0, 0); PG8_LDB(B1, 0, 1); PG8_SCHED; PG8_LDA(At, 0, 0); PG8_STAGE(PG8_SA(1, 1), a1 + hstep, voffA);
;             PG8_WAIT_V(8); PG8_WAIT_L(0); PG8_BAR; PG8_MMA(0, 0, At, B0); PG8_MMA(0, 1, At, B1); PG8_BAR; PG8_SCHED;
;             PG8_LDA(At, 0, 1); PG8_STAGE(PG8_SB(0, 0), b2, voffB); PG8_STAGE(PG8_SB(0, 1), b2 + hstep, voffB); PG8_STAGE(PG8_SA(0, 0), a2, voffA);
;             PG8_WAIT_V(8); PG8_WAIT_L(0); PG8_BAR; PG8_MMA(1, 0, At, B0); PG8_MMA(1, 1, At, B1); PG8_BAR; PG8_SCHED;
	s_setprio 1
	s_waitcnt lgkmcnt(0)
	v_mfma_f32_16x16x32_bf16 v[126:129], v[130:133], v[176:179], v[126:129]
	v_mfma_f32_16x16x32_bf16 v[122:125], v[138:141], v[176:179], v[122:125]
	v_mfma_f32_16x16x32_bf16 v[110:113], v[130:133], v[196:199], v[110:113]
	v_mfma_f32_16x16x32_bf16 v[106:109], v[138:141], v[196:199], v[106:109]
	v_mfma_f32_16x16x32_bf16 v[94:97], v[130:133], v[204:207], v[94:97]
	v_mfma_f32_16x16x32_bf16 v[90:93], v[138:141], v[204:207], v[90:93]
	v_mfma_f32_16x16x32_bf16 v[78:81], v[130:133], v[212:215], v[78:81]
	v_mfma_f32_16x16x32_bf16 v[74:77], v[138:141], v[212:215], v[74:77]
	v_mfma_f32_16x16x32_bf16 v[126:129], v[134:137], v[180:183], v[126:129]
	v_mfma_f32_16x16x32_bf16 v[122:125], v[142:145], v[180:183], v[122:125]
	v_mfma_f32_16x16x32_bf16 v[110:113], v[134:137], v[200:203], v[110:113]
	v_mfma_f32_16x16x32_bf16 v[106:109], v[142:145], v[200:203], v[106:109]
	v_mfma_f32_16x16x32_bf16 v[94:97], v[134:137], v[208:211], v[94:97]
	v_mfma_f32_16x16x32_bf16 v[90:93], v[142:145], v[208:211], v[90:93]
	v_mfma_f32_16x16x32_bf16 v[78:81], v[134:137], v[216:219], v[78:81]
	v_mfma_f32_16x16x32_bf16 v[74:77], v[142:145], v[216:219], v[74:77]
	s_setprio 0
	s_setprio 1
	v_mfma_f32_16x16x32_bf16 v[118:121], v[156:159], v[176:179], v[118:121]
	v_mfma_f32_16x16x32_bf16 v[114:117], v[168:171], v[176:179], v[114:117]
	v_mfma_f32_16x16x32_bf16 v[102:105], v[156:159], v[196:199], v[102:105]
	v_mfma_f32_16x16x32_bf16 v[98:101], v[168:171], v[196:199], v[98:101]
	v_mfma_f32_16x16x32_bf16 v[86:89], v[156:159], v[204:207], v[86:89]
	v_mfma_f32_16x16x32_bf16 v[82:85], v[168:171], v[204:207], v[82:85]
	v_mfma_f32_16x16x32_bf16 v[70:73], v[156:159], v[212:215], v[70:73]
	v_mfma_f32_16x16x32_bf16 v[66:69], v[168:171], v[212:215], v[66:69]
	v_mfma_f32_16x16x32_bf16 v[118:121], v[164:167], v[180:183], v[118:121]
	v_mfma_f32_16x16x32_bf16 v[114:117], v[172:175], v[180:183], v[114:117]
	v_mfma_f32_16x16x32_bf16 v[102:105], v[164:167], v[200:203], v[102:105]
	v_mfma_f32_16x16x32_bf16 v[98:101], v[172:175], v[200:203], v[98:101]
	v_mfma_f32_16x16x32_bf16 v[86:89], v[164:167], v[208:211], v[86:89]
	v_mfma_f32_16x16x32_bf16 v[82:85], v[172:175], v[208:211], v[82:85]
	v_mfma_f32_16x16x32_bf16 v[70:73], v[164:167], v[216:219], v[70:73]
	v_mfma_f32_16x16x32_bf16 v[66:69], v[172:175], v[216:219], v[66:69]
	s_setprio 0
	s_barrier
	s_add_i32 s33, s84, s61
	v_lshl_add_u64 v[184:185], s[54:55], 0, v[0:1]
	s_mov_b32 m0, s33
	ds_read_b128 v[176:179], v163 offset:16384
	ds_read_b128 v[180:183], v163 offset:17408
	ds_read_b128 v[196:199], v163 offset:18432
	ds_read_b128 v[200:203], v163 offset:19456
	ds_read_b128 v[204:207], v163 offset:20480
	ds_read_b128 v[208:211], v163 offset:21504
	ds_read_b128 v[212:215], v163 offset:22528
	ds_read_b128 v[216:219], v163 offset:23552
	global_load_lds_dwordx4 v[184:185], off
	s_add_i32 m0, s33, 0x2000
	s_add_u32 s82, s54, 0x40000
	v_lshl_add_u64 v[220:221], s[54:55], 0, v[146:147]
	s_addc_u32 s83, s55, 0
	s_add_i32 s33, s85, s61
	global_load_lds_dwordx4 v[220:221], off
	v_lshl_add_u64 v[222:223], s[82:83], 0, v[0:1]
	s_mov_b32 m0, s33
	v_lshl_add_u64 v[224:225], s[56:57], 0, v[148:149]
	global_load_lds_dwordx4 v[222:223], off
	v_lshl_add_u64 v[222:223], s[82:83], 0, v[146:147]
	s_add_i32 m0, s33, 0x2000
	s_nop 0
	global_load_lds_dwordx4 v[222:223], off
	v_lshl_add_u64 v[222:223], s[56:57], 0, v[150:151]
	s_mov_b32 m0, s62
	s_nop 0
	global_load_lds_dwordx4 v[222:223], off
	s_mov_b32 m0, s63
	s_nop 0
	global_load_lds_dwordx4 v[224:225], off
	s_waitcnt vmcnt(8)
	s_waitcnt lgkmcnt(0)
	s_barrier
	s_setprio 1
	s_waitcnt lgkmcnt(0)
	v_mfma_f32_16x16x32_bf16 v[62:65], v[130:133], v[176:179], v[62:65]
	v_mfma_f32_16x16x32_bf16 v[58:61], v[138:141], v[176:179], v[58:61]
	v_mfma_f32_16x16x32_bf16 v[46:49], v[130:133], v[196:199], v[46:49]
	v_mfma_f32_16x16x32_bf16 v[42:45], v[138:141], v[196:199], v[42:45]
	v_mfma_f32_16x16x32_bf16 v[30:33], v[130:133], v[204:207], v[30:33]
	v_mfma_f32_16x16x32_bf16 v[26:29], v[138:141], v[204:207], v[26:29]
	v_mfma_f32_16x16x32_bf16 v[14:17], v[130:133], v[212:215], v[14:17]
	v_mfma_f32_16x16x32_bf16 v[10:13], v[138:141], v[212:215], v[10:13]
	v_mfma_f32_16x16x32_bf16 v[62:65], v[134:137], v[180:183], v[62:65]
	v_mfma_f32_16x16x32_bf16 v[58:61], v[142:145], v[180:183], v[58:61]
	v_mfma_f32_16x16x32_bf16 v[46:49], v[134:137], v[200:203], v[46:49]
	v_mfma_f32_16x16x32_bf16 v[42:45], v[142:145], v[200:203], v[42:45]
	v_mfma_f32_16x16x32_bf16 v[30:33], v[134:137], v[208:211], v[30:33]
	v_mfma_f32_16x16x32_bf16 v[26:29], v[142:145], v[208:211], v[26:29]
	v_mfma_f32_16x16x32_bf16 v[14:17], v[134:137], v[216:219], v[14:17]
	v_mfma_f32_16x16x32_bf16 v[10:13], v[142:145], v[216:219], v[10:13]
	s_setprio 0
	s_setprio 1
	v_mfma_f32_16x16x32_bf16 v[54:57], v[156:159], v[176:179], v[54:57]
	v_mfma_f32_16x16x32_bf16 v[50:53], v[168:171], v[176:179], v[50:53]
	v_mfma_f32_16x16x32_bf16 v[38:41], v[156:159], v[196:199], v[38:41]
	v_mfma_f32_16x16x32_bf16 v[34:37], v[168:171], v[196:199], v[34:37]
	v_mfma_f32_16x16x32_bf16 v[22:25], v[156:159], v[204:207], v[22:25]
	v_mfma_f32_16x16x32_bf16 v[18:21], v[168:171], v[204:207], v[18:21]
	v_mfma_f32_16x16x32_bf16 v[6:9], v[156:159], v[212:215], v[6:9]
	v_mfma_f32_16x16x32_bf16 v[2:5], v[168:171], v[212:215], v[2:5]
	v_mfma_f32_16x16x32_bf16 v[54:57], v[164:167], v[180:183], v[54:57]
	v_mfma_f32_16x16x32_bf16 v[50:53], v[172:175], v[180:183], v[50:53]
	v_mfma_f32_16x16x32_bf16 v[38:41], v[164:167], v[200:203], v[38:41]
	v_mfma_f32_16x16x32_bf16 v[34:37], v[172:175], v[200:203], v[34:37]
	v_mfma_f32_16x16x32_bf16 v[22:25], v[164:167], v[208:211], v[22:25]
	v_mfma_f32_16x16x32_bf16 v[18:21], v[172:175], v[208:211], v[18:21]
	v_mfma_f32_16x16x32_bf16 v[6:9], v[164:167], v[216:219], v[6:9]
	v_mfma_f32_16x16x32_bf16 v[2:5], v[172:175], v[216:219], v[2:5]
	s_setprio 0
	s_barrier
; #define PG8_STAGE(bufoff, gbase, voff) do { _Pragma("unroll") for (int _i = 0; _i < 2; ++_i) \
;         __builtin_amdgcn_global_load_lds((const unsigned*)((const char*)(gbase) + (voff)[_i]), (PG8_LAS unsigned*)(lds + (bufoff) + ldsw + _i * 8192), 16, 0, 0); } while (0)
; #define PG8_LDA(dst, b, h) do { _Pragma("unroll") for (int m = 0; m < 4; ++m) _Pragma("unroll") for (int k = 0; k < 2; ++k) dst[m][k] = *(const PG8_LAS bf16x8*)(lds + PG8_SA(b, h) + aoff + m * 2048 + k * 1024); } while (0)
; #define PG8_LDB(dst, b, h) do { _Pragma("unroll") for (int n = 0; n < 2; ++n) _Pragma("unroll") for (int k = 0; k < 2; ++k) dst[n][k] = *(const PG8_LAS bf16x8*)(lds + PG8_SB(b, h) + boff + n * 2048 + k * 1024); } while (0)
; #define PG8_MMA(ai, bj, At, Bt) do { __builtin_amdgcn_s_setprio(1); _Pragma("unroll") for (int k = 0; k < 2; ++k) _Pragma("unroll") for (int m = 0; m < 4; ++m) _Pragma("unroll") for (int n = 0; n < 2; ++n) \
;         acc[ai][bj][m][n] = __builtin_amdgcn_mfma_f32_16x16x32_bf16(Bt[n][k], At[m][k], acc[ai][bj][m][n], 0, 0, 0); __builtin_amdgcn_s_setprio(0); } while (0)
; #define PG8_WAIT_V(n) asm volatile("s_waitcnt vmcnt(" #n ")" ::: "memory")
; #define PG8_WAIT_L(n) asm volatile("s_waitcnt lgkmcnt(" #n ")" ::: "memory")
; #define PG8_BAR __builtin_amdgcn_s_barrier()
; #define PG8_SCHED __builtin_amdgcn_sched_barrier(0)
; template <class Epi, class Sched, bool ALIGN_EPI = false, bool SP2 = false>
; __device__ __forceinline__ void gemm_phase(PG8_LAS unsigned char* lds, const Gemm g, const Sched& S, const Epi& E, int tid_in) {
;     ...
;             PG8_LDB(B0, 1, 0); PG8_LDB(B1, 1, 1); PG8_SCHED; PG8_LDA(At, 1, 0); PG8_STAGE(PG8_SA(0, 1), a2 + hstep, voffA);
;             PG8_WAIT_V(8); PG8_WAIT_L(0); PG8_BAR; PG8_MMA(0, 0, At, B0); PG8_MMA(0, 1, At, B1); PG8_BAR; PG8_SCHED;
	s_add_i32 s33, 0, 0x18000
	s_add_i32 s74, 0, 0x1c000
	v_add_u32_e32 v142, s33, v162
	v_add_u32_e32 v172, s74, v162
	ds_read_b128 v[130:133], v142
	ds_read_b128 v[134:137], v142 offset:1024
	ds_read_b128 v[138:141], v142 offset:2048
	ds_read_b128 v[142:145], v142 offset:3072
	ds_read_b128 v[156:159], v172
	ds_read_b128 v[164:167], v172 offset:1024
	ds_read_b128 v[168:171], v172 offset:2048
	ds_read_b128 v[172:175], v172 offset:3072
	s_add_u32 s56, s56, 0x40000
	s_addc_u32 s57, s57, 0
	s_mov_b32 m0, s64
	v_lshl_add_u64 v[226:227], s[56:57], 0, v[150:151]
	ds_read_b128 v[176:179], v163 offset:32768
	ds_read_b128 v[180:183], v163 offset:33792
	ds_read_b128 v[196:199], v163 offset:34816
	ds_read_b128 v[200:203], v163 offset:35840
	ds_read_b128 v[204:207], v163 offset:36864
	ds_read_b128 v[208:211], v163 offset:37888
	ds_read_b128 v[212:215], v163 offset:38912
	ds_read_b128 v[216:219], v163 offset:39936
	global_load_lds_dwordx4 v[226:227], off
	v_lshl_add_u64 v[226:227], s[56:57], 0, v[148:149]
	s_mov_b32 m0, s65
	s_nop 0
	global_load_lds_dwordx4 v[226:227], off
	s_waitcnt vmcnt(8)
	s_waitcnt lgkmcnt(0)
	s_barrier
	s_setprio 1
	s_waitcnt lgkmcnt(0)
	v_mfma_f32_16x16x32_bf16 v[126:129], v[130:133], v[176:179], v[126:129]
	v_mfma_f32_16x16x32_bf16 v[122:125], v[138:141], v[176:179], v[122:125]
	v_mfma_f32_16x16x32_bf16 v[110:113], v[130:133], v[196:199], v[110:113]
	v_mfma_f32_16x16x32_bf16 v[106:109], v[138:141], v[196:199], v[106:109]
	v_mfma_f32_16x16x32_bf16 v[94:97], v[130:133], v[204:207], v[94:97]
	v_mfma_f32_16x16x32_bf16 v[90:93], v[138:141], v[204:207], v[90:93]
	v_mfma_f32_16x16x32_bf16 v[78:81], v[130:133], v[212:215], v[78:81]
	v_mfma_f32_16x16x32_bf16 v[74:77], v[138:141], v[212:215], v[74:77]
	v_mfma_f32_16x16x32_bf16 v[126:129], v[134:137], v[180:183], v[126:129]
	v_mfma_f32_16x16x32_bf16 v[122:125], v[142:145], v[180:183], v[122:125]
	v_mfma_f32_16x16x32_bf16 v[110:113], v[134:137], v[200:203], v[110:113]
	v_mfma_f32_16x16x32_bf16 v[106:109], v[142:145], v[200:203], v[106:109]
	v_mfma_f32_16x16x32_bf16 v[94:97], v[134:137], v[208:211], v[94:97]
	v_mfma_f32_16x16x32_bf16 v[90:93], v[142:145], v[208:211], v[90:93]
	v_mfma_f32_16x16x32_bf16 v[78:81], v[134:137], v[216:219], v[78:81]
	v_mfma_f32_16x16x32_bf16 v[74:77], v[142:145], v[216:219], v[74:77]
	s_setprio 0
	s_setprio 1
	v_mfma_f32_16x16x32_bf16 v[118:121], v[156:159], v[176:179], v[118:121]
	v_mfma_f32_16x16x32_bf16 v[114:117], v[168:171], v[176:179], v[114:117]
	v_mfma_f32_16x16x32_bf16 v[102:105], v[156:159], v[196:199], v[102:105]
	v_mfma_f32_16x16x32_bf16 v[98:101], v[168:171], v[196:199], v[98:101]
	v_mfma_f32_16x16x32_bf16 v[86:89], v[156:159], v[204:207], v[86:89]
	v_mfma_f32_16x16x32_bf16 v[82:85], v[168:171], v[204:207], v[82:85]
	v_mfma_f32_16x16x32_bf16 v[70:73], v[156:159], v[212:215], v[70:73]
	v_mfma_f32_16x16x32_bf16 v[66:69], v[168:171], v[212:215], v[66:69]
	v_mfma_f32_16x16x32_bf16 v[118:121], v[164:167], v[180:183], v[118:121]
	v_mfma_f32_16x16x32_bf16 v[114:117], v[172:175], v[180:183], v[114:117]
	v_mfma_f32_16x16x32_bf16 v[102:105], v[164:167], v[200:203], v[102:105]
	v_mfma_f32_16x16x32_bf16 v[98:101], v[172:175], v[200:203], v[98:101]
	v_mfma_f32_16x16x32_bf16 v[86:89], v[164:167], v[208:211], v[86:89]
	v_mfma_f32_16x16x32_bf16 v[82:85], v[172:175], v[208:211], v[82:85]
	v_mfma_f32_16x16x32_bf16 v[70:73], v[164:167], v[216:219], v[70:73]
	v_mfma_f32_16x16x32_bf16 v[66:69], v[172:175], v[216:219], v[66:69]
	s_setprio 0
	s_barrier
; #define PG8_STAGE(bufoff, gbase, voff) do { _Pragma("unroll") for (int _i = 0; _i < 2; ++_i) \
;         __builtin_amdgcn_global_load_lds((const unsigned*)((const char*)(gbase) + (voff)[_i]), (PG8_LAS unsigned*)(lds + (bufoff) + ldsw + _i * 8192), 16, 0, 0); } while (0)
; #define PG8_LDA(dst, b, h) do { _Pragma("unroll") for (int m = 0; m < 4; ++m) _Pragma("unroll") for (int k = 0; k < 2; ++k) dst[m][k] = *(const PG8_LAS bf16x8*)(lds + PG8_SA(b, h) + aoff + m * 2048 + k * 1024); } while (0)
; #define PG8_MMA(ai, bj, At, Bt) do { __builtin_amdgcn_s_setprio(1); _Pragma("unroll") for (int k = 0; k < 2; ++k) _Pragma("unroll") for (int m = 0; m < 4; ++m) _Pragma("unroll") for (int n = 0; n < 2; ++n) \
;         acc[ai][bj][m][n] = __builtin_amdgcn_mfma_f32_16x16x32_bf16(Bt[n][k], At[m][k], acc[ai][bj][m][n], 0, 0, 0); __builtin_amdgcn_s_setprio(0); } while (0)
; #define PG8_WAIT_V(n) asm volatile("s_waitcnt vmcnt(" #n ")" ::: "memory")
; #define PG8_WAIT_L(n) asm volatile("s_waitcnt lgkmcnt(" #n ")" ::: "memory")
; #define PG8_BAR __builtin_amdgcn_s_barrier()
; #define PG8_SCHED __builtin_amdgcn_sched_barrier(0)
; template <class Epi, class Sched, bool ALIGN_EPI = false, bool SP2 = false>
; __device__ __forceinline__ void gemm_phase(PG8_LAS unsigned char* lds, const Gemm g, const Sched& S, const Epi& E, int tid_in) {
;     ...
;             PG8_LDA(At, 1, 1); PG8_STAGE(PG8_SB(1, 0), b3, voffB); PG8_STAGE(PG8_SB(1, 1), b3 + hstep, voffB); PG8_STAGE(PG8_SA(1, 0), a3, voffA);
;             PG8_WAIT_V(8); PG8_WAIT_L(0); PG8_BAR; PG8_MMA(1, 0, At, B0); PG8_MMA(1, 1, At, B1); PG8_BAR; PG8_SCHED;
;     ...
;         if constexpr (ALIGN_EPI) { if (wr == 0) PG8_BAR; }
	s_add_i32 s56, s33, s61
	v_lshl_add_u64 v[184:185], v[184:185], 0, s[26:27]
	s_mov_b32 m0, s56
	ds_read_b128 v[176:179], v163 offset:49152
	ds_read_b128 v[180:183], v163 offset:50176
	ds_read_b128 v[196:199], v163 offset:51200
	ds_read_b128 v[200:203], v163 offset:52224
	ds_read_b128 v[204:207], v163 offset:53248
	ds_read_b128 v[208:211], v163 offset:54272
	ds_read_b128 v[212:215], v163 offset:55296
	ds_read_b128 v[216:219], v163 offset:56320
	global_load_lds_dwordx4 v[184:185], off
	s_add_i32 m0, s56, 0x2000
	s_add_u32 s54, s54, 0x40080
	v_lshl_add_u64 v[184:185], v[220:221], 0, s[26:27]
	s_addc_u32 s55, s55, 0
	s_add_i32 s56, s74, s61
	global_load_lds_dwordx4 v[184:185], off
	v_lshl_add_u64 v[184:185], s[54:55], 0, v[0:1]
	s_mov_b32 m0, s56
	s_nop 0
	global_load_lds_dwordx4 v[184:185], off
	v_lshl_add_u64 v[184:185], s[54:55], 0, v[146:147]
	s_add_i32 m0, s56, 0x2000
	s_nop 0
	global_load_lds_dwordx4 v[184:185], off
	v_lshl_add_u64 v[184:185], v[222:223], 0, s[26:27]
	s_mov_b32 m0, s70
	s_nop 0
	global_load_lds_dwordx4 v[184:185], off
	v_lshl_add_u64 v[184:185], v[224:225], 0, s[26:27]
	s_mov_b32 m0, s75
	s_nop 0
	global_load_lds_dwordx4 v[184:185], off
	s_waitcnt vmcnt(8)
	s_waitcnt lgkmcnt(0)
	s_barrier
	s_setprio 1
	s_waitcnt lgkmcnt(0)
	v_mfma_f32_16x16x32_bf16 v[62:65], v[130:133], v[176:179], v[62:65]
	v_mfma_f32_16x16x32_bf16 v[58:61], v[138:141], v[176:179], v[58:61]
	v_mfma_f32_16x16x32_bf16 v[46:49], v[130:133], v[196:199], v[46:49]
	v_mfma_f32_16x16x32_bf16 v[42:45], v[138:141], v[196:199], v[42:45]
	v_mfma_f32_16x16x32_bf16 v[30:33], v[130:133], v[204:207], v[30:33]
	v_mfma_f32_16x16x32_bf16 v[26:29], v[138:141], v[204:207], v[26:29]
	v_mfma_f32_16x16x32_bf16 v[14:17], v[130:133], v[212:215], v[14:17]
	v_mfma_f32_16x16x32_bf16 v[10:13], v[138:141], v[212:215], v[10:13]
	v_mfma_f32_16x16x32_bf16 v[62:65], v[134:137], v[180:183], v[62:65]
	v_mfma_f32_16x16x32_bf16 v[58:61], v[142:145], v[180:183], v[58:61]
	v_mfma_f32_16x16x32_bf16 v[46:49], v[134:137], v[200:203], v[46:49]
	v_mfma_f32_16x16x32_bf16 v[42:45], v[142:145], v[200:203], v[42:45]
	v_mfma_f32_16x16x32_bf16 v[30:33], v[134:137], v[208:211], v[30:33]
	v_mfma_f32_16x16x32_bf16 v[26:29], v[142:145], v[208:211], v[26:29]
	v_mfma_f32_16x16x32_bf16 v[14:17], v[134:137], v[216:219], v[14:17]
	v_mfma_f32_16x16x32_bf16 v[10:13], v[142:145], v[216:219], v[10:13]
	s_setprio 0
	s_setprio 1
	v_mfma_f32_16x16x32_bf16 v[54:57], v[156:159], v[176:179], v[54:57]
	v_mfma_f32_16x16x32_bf16 v[50:53], v[168:171], v[176:179], v[50:53]
	v_mfma_f32_16x16x32_bf16 v[38:41], v[156:159], v[196:199], v[38:41]
	v_mfma_f32_16x16x32_bf16 v[34:37], v[168:171], v[196:199], v[34:37]
	v_mfma_f32_16x16x32_bf16 v[22:25], v[156:159], v[204:207], v[22:25]
	v_mfma_f32_16x16x32_bf16 v[18:21], v[168:171], v[204:207], v[18:21]
	v_mfma_f32_16x16x32_bf16 v[6:9], v[156:159], v[212:215], v[6:9]
	v_mfma_f32_16x16x32_bf16 v[2:5], v[168:171], v[212:215], v[2:5]
	v_mfma_f32_16x16x32_bf16 v[54:57], v[164:167], v[180:183], v[54:57]
	v_mfma_f32_16x16x32_bf16 v[50:53], v[172:175], v[180:183], v[50:53]
	v_mfma_f32_16x16x32_bf16 v[38:41], v[164:167], v[200:203], v[38:41]
	v_mfma_f32_16x16x32_bf16 v[34:37], v[172:175], v[200:203], v[34:37]
	v_mfma_f32_16x16x32_bf16 v[22:25], v[164:167], v[208:211], v[22:25]
	v_mfma_f32_16x16x32_bf16 v[18:21], v[172:175], v[208:211], v[18:21]
	v_mfma_f32_16x16x32_bf16 v[6:9], v[164:167], v[216:219], v[6:9]
	v_mfma_f32_16x16x32_bf16 v[2:5], v[172:175], v[216:219], v[2:5]
	s_setprio 0
	s_add_i32 s80, s80, 2
	s_add_u32 s52, s52, 0x100
	s_addc_u32 s53, s53, 0
	s_add_u32 s78, s78, 0x100
	s_addc_u32 s79, s79, 0
	s_cmp_gt_u32 s80, 13
	s_barrier
	s_cbranch_scc0 .LBB0_206
	s_and_b64 vcc, exec, s[40:41]
	s_cbranch_vccz .LBB0_209
	s_barrier

;     __device__ __forceinline__ bool next(int i, Unit& u) const { if (i >= n) return false; int o = own; asm volatile("" : "+s"(o)); u.pm = swap ? i : o; u.pn = swap ? o : i; u.idx = i; return true; }
; #define PG8_STAGE(bufoff, gbase, voff) do { _Pragma("unroll") for (int _i = 0; _i < 2; ++_i) \
;         __builtin_amdgcn_global_load_lds((const unsigned*)((const char*)(gbase) + (voff)[_i]), (PG8_LAS unsigned*)(lds + (bufoff) + ldsw + _i * 8192), 16, 0, 0); } while (0)
; #define PG8_LDA(dst, b, h) do { _Pragma("unroll") for (int m = 0; m < 4; ++m) _Pragma("unroll") for (int k = 0; k < 2; ++k) dst[m][k] = *(const PG8_LAS bf16x8*)(lds + PG8_SA(b, h) + aoff + m * 2048 + k * 1024); } while (0)
; #define PG8_LDB(dst, b, h) do { _Pragma("unroll") for (int n = 0; n < 2; ++n) _Pragma("unroll") for (int k = 0; k < 2; ++k) dst[n][k] = *(const PG8_LAS bf16x8*)(lds + PG8_SB(b, h) + boff + n * 2048 + k * 1024); } while (0)
; #define PG8_WAIT_V(n) asm volatile("s_waitcnt vmcnt(" #n ")" ::: "memory")
; template <class Epi, class Sched, bool ALIGN_EPI = false, bool SP2 = false>
; __device__ __forceinline__ void gemm_phase(PG8_LAS unsigned char* lds, const Gemm g, const Sched& S, const Epi& E, int tid_in) {
;     ...
;         const bool has_next = S.next(ui + 1, nxt);
;         const char* nA = has_next ? (const char*)g.A + (size_t)nxt.pm * tstep : cA; const char* nB = has_next ? (const char*)g.Bt + (size_t)nxt.pn * tstep : cB;
;         for (int t = 0; t < nt; t += 2) {
;             const bool last = (t == nt - 2);
;             const char* a1 = cA + (size_t)(t + 1) * kstep;
;             const char* a2 = last ? nA : cA + (size_t)(t + 2) * kstep; const char* b2 = last ? nB : cB + (size_t)(t + 2) * kstep;
;             const char* a3 = a2 + kstep; const char* b3 = b2 + kstep;
;             if (last && has_next) S.a_ready(nxt);
;             if constexpr (SP2) {
;             PG8_LDB(B0, 0, 0); PG8_LDB(B1, 0, 1); PG8_SCHED; PG8_LDA(At, 0, 0); PG8_STAGE(PG8_SA(1, 1), a1 + hstep, voffA);
;             PG8_WAIT_V(8); PG8_WAIT_L(0); PG8_BAR; PG8_MMA(0, 0, At, B0); PG8_MMA(0, 1, At, B1); PG8_BAR; PG8_SCHED;
;             PG8_LDA(At, 0, 1); PG8_STAGE(PG8_SB(0, 0), b2, voffB); PG8_STAGE(PG8_SB(0, 1), b2 + hstep, voffB); PG8_STAGE(PG8_SA(0, 0), a2, voffA);
;             PG8_WAIT_V(8); PG8_WAIT_L(0); PG8_BAR; PG8_MMA(1, 0, At, B0); PG8_MMA(1, 1, At, B1); PG8_BAR; PG8_SCHED;
.LBB0_358:
	s_ashr_i32 s51, s50, 31
	s_lshl_b64 s[54:55], s[50:51], 19
	s_add_u32 s54, s68, s54
	s_addc_u32 s55, s69, s55
	s_and_b64 s[56:57], s[48:49], exec
	s_cselect_b32 s51, s55, s59
	s_cselect_b32 s81, s54, s58
	s_ashr_i32 s53, s52, 31
	s_lshl_b64 s[56:57], s[52:53], 19
	s_add_u32 s56, s64, s56
	s_addc_u32 s57, s65, s57
	s_and_b64 s[62:63], s[48:49], exec
	s_cselect_b32 s53, s57, s61
	s_cselect_b32 s82, s56, s60
	s_add_u32 s58, s58, 0x40080
	s_addc_u32 s59, s59, 0
	s_add_u32 s83, s60, 0x100
	s_addc_u32 vcc_lo, s61, 0
	s_mov_b32 vcc_hi, -2
	s_waitcnt vmcnt(0)
	v_add_u32_e32 v142, s84, v214
	v_add_u32_e32 v158, s85, v214
	s_waitcnt lgkmcnt(0)
	ds_read_b128 v[130:133], v142
	ds_read_b128 v[134:137], v142 offset:1024
	ds_read_b128 v[138:141], v142 offset:2048
	ds_read_b128 v[142:145], v142 offset:3072
	ds_read_b128 v[146:149], v158
	ds_read_b128 v[150:153], v158 offset:1024
	ds_read_b128 v[154:157], v158 offset:2048
	ds_read_b128 v[158:161], v158 offset:3072
	s_add_u32 s60, s58, 0xfffc0080
	s_addc_u32 s61, s59, -1
	s_cmp_eq_u32 vcc_hi, 12
	s_cselect_b32 s63, s51, s61
	s_cselect_b32 s62, s81, s60
	s_cselect_b32 s61, s53, vcc_lo
	s_cselect_b32 s60, s82, s83
	v_lshl_add_u64 v[216:217], s[58:59], 0, v[202:203]
	s_add_i32 m0, s76, 0xc000
	ds_read_b128 v[162:165], v215
	ds_read_b128 v[166:169], v215 offset:1024
	ds_read_b128 v[170:173], v215 offset:2048
	ds_read_b128 v[174:177], v215 offset:3072
	ds_read_b128 v[178:181], v215 offset:4096
	ds_read_b128 v[182:185], v215 offset:5120
	ds_read_b128 v[206:209], v215 offset:6144
	ds_read_b128 v[210:213], v215 offset:7168
	global_load_lds_dwordx4 v[216:217], off
	v_lshl_add_u64 v[216:217], s[58:59], 0, v[204:205]
	s_add_i32 m0, s76, 0xe000
	s_nop 0
	global_load_lds_dwordx4 v[216:217], off
	s_waitcnt vmcnt(8)
	s_waitcnt lgkmcnt(0)
	s_barrier
	s_setprio 1
	s_waitcnt lgkmcnt(0)
	v_mfma_f32_16x16x32_bf16 v[126:129], v[130:133], v[162:165], 0
	v_mfma_f32_16x16x32_bf16 v[122:125], v[138:141], v[162:165], 0
	v_mfma_f32_16x16x32_bf16 v[110:113], v[130:133], v[170:173], 0
	v_mfma_f32_16x16x32_bf16 v[106:109], v[138:141], v[170:173], 0
	v_mfma_f32_16x16x32_bf16 v[94:97], v[130:133], v[178:181], 0
	v_mfma_f32_16x16x32_bf16 v[90:93], v[138:141], v[178:181], 0
	v_mfma_f32_16x16x32_bf16 v[78:81], v[130:133], v[206:209], 0
	v_mfma_f32_16x16x32_bf16 v[74:77], v[138:141], v[206:209], 0
	v_mfma_f32_16x16x32_bf16 v[126:129], v[134:137], v[166:169], v[126:129]
	v_mfma_f32_16x16x32_bf16 v[122:125], v[142:145], v[166:169], v[122:125]
	v_mfma_f32_16x16x32_bf16 v[110:113], v[134:137], v[174:177], v[110:113]
	v_mfma_f32_16x16x32_bf16 v[106:109], v[142:145], v[174:177], v[106:109]
	v_mfma_f32_16x16x32_bf16 v[94:97], v[134:137], v[182:185], v[94:97]
	v_mfma_f32_16x16x32_bf16 v[90:93], v[142:145], v[182:185], v[90:93]
	v_mfma_f32_16x16x32_bf16 v[78:81], v[134:137], v[210:213], v[78:81]
	v_mfma_f32_16x16x32_bf16 v[74:77], v[142:145], v[210:213], v[74:77]
	s_setprio 0
	s_setprio 1
	v_mfma_f32_16x16x32_bf16 v[118:121], v[146:149], v[162:165], 0
	v_mfma_f32_16x16x32_bf16 v[114:117], v[154:157], v[162:165], 0
	v_mfma_f32_16x16x32_bf16 v[102:105], v[146:149], v[170:173], 0
	v_mfma_f32_16x16x32_bf16 v[98:101], v[154:157], v[170:173], 0
	v_mfma_f32_16x16x32_bf16 v[86:89], v[146:149], v[178:181], 0
	v_mfma_f32_16x16x32_bf16 v[82:85], v[154:157], v[178:181], 0
	v_mfma_f32_16x16x32_bf16 v[70:73], v[146:149], v[206:209], 0
	v_mfma_f32_16x16x32_bf16 v[66:69], v[154:157], v[206:209], 0
	v_mfma_f32_16x16x32_bf16 v[118:121], v[150:153], v[166:169], v[118:121]
	v_mfma_f32_16x16x32_bf16 v[114:117], v[158:161], v[166:169], v[114:117]
	v_mfma_f32_16x16x32_bf16 v[102:105], v[150:153], v[174:177], v[102:105]
	v_mfma_f32_16x16x32_bf16 v[98:101], v[158:161], v[174:177], v[98:101]
	v_mfma_f32_16x16x32_bf16 v[86:89], v[150:153], v[182:185], v[86:89]
	v_mfma_f32_16x16x32_bf16 v[82:85], v[158:161], v[182:185], v[82:85]
	v_mfma_f32_16x16x32_bf16 v[70:73], v[150:153], v[210:213], v[70:73]
	v_mfma_f32_16x16x32_bf16 v[66:69], v[158:161], v[210:213], v[66:69]
	s_setprio 0
	s_barrier
	s_add_i32 s92, s84, s75
	v_lshl_add_u64 v[216:217], s[60:61], 0, v[0:1]
	s_mov_b32 m0, s92
	ds_read_b128 v[162:165], v215 offset:16384
	ds_read_b128 v[166:169], v215 offset:17408
	ds_read_b128 v[170:173], v215 offset:18432
	ds_read_b128 v[174:177], v215 offset:19456
	ds_read_b128 v[178:181], v215 offset:20480
	ds_read_b128 v[182:185], v215 offset:21504
	ds_read_b128 v[206:209], v215 offset:22528
	ds_read_b128 v[210:213], v215 offset:23552
	global_load_lds_dwordx4 v[216:217], off
	s_add_i32 m0, s92, 0x2000
	s_add_u32 s92, s60, 0x40000
	v_lshl_add_u64 v[218:219], s[60:61], 0, v[196:197]
	s_addc_u32 s93, s61, 0
	s_add_i32 s94, s85, s75
	global_load_lds_dwordx4 v[218:219], off
	v_lshl_add_u64 v[220:221], s[92:93], 0, v[0:1]
	s_mov_b32 m0, s94
	v_lshl_add_u64 v[222:223], s[62:63], 0, v[198:199]
	global_load_lds_dwordx4 v[220:221], off
	v_lshl_add_u64 v[220:221], s[92:93], 0, v[196:197]
	s_add_i32 m0, s94, 0x2000
	s_nop 0
	global_load_lds_dwordx4 v[220:221], off
	v_lshl_add_u64 v[220:221], s[62:63], 0, v[200:201]
	s_mov_b32 m0, s76
	s_nop 0
	global_load_lds_dwordx4 v[220:221], off
	s_mov_b32 m0, s77
	s_nop 0
	global_load_lds_dwordx4 v[222:223], off
	s_waitcnt vmcnt(8)
	s_waitcnt lgkmcnt(0)
	s_barrier
; #define PG8_STAGE(bufoff, gbase, voff) do { _Pragma("unroll") for (int _i = 0; _i < 2; ++_i) \
;         __builtin_amdgcn_global_load_lds((const unsigned*)((const char*)(gbase) + (voff)[_i]), (PG8_LAS unsigned*)(lds + (bufoff) + ldsw + _i * 8192), 16, 0, 0); } while (0)
; #define PG8_LDA(dst, b, h) do { _Pragma("unroll") for (int m = 0; m < 4; ++m) _Pragma("unroll") for (int k = 0; k < 2; ++k) dst[m][k] = *(const PG8_LAS bf16x8*)(lds + PG8_SA(b, h) + aoff + m * 2048 + k * 1024); } while (0)
; #define PG8_LDB(dst, b, h) do { _Pragma("unroll") for (int n = 0; n < 2; ++n) _Pragma("unroll") for (int k = 0; k < 2; ++k) dst[n][k] = *(const PG8_LAS bf16x8*)(lds + PG8_SB(b, h) + boff + n * 2048 + k * 1024); } while (0)
; #define PG8_MMA(ai, bj, At, Bt) do { __builtin_amdgcn_s_setprio(1); _Pragma("unroll") for (int k = 0; k < 2; ++k) _Pragma("unroll") for (int m = 0; m < 4; ++m) _Pragma("unroll") for (int n = 0; n < 2; ++n) \
;         acc[ai][bj][m][n] = __builtin_amdgcn_mfma_f32_16x16x32_bf16(Bt[n][k], At[m][k], acc[ai][bj][m][n], 0, 0, 0); __builtin_amdgcn_s_setprio(0); } while (0)
; #define PG8_WAIT_V(n) asm volatile("s_waitcnt vmcnt(" #n ")" ::: "memory")
; #define PG8_WAIT_L(n) asm volatile("s_waitcnt lgkmcnt(" #n ")" ::: "memory")
; #define PG8_BAR __builtin_amdgcn_s_barrier()
; #define PG8_SCHED __builtin_amdgcn_sched_barrier(0)
; template <class Epi, class Sched, bool ALIGN_EPI = false, bool SP2 = false>
; __device__ __forceinline__ void gemm_phase(PG8_LAS unsigned char* lds, const Gemm g, const Sched& S, const Epi& E, int tid_in) {
;     ...
;             PG8_WAIT_V(8); PG8_WAIT_L(0); PG8_BAR; PG8_MMA(1, 0, At, B0); PG8_MMA(1, 1, At, B1); PG8_BAR; PG8_SCHED;
;             PG8_LDB(B0, 1, 0); PG8_LDB(B1, 1, 1); PG8_SCHED; PG8_LDA(At, 1, 0); PG8_STAGE(PG8_SA(0, 1), a2 + hstep, voffA);
;             PG8_WAIT_V(8); PG8_WAIT_L(0); PG8_BAR; PG8_MMA(0, 0, At, B0); PG8_MMA(0, 1, At, B1); PG8_BAR; PG8_SCHED;
	s_setprio 1
	s_waitcnt lgkmcnt(0)
	v_mfma_f32_16x16x32_bf16 v[62:65], v[130:133], v[162:165], 0
	v_mfma_f32_16x16x32_bf16 v[58:61], v[138:141], v[162:165], 0
	v_mfma_f32_16x16x32_bf16 v[46:49], v[130:133], v[170:173], 0
	v_mfma_f32_16x16x32_bf16 v[42:45], v[138:141], v[170:173], 0
	v_mfma_f32_16x16x32_bf16 v[30:33], v[130:133], v[178:181], 0
	v_mfma_f32_16x16x32_bf16 v[26:29], v[138:141], v[178:181], 0
	v_mfma_f32_16x16x32_bf16 v[14:17], v[130:133], v[206:209], 0
	v_mfma_f32_16x16x32_bf16 v[10:13], v[138:141], v[206:209], 0
	v_mfma_f32_16x16x32_bf16 v[62:65], v[134:137], v[166:169], v[62:65]
	v_mfma_f32_16x16x32_bf16 v[58:61], v[142:145], v[166:169], v[58:61]
	v_mfma_f32_16x16x32_bf16 v[46:49], v[134:137], v[174:177], v[46:49]
	v_mfma_f32_16x16x32_bf16 v[42:45], v[142:145], v[174:177], v[42:45]
	v_mfma_f32_16x16x32_bf16 v[30:33], v[134:137], v[182:185], v[30:33]
	v_mfma_f32_16x16x32_bf16 v[26:29], v[142:145], v[182:185], v[26:29]
	v_mfma_f32_16x16x32_bf16 v[14:17], v[134:137], v[210:213], v[14:17]
	v_mfma_f32_16x16x32_bf16 v[10:13], v[142:145], v[210:213], v[10:13]
	s_setprio 0
	s_setprio 1
	v_mfma_f32_16x16x32_bf16 v[54:57], v[146:149], v[162:165], 0
	v_mfma_f32_16x16x32_bf16 v[50:53], v[154:157], v[162:165], 0
	v_mfma_f32_16x16x32_bf16 v[38:41], v[146:149], v[170:173], 0
	v_mfma_f32_16x16x32_bf16 v[34:37], v[154:157], v[170:173], 0
	v_mfma_f32_16x16x32_bf16 v[22:25], v[146:149], v[178:181], 0
	v_mfma_f32_16x16x32_bf16 v[18:21], v[154:157], v[178:181], 0
	v_mfma_f32_16x16x32_bf16 v[6:9], v[146:149], v[206:209], 0
	v_mfma_f32_16x16x32_bf16 v[2:5], v[154:157], v[206:209], 0
	v_mfma_f32_16x16x32_bf16 v[54:57], v[150:153], v[166:169], v[54:57]
	v_mfma_f32_16x16x32_bf16 v[50:53], v[158:161], v[166:169], v[50:53]
	v_mfma_f32_16x16x32_bf16 v[38:41], v[150:153], v[174:177], v[38:41]
	v_mfma_f32_16x16x32_bf16 v[34:37], v[158:161], v[174:177], v[34:37]
	v_mfma_f32_16x16x32_bf16 v[22:25], v[150:153], v[182:185], v[22:25]
	v_mfma_f32_16x16x32_bf16 v[18:21], v[158:161], v[182:185], v[18:21]
	v_mfma_f32_16x16x32_bf16 v[6:9], v[150:153], v[210:213], v[6:9]
	v_mfma_f32_16x16x32_bf16 v[2:5], v[158:161], v[210:213], v[2:5]
	s_setprio 0
	s_barrier
	v_add_u32_e32 v142, s33, v214
	v_add_u32_e32 v158, s74, v214
	ds_read_b128 v[130:133], v142
	ds_read_b128 v[134:137], v142 offset:1024
	ds_read_b128 v[138:141], v142 offset:2048
	ds_read_b128 v[142:145], v142 offset:3072
	ds_read_b128 v[146:149], v158
	ds_read_b128 v[150:153], v158 offset:1024
	ds_read_b128 v[154:157], v158 offset:2048
	ds_read_b128 v[158:161], v158 offset:3072
	s_add_u32 s62, s62, 0x40000
	s_addc_u32 s63, s63, 0
	s_mov_b32 m0, s78
	v_lshl_add_u64 v[224:225], s[62:63], 0, v[200:201]
	ds_read_b128 v[162:165], v215 offset:32768
	ds_read_b128 v[166:169], v215 offset:33792
	ds_read_b128 v[170:173], v215 offset:34816
	ds_read_b128 v[174:177], v215 offset:35840
	ds_read_b128 v[178:181], v215 offset:36864
	ds_read_b128 v[182:185], v215 offset:37888
	ds_read_b128 v[206:209], v215 offset:38912
	ds_read_b128 v[210:213], v215 offset:39936
	global_load_lds_dwordx4 v[224:225], off
	v_lshl_add_u64 v[224:225], s[62:63], 0, v[198:199]
	s_mov_b32 m0, s79
	s_nop 0
	global_load_lds_dwordx4 v[224:225], off
	s_waitcnt vmcnt(8)
	s_waitcnt lgkmcnt(0)
	s_barrier
	s_setprio 1
	s_waitcnt lgkmcnt(0)
	v_mfma_f32_16x16x32_bf16 v[126:129], v[130:133], v[162:165], v[126:129]
	v_mfma_f32_16x16x32_bf16 v[122:125], v[138:141], v[162:165], v[122:125]
	v_mfma_f32_16x16x32_bf16 v[110:113], v[130:133], v[170:173], v[110:113]
	v_mfma_f32_16x16x32_bf16 v[106:109], v[138:141], v[170:173], v[106:109]
	v_mfma_f32_16x16x32_bf16 v[94:97], v[130:133], v[178:181], v[94:97]
	v_mfma_f32_16x16x32_bf16 v[90:93], v[138:141], v[178:181], v[90:93]
	v_mfma_f32_16x16x32_bf16 v[78:81], v[130:133], v[206:209], v[78:81]
	v_mfma_f32_16x16x32_bf16 v[74:77], v[138:141], v[206:209], v[74:77]
	v_mfma_f32_16x16x32_bf16 v[126:129], v[134:137], v[166:169], v[126:129]
	v_mfma_f32_16x16x32_bf16 v[122:125], v[142:145], v[166:169], v[122:125]
	v_mfma_f32_16x16x32_bf16 v[110:113], v[134:137], v[174:177], v[110:113]
	v_mfma_f32_16x16x32_bf16 v[106:109], v[142:145], v[174:177], v[106:109]
	v_mfma_f32_16x16x32_bf16 v[94:97], v[134:137], v[182:185], v[94:97]
	v_mfma_f32_16x16x32_bf16 v[90:93], v[142:145], v[182:185], v[90:93]
	v_mfma_f32_16x16x32_bf16 v[78:81], v[134:137], v[210:213], v[78:81]
	v_mfma_f32_16x16x32_bf16 v[74:77], v[142:145], v[210:213], v[74:77]
	s_setprio 0
	s_setprio 1
	v_mfma_f32_16x16x32_bf16 v[118:121], v[146:149], v[162:165], v[118:121]
	v_mfma_f32_16x16x32_bf16 v[114:117], v[154:157], v[162:165], v[114:117]
	v_mfma_f32_16x16x32_bf16 v[102:105], v[146:149], v[170:173], v[102:105]
	v_mfma_f32_16x16x32_bf16 v[98:101], v[154:157], v[170:173], v[98:101]
	v_mfma_f32_16x16x32_bf16 v[86:89], v[146:149], v[178:181], v[86:89]
	v_mfma_f32_16x16x32_bf16 v[82:85], v[154:157], v[178:181], v[82:85]
	v_mfma_f32_16x16x32_bf16 v[70:73], v[146:149], v[206:209], v[70:73]
	v_mfma_f32_16x16x32_bf16 v[66:69], v[154:157], v[206:209], v[66:69]
	v_mfma_f32_16x16x32_bf16 v[118:121], v[150:153], v[166:169], v[118:121]
	v_mfma_f32_16x16x32_bf16 v[114:117], v[158:161], v[166:169], v[114:117]
	v_mfma_f32_16x16x32_bf16 v[102:105], v[150:153], v[174:177], v[102:105]
	v_mfma_f32_16x16x32_bf16 v[98:101], v[158:161], v[174:177], v[98:101]
	v_mfma_f32_16x16x32_bf16 v[86:89], v[150:153], v[182:185], v[86:89]
	v_mfma_f32_16x16x32_bf16 v[82:85], v[158:161], v[182:185], v[82:85]
	v_mfma_f32_16x16x32_bf16 v[70:73], v[150:153], v[210:213], v[70:73]
	v_mfma_f32_16x16x32_bf16 v[66:69], v[158:161], v[210:213], v[66:69]
	s_setprio 0
	s_barrier
; #define PG8_STAGE(bufoff, gbase, voff) do { _Pragma("unroll") for (int _i = 0; _i < 2; ++_i) \
;         __builtin_amdgcn_global_load_lds((const unsigned*)((const char*)(gbase) + (voff)[_i]), (PG8_LAS unsigned*)(lds + (bufoff) + ldsw + _i * 8192), 16, 0, 0); } while (0)
; #define PG8_LDA(dst, b, h) do { _Pragma("unroll") for (int m = 0; m < 4; ++m) _Pragma("unroll") for (int k = 0; k < 2; ++k) dst[m][k] = *(const PG8_LAS bf16x8*)(lds + PG8_SA(b, h) + aoff + m * 2048 + k * 1024); } while (0)
; #define PG8_LDB(dst, b, h) do { _Pragma("unroll") for (int n = 0; n < 2; ++n) _Pragma("unroll") for (int k = 0; k < 2; ++k) dst[n][k] = *(const PG8_LAS bf16x8*)(lds + PG8_SB(b, h) + boff + n * 2048 + k * 1024); } while (0)
; #define PG8_MMA(ai, bj, At, Bt) do { __builtin_amdgcn_s_setprio(1); _Pragma("unroll") for (int k = 0; k < 2; ++k) _Pragma("unroll") for (int m = 0; m < 4; ++m) _Pragma("unroll") for (int n = 0; n < 2; ++n) \
;         acc[ai][bj][m][n] = __builtin_amdgcn_mfma_f32_16x16x32_bf16(Bt[n][k], At[m][k], acc[ai][bj][m][n], 0, 0, 0); __builtin_amdgcn_s_setprio(0); } while (0)
; #define PG8_WAIT_V(n) asm volatile("s_waitcnt vmcnt(" #n ")" ::: "memory")
; #define PG8_BAR __builtin_amdgcn_s_barrier()
; template <class Epi, class Sched, bool ALIGN_EPI = false, bool SP2 = false>
; __device__ __forceinline__ void gemm_phase(PG8_LAS unsigned char* lds, const Gemm g, const Sched& S, const Epi& E, int tid_in) {
;     ...
;         for (int t = 0; t < nt; t += 2) {
;             const bool last = (t == nt - 2);
;             const char* a1 = cA + (size_t)(t + 1) * kstep;
;             const char* a2 = last ? nA : cA + (size_t)(t + 2) * kstep; const char* b2 = last ? nB : cB + (size_t)(t + 2) * kstep;
;             const char* a3 = a2 + kstep; const char* b3 = b2 + kstep;
;             if (last && has_next) S.a_ready(nxt);
;             if constexpr (SP2) {
;             PG8_LDB(B0, 0, 0); PG8_LDB(B1, 0, 1); PG8_SCHED; PG8_LDA(At, 0, 0); PG8_STAGE(PG8_SA(1, 1), a1 + hstep, voffA);
;             PG8_WAIT_V(8); PG8_WAIT_L(0); PG8_BAR; PG8_MMA(0, 0, At, B0); PG8_MMA(0, 1, At, B1); PG8_BAR; PG8_SCHED;
;     ...
;             PG8_LDA(At, 1, 1); PG8_STAGE(PG8_SB(1, 0), b3, voffB); PG8_STAGE(PG8_SB(1, 1), b3 + hstep, voffB); PG8_STAGE(PG8_SA(1, 0), a3, voffA);
;             PG8_WAIT_V(8); PG8_WAIT_L(0); PG8_BAR; PG8_MMA(1, 0, At, B0); PG8_MMA(1, 1, At, B1); PG8_BAR; PG8_SCHED;
	s_add_i32 s62, s33, s75
	v_lshl_add_u64 v[216:217], v[216:217], 0, s[26:27]
	s_mov_b32 m0, s62
	ds_read_b128 v[162:165], v215 offset:49152
	ds_read_b128 v[166:169], v215 offset:50176
	ds_read_b128 v[170:173], v215 offset:51200
	ds_read_b128 v[174:177], v215 offset:52224
	ds_read_b128 v[178:181], v215 offset:53248
	ds_read_b128 v[182:185], v215 offset:54272
	ds_read_b128 v[206:209], v215 offset:55296
	ds_read_b128 v[210:213], v215 offset:56320
	global_load_lds_dwordx4 v[216:217], off
	s_add_i32 m0, s62, 0x2000
	s_add_u32 s60, s60, 0x40080
	v_lshl_add_u64 v[216:217], v[218:219], 0, s[26:27]
	s_addc_u32 s61, s61, 0
	s_add_i32 s62, s74, s75
	global_load_lds_dwordx4 v[216:217], off
	v_lshl_add_u64 v[216:217], s[60:61], 0, v[0:1]
	s_mov_b32 m0, s62
	s_nop 0
	global_load_lds_dwordx4 v[216:217], off
	v_lshl_add_u64 v[216:217], s[60:61], 0, v[196:197]
	s_add_i32 m0, s62, 0x2000
	s_nop 0
	global_load_lds_dwordx4 v[216:217], off
	v_lshl_add_u64 v[216:217], v[220:221], 0, s[26:27]
	s_mov_b32 m0, s38
	s_nop 0
	global_load_lds_dwordx4 v[216:217], off
	v_lshl_add_u64 v[216:217], v[222:223], 0, s[26:27]
	s_mov_b32 m0, s39
	s_nop 0
	global_load_lds_dwordx4 v[216:217], off
	s_waitcnt vmcnt(8)
	s_waitcnt lgkmcnt(0)
	s_barrier
	s_setprio 1
	s_waitcnt lgkmcnt(0)
	v_mfma_f32_16x16x32_bf16 v[62:65], v[130:133], v[162:165], v[62:65]
	v_mfma_f32_16x16x32_bf16 v[58:61], v[138:141], v[162:165], v[58:61]
	v_mfma_f32_16x16x32_bf16 v[46:49], v[130:133], v[170:173], v[46:49]
	v_mfma_f32_16x16x32_bf16 v[42:45], v[138:141], v[170:173], v[42:45]
	v_mfma_f32_16x16x32_bf16 v[30:33], v[130:133], v[178:181], v[30:33]
	v_mfma_f32_16x16x32_bf16 v[26:29], v[138:141], v[178:181], v[26:29]
	v_mfma_f32_16x16x32_bf16 v[14:17], v[130:133], v[206:209], v[14:17]
	v_mfma_f32_16x16x32_bf16 v[10:13], v[138:141], v[206:209], v[10:13]
	v_mfma_f32_16x16x32_bf16 v[62:65], v[134:137], v[166:169], v[62:65]
	v_mfma_f32_16x16x32_bf16 v[58:61], v[142:145], v[166:169], v[58:61]
	v_mfma_f32_16x16x32_bf16 v[46:49], v[134:137], v[174:177], v[46:49]
	v_mfma_f32_16x16x32_bf16 v[42:45], v[142:145], v[174:177], v[42:45]
	v_mfma_f32_16x16x32_bf16 v[30:33], v[134:137], v[182:185], v[30:33]
	v_mfma_f32_16x16x32_bf16 v[26:29], v[142:145], v[182:185], v[26:29]
	v_mfma_f32_16x16x32_bf16 v[14:17], v[134:137], v[210:213], v[14:17]
	v_mfma_f32_16x16x32_bf16 v[10:13], v[142:145], v[210:213], v[10:13]
	s_setprio 0
	s_setprio 1
	v_mfma_f32_16x16x32_bf16 v[54:57], v[146:149], v[162:165], v[54:57]
	v_mfma_f32_16x16x32_bf16 v[50:53], v[154:157], v[162:165], v[50:53]
	v_mfma_f32_16x16x32_bf16 v[38:41], v[146:149], v[170:173], v[38:41]
	v_mfma_f32_16x16x32_bf16 v[34:37], v[154:157], v[170:173], v[34:37]
	v_mfma_f32_16x16x32_bf16 v[22:25], v[146:149], v[178:181], v[22:25]
	v_mfma_f32_16x16x32_bf16 v[18:21], v[154:157], v[178:181], v[18:21]
	v_mfma_f32_16x16x32_bf16 v[6:9], v[146:149], v[206:209], v[6:9]
	v_mfma_f32_16x16x32_bf16 v[2:5], v[154:157], v[206:209], v[2:5]
	v_mfma_f32_16x16x32_bf16 v[54:57], v[150:153], v[166:169], v[54:57]
	v_mfma_f32_16x16x32_bf16 v[50:53], v[158:161], v[166:169], v[50:53]
	v_mfma_f32_16x16x32_bf16 v[38:41], v[150:153], v[174:177], v[38:41]
	v_mfma_f32_16x16x32_bf16 v[34:37], v[158:161], v[174:177], v[34:37]
	v_mfma_f32_16x16x32_bf16 v[22:25], v[150:153], v[182:185], v[22:25]
	v_mfma_f32_16x16x32_bf16 v[18:21], v[158:161], v[182:185], v[18:21]
	v_mfma_f32_16x16x32_bf16 v[6:9], v[150:153], v[210:213], v[6:9]
	v_mfma_f32_16x16x32_bf16 v[2:5], v[158:161], v[210:213], v[2:5]
	s_setprio 0
	s_add_i32 vcc_hi, vcc_hi, 2
	s_add_u32 s58, s58, 0x100
	s_addc_u32 s59, s59, 0
	s_add_u32 s83, s83, 0x100
	s_addc_u32 vcc_lo, vcc_lo, 0
	s_cmp_gt_u32 vcc_hi, 13
	s_barrier
.LBB0_359:
	v_add_u32_e32 v142, s84, v214
	v_add_u32_e32 v158, s85, v214
	s_waitcnt lgkmcnt(0)
	ds_read_b128 v[130:133], v142
	ds_read_b128 v[134:137], v142 offset:1024
	ds_read_b128 v[138:141], v142 offset:2048
	ds_read_b128 v[142:145], v142 offset:3072
	ds_read_b128 v[146:149], v158
	ds_read_b128 v[150:153], v158 offset:1024
	ds_read_b128 v[154:157], v158 offset:2048
	ds_read_b128 v[158:161], v158 offset:3072
	s_add_u32 s60, s58, 0xfffc0080
	s_addc_u32 s61, s59, -1
	s_cmp_eq_u32 vcc_hi, 12
	s_cselect_b32 s63, s51, s61
	s_cselect_b32 s62, s81, s60
	s_cselect_b32 s61, s53, vcc_lo
	s_cselect_b32 s60, s82, s83
	v_lshl_add_u64 v[216:217], s[58:59], 0, v[202:203]
	s_add_i32 m0, s76, 0xc000
	ds_read_b128 v[162:165], v215
	ds_read_b128 v[166:169], v215 offset:1024
	ds_read_b128 v[170:173], v215 offset:2048
	ds_read_b128 v[174:177], v215 offset:3072
	ds_read_b128 v[178:181], v215 offset:4096
	ds_read_b128 v[182:185], v215 offset:5120
	ds_read_b128 v[206:209], v215 offset:6144
	ds_read_b128 v[210:213], v215 offset:7168
	global_load_lds_dwordx4 v[216:217], off
	v_lshl_add_u64 v[216:217], s[58:59], 0, v[204:205]
	s_add_i32 m0, s76, 0xe000
	s_nop 0
	global_load_lds_dwordx4 v[216:217], off
	s_waitcnt vmcnt(8)
	s_waitcnt lgkmcnt(0)
	s_barrier
; #define PG8_STAGE(bufoff, gbase, voff) do { _Pragma("unroll") for (int _i = 0; _i < 2; ++_i) \
;         __builtin_amdgcn_global_load_lds((const unsigned*)((const char*)(gbase) + (voff)[_i]), (PG8_LAS unsigned*)(lds + (bufoff) + ldsw + _i * 8192), 16, 0, 0); } while (0)
; #define PG8_LDA(dst, b, h) do { _Pragma("unroll") for (int m = 0; m < 4; ++m) _Pragma("unroll") for (int k = 0; k < 2; ++k) dst[m][k] = *(const PG8_LAS bf16x8*)(lds + PG8_SA(b, h) + aoff + m * 2048 + k * 1024); } while (0)
; #define PG8_MMA(ai, bj, At, Bt) do { __builtin_amdgcn_s_setprio(1); _Pragma("unroll") for (int k = 0; k < 2; ++k) _Pragma("unroll") for (int m = 0; m < 4; ++m) _Pragma("unroll") for (int n = 0; n < 2; ++n) \
;         acc[ai][bj][m][n] = __builtin_amdgcn_mfma_f32_16x16x32_bf16(Bt[n][k], At[m][k], acc[ai][bj][m][n], 0, 0, 0); __builtin_amdgcn_s_setprio(0); } while (0)
; #define PG8_WAIT_V(n) asm volatile("s_waitcnt vmcnt(" #n ")" ::: "memory")
; #define PG8_WAIT_L(n) asm volatile("s_waitcnt lgkmcnt(" #n ")" ::: "memory")
; #define PG8_BAR __builtin_amdgcn_s_barrier()
; #define PG8_SCHED __builtin_amdgcn_sched_barrier(0)
; template <class Epi, class Sched, bool ALIGN_EPI = false, bool SP2 = false>
; __device__ __forceinline__ void gemm_phase(PG8_LAS unsigned char* lds, const Gemm g, const Sched& S, const Epi& E, int tid_in) {
;     ...
;             PG8_WAIT_V(8); PG8_WAIT_L(0); PG8_BAR; PG8_MMA(0, 0, At, B0); PG8_MMA(0, 1, At, B1); PG8_BAR; PG8_SCHED;
;             PG8_LDA(At, 0, 1); PG8_STAGE(PG8_SB(0, 0), b2, voffB); PG8_STAGE(PG8_SB(0, 1), b2 + hstep, voffB); PG8_STAGE(PG8_SA(0, 0), a2, voffA);
;             PG8_WAIT_V(8); PG8_WAIT_L(0); PG8_BAR; PG8_MMA(1, 0, At, B0); PG8_MMA(1, 1, At, B1); PG8_BAR; PG8_SCHED;
	s_setprio 1
	s_waitcnt lgkmcnt(0)
	v_mfma_f32_16x16x32_bf16 v[126:129], v[130:133], v[162:165], v[126:129]
	v_mfma_f32_16x16x32_bf16 v[122:125], v[138:141], v[162:165], v[122:125]
	v_mfma_f32_16x16x32_bf16 v[110:113], v[130:133], v[170:173], v[110:113]
	v_mfma_f32_16x16x32_bf16 v[106:109], v[138:141], v[170:173], v[106:109]
	v_mfma_f32_16x16x32_bf16 v[94:97], v[130:133], v[178:181], v[94:97]
	v_mfma_f32_16x16x32_bf16 v[90:93], v[138:141], v[178:181], v[90:93]
	v_mfma_f32_16x16x32_bf16 v[78:81], v[130:133], v[206:209], v[78:81]
	v_mfma_f32_16x16x32_bf16 v[74:77], v[138:141], v[206:209], v[74:77]
	v_mfma_f32_16x16x32_bf16 v[126:129], v[134:137], v[166:169], v[126:129]
	v_mfma_f32_16x16x32_bf16 v[122:125], v[142:145], v[166:169], v[122:125]
	v_mfma_f32_16x16x32_bf16 v[110:113], v[134:137], v[174:177], v[110:113]
	v_mfma_f32_16x16x32_bf16 v[106:109], v[142:145], v[174:177], v[106:109]
	v_mfma_f32_16x16x32_bf16 v[94:97], v[134:137], v[182:185], v[94:97]
	v_mfma_f32_16x16x32_bf16 v[90:93], v[142:145], v[182:185], v[90:93]
	v_mfma_f32_16x16x32_bf16 v[78:81], v[134:137], v[210:213], v[78:81]
	v_mfma_f32_16x16x32_bf16 v[74:77], v[142:145], v[210:213], v[74:77]
	s_setprio 0
	s_setprio 1
	v_mfma_f32_16x16x32_bf16 v[118:121], v[146:149], v[162:165], v[118:121]
	v_mfma_f32_16x16x32_bf16 v[114:117], v[154:157], v[162:165], v[114:117]
	v_mfma_f32_16x16x32_bf16 v[102:105], v[146:149], v[170:173], v[102:105]
	v_mfma_f32_16x16x32_bf16 v[98:101], v[154:157], v[170:173], v[98:101]
	v_mfma_f32_16x16x32_bf16 v[86:89], v[146:149], v[178:181], v[86:89]
	v_mfma_f32_16x16x32_bf16 v[82:85], v[154:157], v[178:181], v[82:85]
	v_mfma_f32_16x16x32_bf16 v[70:73], v[146:149], v[206:209], v[70:73]
	v_mfma_f32_16x16x32_bf16 v[66:69], v[154:157], v[206:209], v[66:69]
	v_mfma_f32_16x16x32_bf16 v[118:121], v[150:153], v[166:169], v[118:121]
	v_mfma_f32_16x16x32_bf16 v[114:117], v[158:161], v[166:169], v[114:117]
	v_mfma_f32_16x16x32_bf16 v[102:105], v[150:153], v[174:177], v[102:105]
	v_mfma_f32_16x16x32_bf16 v[98:101], v[158:161], v[174:177], v[98:101]
	v_mfma_f32_16x16x32_bf16 v[86:89], v[150:153], v[182:185], v[86:89]
	v_mfma_f32_16x16x32_bf16 v[82:85], v[158:161], v[182:185], v[82:85]
	v_mfma_f32_16x16x32_bf16 v[70:73], v[150:153], v[210:213], v[70:73]
	v_mfma_f32_16x16x32_bf16 v[66:69], v[158:161], v[210:213], v[66:69]
	s_setprio 0
	s_barrier
	s_add_i32 s92, s84, s75
	v_lshl_add_u64 v[216:217], s[60:61], 0, v[0:1]
	s_mov_b32 m0, s92
	ds_read_b128 v[162:165], v215 offset:16384
	ds_read_b128 v[166:169], v215 offset:17408
	ds_read_b128 v[170:173], v215 offset:18432
	ds_read_b128 v[174:177], v215 offset:19456
	ds_read_b128 v[178:181], v215 offset:20480
	ds_read_b128 v[182:185], v215 offset:21504
	ds_read_b128 v[206:209], v215 offset:22528
	ds_read_b128 v[210:213], v215 offset:23552
	global_load_lds_dwordx4 v[216:217], off
	s_add_i32 m0, s92, 0x2000
	s_add_u32 s92, s60, 0x40000
	v_lshl_add_u64 v[218:219], s[60:61], 0, v[196:197]
	s_addc_u32 s93, s61, 0
	s_add_i32 s94, s85, s75
	global_load_lds_dwordx4 v[218:219], off
	v_lshl_add_u64 v[220:221], s[92:93], 0, v[0:1]
	s_mov_b32 m0, s94
	v_lshl_add_u64 v[222:223], s[62:63], 0, v[198:199]
	global_load_lds_dwordx4 v[220:221], off
	v_lshl_add_u64 v[220:221], s[92:93], 0, v[196:197]
	s_add_i32 m0, s94, 0x2000
	s_nop 0
	global_load_lds_dwordx4 v[220:221], off
	v_lshl_add_u64 v[220:221], s[62:63], 0, v[200:201]
	s_mov_b32 m0, s76
	s_nop 0
	global_load_lds_dwordx4 v[220:221], off
	s_mov_b32 m0, s77
	s_nop 0
	global_load_lds_dwordx4 v[222:223], off
	s_waitcnt vmcnt(8)
	s_waitcnt lgkmcnt(0)
	s_barrier
	s_setprio 1
	s_waitcnt lgkmcnt(0)
	v_mfma_f32_16x16x32_bf16 v[62:65], v[130:133], v[162:165], v[62:65]
	v_mfma_f32_16x16x32_bf16 v[58:61], v[138:141], v[162:165], v[58:61]
	v_mfma_f32_16x16x32_bf16 v[46:49], v[130:133], v[170:173], v[46:49]
	v_mfma_f32_16x16x32_bf16 v[42:45], v[138:141], v[170:173], v[42:45]
	v_mfma_f32_16x16x32_bf16 v[30:33], v[130:133], v[178:181], v[30:33]
	v_mfma_f32_16x16x32_bf16 v[26:29], v[138:141], v[178:181], v[26:29]
	v_mfma_f32_16x16x32_bf16 v[14:17], v[130:133], v[206:209], v[14:17]
	v_mfma_f32_16x16x32_bf16 v[10:13], v[138:141], v[206:209], v[10:13]
	v_mfma_f32_16x16x32_bf16 v[62:65], v[134:137], v[166:169], v[62:65]
	v_mfma_f32_16x16x32_bf16 v[58:61], v[142:145], v[166:169], v[58:61]
	v_mfma_f32_16x16x32_bf16 v[46:49], v[134:137], v[174:177], v[46:49]
	v_mfma_f32_16x16x32_bf16 v[42:45], v[142:145], v[174:177], v[42:45]
	v_mfma_f32_16x16x32_bf16 v[30:33], v[134:137], v[182:185], v[30:33]
	v_mfma_f32_16x16x32_bf16 v[26:29], v[142:145], v[182:185], v[26:29]
	v_mfma_f32_16x16x32_bf16 v[14:17], v[134:137], v[210:213], v[14:17]
	v_mfma_f32_16x16x32_bf16 v[10:13], v[142:145], v[210:213], v[10:13]
	s_setprio 0
	s_setprio 1
	v_mfma_f32_16x16x32_bf16 v[54:57], v[146:149], v[162:165], v[54:57]
	v_mfma_f32_16x16x32_bf16 v[50:53], v[154:157], v[162:165], v[50:53]
	v_mfma_f32_16x16x32_bf16 v[38:41], v[146:149], v[170:173], v[38:41]
	v_mfma_f32_16x16x32_bf16 v[34:37], v[154:157], v[170:173], v[34:37]
	v_mfma_f32_16x16x32_bf16 v[22:25], v[146:149], v[178:181], v[22:25]
	v_mfma_f32_16x16x32_bf16 v[18:21], v[154:157], v[178:181], v[18:21]
	v_mfma_f32_16x16x32_bf16 v[6:9], v[146:149], v[206:209], v[6:9]
	v_mfma_f32_16x16x32_bf16 v[2:5], v[154:157], v[206:209], v[2:5]
	v_mfma_f32_16x16x32_bf16 v[54:57], v[150:153], v[166:169], v[54:57]
	v_mfma_f32_16x16x32_bf16 v[50:53], v[158:161], v[166:169], v[50:53]
	v_mfma_f32_16x16x32_bf16 v[38:41], v[150:153], v[174:177], v[38:41]
	v_mfma_f32_16x16x32_bf16 v[34:37], v[158:161], v[174:177], v[34:37]
	v_mfma_f32_16x16x32_bf16 v[22:25], v[150:153], v[182:185], v[22:25]
	v_mfma_f32_16x16x32_bf16 v[18:21], v[158:161], v[182:185], v[18:21]
	v_mfma_f32_16x16x32_bf16 v[6:9], v[150:153], v[210:213], v[6:9]
	v_mfma_f32_16x16x32_bf16 v[2:5], v[158:161], v[210:213], v[2:5]
	s_setprio 0
	s_barrier
; #define PG8_STAGE(bufoff, gbase, voff) do { _Pragma("unroll") for (int _i = 0; _i < 2; ++_i) \
;         __builtin_amdgcn_global_load_lds((const unsigned*)((const char*)(gbase) + (voff)[_i]), (PG8_LAS unsigned*)(lds + (bufoff) + ldsw + _i * 8192), 16, 0, 0); } while (0)
; #define PG8_LDA(dst, b, h) do { _Pragma("unroll") for (int m = 0; m < 4; ++m) _Pragma("unroll") for (int k = 0; k < 2; ++k) dst[m][k] = *(const PG8_LAS bf16x8*)(lds + PG8_SA(b, h) + aoff + m * 2048 + k * 1024); } while (0)
; #define PG8_LDB(dst, b, h) do { _Pragma("unroll") for (int n = 0; n < 2; ++n) _Pragma("unroll") for (int k = 0; k < 2; ++k) dst[n][k] = *(const PG8_LAS bf16x8*)(lds + PG8_SB(b, h) + boff + n * 2048 + k * 1024); } while (0)
; #define PG8_MMA(ai, bj, At, Bt) do { __builtin_amdgcn_s_setprio(1); _Pragma("unroll") for (int k = 0; k < 2; ++k) _Pragma("unroll") for (int m = 0; m < 4; ++m) _Pragma("unroll") for (int n = 0; n < 2; ++n) \
;         acc[ai][bj][m][n] = __builtin_amdgcn_mfma_f32_16x16x32_bf16(Bt[n][k], At[m][k], acc[ai][bj][m][n], 0, 0, 0); __builtin_amdgcn_s_setprio(0); } while (0)
; #define PG8_WAIT_V(n) asm volatile("s_waitcnt vmcnt(" #n ")" ::: "memory")
; #define PG8_WAIT_L(n) asm volatile("s_waitcnt lgkmcnt(" #n ")" ::: "memory")
; #define PG8_BAR __builtin_amdgcn_s_barrier()
; #define PG8_SCHED __builtin_amdgcn_sched_barrier(0)
; template <class Epi, class Sched, bool ALIGN_EPI = false, bool SP2 = false>
; __device__ __forceinline__ void gemm_phase(PG8_LAS unsigned char* lds, const Gemm g, const Sched& S, const Epi& E, int tid_in) {
;     ...
;             PG8_LDB(B0, 1, 0); PG8_LDB(B1, 1, 1); PG8_SCHED; PG8_LDA(At, 1, 0); PG8_STAGE(PG8_SA(0, 1), a2 + hstep, voffA);
;             PG8_WAIT_V(8); PG8_WAIT_L(0); PG8_BAR; PG8_MMA(0, 0, At, B0); PG8_MMA(0, 1, At, B1); PG8_BAR; PG8_SCHED;
	v_add_u32_e32 v142, s33, v214
	v_add_u32_e32 v158, s74, v214
	ds_read_b128 v[130:133], v142
	ds_read_b128 v[134:137], v142 offset:1024
	ds_read_b128 v[138:141], v142 offset:2048
	ds_read_b128 v[142:145], v142 offset:3072
	ds_read_b128 v[146:149], v158
	ds_read_b128 v[150:153], v158 offset:1024
	ds_read_b128 v[154:157], v158 offset:2048
	ds_read_b128 v[158:161], v158 offset:3072
	s_add_u32 s62, s62, 0x40000
	s_addc_u32 s63, s63, 0
	s_mov_b32 m0, s78
	v_lshl_add_u64 v[224:225], s[62:63], 0, v[200:201]
	ds_read_b128 v[162:165], v215 offset:32768
	ds_read_b128 v[166:169], v215 offset:33792
	ds_read_b128 v[170:173], v215 offset:34816
	ds_read_b128 v[174:177], v215 offset:35840
	ds_read_b128 v[178:181], v215 offset:36864
	ds_read_b128 v[182:185], v215 offset:37888
	ds_read_b128 v[206:209], v215 offset:38912
	ds_read_b128 v[210:213], v215 offset:39936
	global_load_lds_dwordx4 v[224:225], off
	v_lshl_add_u64 v[224:225], s[62:63], 0, v[198:199]
	s_mov_b32 m0, s79
	s_nop 0
	global_load_lds_dwordx4 v[224:225], off
	s_waitcnt vmcnt(8)
	s_waitcnt lgkmcnt(0)
	s_barrier
	s_setprio 1
	s_waitcnt lgkmcnt(0)
	v_mfma_f32_16x16x32_bf16 v[126:129], v[130:133], v[162:165], v[126:129]
	v_mfma_f32_16x16x32_bf16 v[122:125], v[138:141], v[162:165], v[122:125]
	v_mfma_f32_16x16x32_bf16 v[110:113], v[130:133], v[170:173], v[110:113]
	v_mfma_f32_16x16x32_bf16 v[106:109], v[138:141], v[170:173], v[106:109]
	v_mfma_f32_16x16x32_bf16 v[94:97], v[130:133], v[178:181], v[94:97]
	v_mfma_f32_16x16x32_bf16 v[90:93], v[138:141], v[178:181], v[90:93]
	v_mfma_f32_16x16x32_bf16 v[78:81], v[130:133], v[206:209], v[78:81]
	v_mfma_f32_16x16x32_bf16 v[74:77], v[138:141], v[206:209], v[74:77]
	v_mfma_f32_16x16x32_bf16 v[126:129], v[134:137], v[166:169], v[126:129]
	v_mfma_f32_16x16x32_bf16 v[122:125], v[142:145], v[166:169], v[122:125]
	v_mfma_f32_16x16x32_bf16 v[110:113], v[134:137], v[174:177], v[110:113]
	v_mfma_f32_16x16x32_bf16 v[106:109], v[142:145], v[174:177], v[106:109]
	v_mfma_f32_16x16x32_bf16 v[94:97], v[134:137], v[182:185], v[94:97]
	v_mfma_f32_16x16x32_bf16 v[90:93], v[142:145], v[182:185], v[90:93]
	v_mfma_f32_16x16x32_bf16 v[78:81], v[134:137], v[210:213], v[78:81]
	v_mfma_f32_16x16x32_bf16 v[74:77], v[142:145], v[210:213], v[74:77]
	s_setprio 0
	s_setprio 1
	v_mfma_f32_16x16x32_bf16 v[118:121], v[146:149], v[162:165], v[118:121]
	v_mfma_f32_16x16x32_bf16 v[114:117], v[154:157], v[162:165], v[114:117]
	v_mfma_f32_16x16x32_bf16 v[102:105], v[146:149], v[170:173], v[102:105]
	v_mfma_f32_16x16x32_bf16 v[98:101], v[154:157], v[170:173], v[98:101]
	v_mfma_f32_16x16x32_bf16 v[86:89], v[146:149], v[178:181], v[86:89]
	v_mfma_f32_16x16x32_bf16 v[82:85], v[154:157], v[178:181], v[82:85]
	v_mfma_f32_16x16x32_bf16 v[70:73], v[146:149], v[206:209], v[70:73]
	v_mfma_f32_16x16x32_bf16 v[66:69], v[154:157], v[206:209], v[66:69]
	v_mfma_f32_16x16x32_bf16 v[118:121], v[150:153], v[166:169], v[118:121]
	v_mfma_f32_16x16x32_bf16 v[114:117], v[158:161], v[166:169], v[114:117]
	v_mfma_f32_16x16x32_bf16 v[102:105], v[150:153], v[174:177], v[102:105]
	v_mfma_f32_16x16x32_bf16 v[98:101], v[158:161], v[174:177], v[98:101]
	v_mfma_f32_16x16x32_bf16 v[86:89], v[150:153], v[182:185], v[86:89]
	v_mfma_f32_16x16x32_bf16 v[82:85], v[158:161], v[182:185], v[82:85]
	v_mfma_f32_16x16x32_bf16 v[70:73], v[150:153], v[210:213], v[70:73]
	v_mfma_f32_16x16x32_bf16 v[66:69], v[158:161], v[210:213], v[66:69]
	s_setprio 0
	s_barrier
; #define PG8_STAGE(bufoff, gbase, voff) do { _Pragma("unroll") for (int _i = 0; _i < 2; ++_i) \
;         __builtin_amdgcn_global_load_lds((const unsigned*)((const char*)(gbase) + (voff)[_i]), (PG8_LAS unsigned*)(lds + (bufoff) + ldsw + _i * 8192), 16, 0, 0); } while (0)
; #define PG8_LDA(dst, b, h) do { _Pragma("unroll") for (int m = 0; m < 4; ++m) _Pragma("unroll") for (int k = 0; k < 2; ++k) dst[m][k] = *(const PG8_LAS bf16x8*)(lds + PG8_SA(b, h) + aoff + m * 2048 + k * 1024); } while (0)
; #define PG8_MMA(ai, bj, At, Bt) do { __builtin_amdgcn_s_setprio(1); _Pragma("unroll") for (int k = 0; k < 2; ++k) _Pragma("unroll") for (int m = 0; m < 4; ++m) _Pragma("unroll") for (int n = 0; n < 2; ++n) \
;         acc[ai][bj][m][n] = __builtin_amdgcn_mfma_f32_16x16x32_bf16(Bt[n][k], At[m][k], acc[ai][bj][m][n], 0, 0, 0); __builtin_amdgcn_s_setprio(0); } while (0)
; #define PG8_WAIT_V(n) asm volatile("s_waitcnt vmcnt(" #n ")" ::: "memory")
; #define PG8_WAIT_L(n) asm volatile("s_waitcnt lgkmcnt(" #n ")" ::: "memory")
; #define PG8_BAR __builtin_amdgcn_s_barrier()
; #define PG8_SCHED __builtin_amdgcn_sched_barrier(0)
; template <class Epi, class Sched, bool ALIGN_EPI = false, bool SP2 = false>
; __device__ __forceinline__ void gemm_phase(PG8_LAS unsigned char* lds, const Gemm g, const Sched& S, const Epi& E, int tid_in) {
;     ...
;             PG8_LDA(At, 1, 1); PG8_STAGE(PG8_SB(1, 0), b3, voffB); PG8_STAGE(PG8_SB(1, 1), b3 + hstep, voffB); PG8_STAGE(PG8_SA(1, 0), a3, voffA);
;             PG8_WAIT_V(8); PG8_WAIT_L(0); PG8_BAR; PG8_MMA(1, 0, At, B0); PG8_MMA(1, 1, At, B1); PG8_BAR; PG8_SCHED;
;     ...
;         if constexpr (ALIGN_EPI) { if (wr == 0) PG8_BAR; }
	s_add_i32 s62, s33, s75
	v_lshl_add_u64 v[216:217], v[216:217], 0, s[26:27]
	s_mov_b32 m0, s62
	ds_read_b128 v[162:165], v215 offset:49152
	ds_read_b128 v[166:169], v215 offset:50176
	ds_read_b128 v[170:173], v215 offset:51200
	ds_read_b128 v[174:177], v215 offset:52224
	ds_read_b128 v[178:181], v215 offset:53248
	ds_read_b128 v[182:185], v215 offset:54272
	ds_read_b128 v[206:209], v215 offset:55296
	ds_read_b128 v[210:213], v215 offset:56320
	global_load_lds_dwordx4 v[216:217], off
	s_add_i32 m0, s62, 0x2000
	s_add_u32 s60, s60, 0x40080
	v_lshl_add_u64 v[216:217], v[218:219], 0, s[26:27]
	s_addc_u32 s61, s61, 0
	s_add_i32 s62, s74, s75
	global_load_lds_dwordx4 v[216:217], off
	v_lshl_add_u64 v[216:217], s[60:61], 0, v[0:1]
	s_mov_b32 m0, s62
	s_nop 0
	global_load_lds_dwordx4 v[216:217], off
	v_lshl_add_u64 v[216:217], s[60:61], 0, v[196:197]
	s_add_i32 m0, s62, 0x2000
	s_nop 0
	global_load_lds_dwordx4 v[216:217], off
	v_lshl_add_u64 v[216:217], v[220:221], 0, s[26:27]
	s_mov_b32 m0, s38
	s_nop 0
	global_load_lds_dwordx4 v[216:217], off
	v_lshl_add_u64 v[216:217], v[222:223], 0, s[26:27]
	s_mov_b32 m0, s39
	s_nop 0
	global_load_lds_dwordx4 v[216:217], off
	s_waitcnt vmcnt(8)
	s_waitcnt lgkmcnt(0)
	s_barrier
	s_setprio 1
	s_waitcnt lgkmcnt(0)
	v_mfma_f32_16x16x32_bf16 v[62:65], v[130:133], v[162:165], v[62:65]
	v_mfma_f32_16x16x32_bf16 v[58:61], v[138:141], v[162:165], v[58:61]
	v_mfma_f32_16x16x32_bf16 v[46:49], v[130:133], v[170:173], v[46:49]
	v_mfma_f32_16x16x32_bf16 v[42:45], v[138:141], v[170:173], v[42:45]
	v_mfma_f32_16x16x32_bf16 v[30:33], v[130:133], v[178:181], v[30:33]
	v_mfma_f32_16x16x32_bf16 v[26:29], v[138:141], v[178:181], v[26:29]
	v_mfma_f32_16x16x32_bf16 v[14:17], v[130:133], v[206:209], v[14:17]
	v_mfma_f32_16x16x32_bf16 v[10:13], v[138:141], v[206:209], v[10:13]
	v_mfma_f32_16x16x32_bf16 v[62:65], v[134:137], v[166:169], v[62:65]
	v_mfma_f32_16x16x32_bf16 v[58:61], v[142:145], v[166:169], v[58:61]
	v_mfma_f32_16x16x32_bf16 v[46:49], v[134:137], v[174:177], v[46:49]
	v_mfma_f32_16x16x32_bf16 v[42:45], v[142:145], v[174:177], v[42:45]
	v_mfma_f32_16x16x32_bf16 v[30:33], v[134:137], v[182:185], v[30:33]
	v_mfma_f32_16x16x32_bf16 v[26:29], v[142:145], v[182:185], v[26:29]
	v_mfma_f32_16x16x32_bf16 v[14:17], v[134:137], v[210:213], v[14:17]
	v_mfma_f32_16x16x32_bf16 v[10:13], v[142:145], v[210:213], v[10:13]
	s_setprio 0
	s_setprio 1
	v_mfma_f32_16x16x32_bf16 v[54:57], v[146:149], v[162:165], v[54:57]
	v_mfma_f32_16x16x32_bf16 v[50:53], v[154:157], v[162:165], v[50:53]
	v_mfma_f32_16x16x32_bf16 v[38:41], v[146:149], v[170:173], v[38:41]
	v_mfma_f32_16x16x32_bf16 v[34:37], v[154:157], v[170:173], v[34:37]
	v_mfma_f32_16x16x32_bf16 v[22:25], v[146:149], v[178:181], v[22:25]
	v_mfma_f32_16x16x32_bf16 v[18:21], v[154:157], v[178:181], v[18:21]
	v_mfma_f32_16x16x32_bf16 v[6:9], v[146:149], v[206:209], v[6:9]
	v_mfma_f32_16x16x32_bf16 v[2:5], v[154:157], v[206:209], v[2:5]
	v_mfma_f32_16x16x32_bf16 v[54:57], v[150:153], v[166:169], v[54:57]
	v_mfma_f32_16x16x32_bf16 v[50:53], v[158:161], v[166:169], v[50:53]
	v_mfma_f32_16x16x32_bf16 v[38:41], v[150:153], v[174:177], v[38:41]
	v_mfma_f32_16x16x32_bf16 v[34:37], v[158:161], v[174:177], v[34:37]
	v_mfma_f32_16x16x32_bf16 v[22:25], v[150:153], v[182:185], v[22:25]
	v_mfma_f32_16x16x32_bf16 v[18:21], v[158:161], v[182:185], v[18:21]
	v_mfma_f32_16x16x32_bf16 v[6:9], v[150:153], v[210:213], v[6:9]
	v_mfma_f32_16x16x32_bf16 v[2:5], v[158:161], v[210:213], v[2:5]
	s_setprio 0
	s_add_i32 vcc_hi, vcc_hi, 2
	s_add_u32 s58, s58, 0x100
	s_addc_u32 s59, s59, 0
	s_add_u32 s83, s83, 0x100
	s_addc_u32 vcc_lo, vcc_lo, 0
	s_cmp_gt_u32 vcc_hi, 13
	s_barrier
	s_cbranch_scc0 .LBB0_359
	s_and_b64 vcc, exec, s[44:45]
	s_cbranch_vccz .LBB0_362
	s_barrier

; #define PG8_STAGE(bufoff, gbase, voff) do { _Pragma("unroll") for (int _i = 0; _i < 2; ++_i) \
;         __builtin_amdgcn_global_load_lds((const unsigned*)((const char*)(gbase) + (voff)[_i]), (PG8_LAS unsigned*)(lds + (bufoff) + ldsw + _i * 8192), 16, 0, 0); } while (0)
; #define PG8_LDA(dst, b, h) do { _Pragma("unroll") for (int m = 0; m < 4; ++m) _Pragma("unroll") for (int k = 0; k < 2; ++k) dst[m][k] = *(const PG8_LAS bf16x8*)(lds + PG8_SA(b, h) + aoff + m * 2048 + k * 1024); } while (0)
; #define PG8_LDB(dst, b, h) do { _Pragma("unroll") for (int n = 0; n < 2; ++n) _Pragma("unroll") for (int k = 0; k < 2; ++k) dst[n][k] = *(const PG8_LAS bf16x8*)(lds + PG8_SB(b, h) + boff + n * 2048 + k * 1024); } while (0)
; #define PG8_WAIT_V(n) asm volatile("s_waitcnt vmcnt(" #n ")" ::: "memory")
; #define PG8_WAIT_L(n) asm volatile("s_waitcnt lgkmcnt(" #n ")" ::: "memory")
; #define PG8_BAR __builtin_amdgcn_s_barrier()
; #define PG8_SCHED __builtin_amdgcn_sched_barrier(0)
; template <class Epi, class Sched, bool ALIGN_EPI = false, bool SP2 = false>
; __device__ __forceinline__ void gemm_phase(PG8_LAS unsigned char* lds, const Gemm g, const Sched& S, const Epi& E, int tid_in) {
;     ...
;         const char* nA = has_next ? (const char*)g.A + (size_t)nxt.pm * tstep : cA; const char* nB = has_next ? (const char*)g.Bt + (size_t)nxt.pn * tstep : cB;
;         for (int t = 0; t < nt; t += 2) {
;             const bool last = (t == nt - 2);
;             const char* a1 = cA + (size_t)(t + 1) * kstep;
;             const char* a2 = last ? nA : cA + (size_t)(t + 2) * kstep; const char* b2 = last ? nB : cB + (size_t)(t + 2) * kstep;
;             const char* a3 = a2 + kstep; const char* b3 = b2 + kstep;
;             if (last && has_next) S.a_ready(nxt);
;             if constexpr (SP2) {
;             PG8_LDB(B0, 0, 0); PG8_LDB(B1, 0, 1); PG8_SCHED; PG8_LDA(At, 0, 0); PG8_STAGE(PG8_SA(1, 1), a1 + hstep, voffA);
;             PG8_WAIT_V(8); PG8_WAIT_L(0); PG8_BAR; PG8_MMA(0, 0, At, B0); PG8_MMA(0, 1, At, B1); PG8_BAR; PG8_SCHED;
;             PG8_LDA(At, 0, 1); PG8_STAGE(PG8_SB(0, 0), b2, voffB); PG8_STAGE(PG8_SB(0, 1), b2 + hstep, voffB); PG8_STAGE(PG8_SA(0, 0), a2, voffA);
;             PG8_WAIT_V(8); PG8_WAIT_L(0); PG8_BAR; PG8_MMA(1, 0, At, B0); PG8_MMA(1, 1, At, B1); PG8_BAR; PG8_SCHED;
.LBB0_491:
	s_ashr_i32 s43, s42, 31
	s_lshl_b64 s[48:49], s[42:43], 19
	s_add_u32 s48, s38, s48
	s_addc_u32 s49, s39, s49
	s_and_b64 s[50:51], s[46:47], exec
	s_cselect_b32 s43, s49, s53
	s_cselect_b32 s78, s48, s52
	s_ashr_i32 s45, s44, 31
	s_lshl_b64 s[50:51], s[44:45], 19
	s_add_u32 s50, s36, s50
	s_addc_u32 s51, s37, s51
	s_and_b64 s[56:57], s[46:47], exec
	s_cselect_b32 s45, s51, s55
	s_cselect_b32 s79, s50, s54
	s_add_u32 s52, s52, 0x40080
	s_addc_u32 s53, s53, 0
	s_add_u32 s80, s54, 0x100
	s_addc_u32 s81, s55, 0
	s_mov_b32 s82, -2
	v_add_u32_e32 v156, s84, v146
	v_add_u32_e32 v172, s85, v146
	ds_read_b128 v[140:143], v156
	ds_read_b128 v[148:151], v156 offset:1024
	ds_read_b128 v[152:155], v156 offset:2048
	ds_read_b128 v[156:159], v156 offset:3072
	ds_read_b128 v[160:163], v172
	ds_read_b128 v[164:167], v172 offset:1024
	ds_read_b128 v[168:171], v172 offset:2048
	ds_read_b128 v[172:175], v172 offset:3072
	s_add_u32 s54, s52, 0xfffc0080
	s_addc_u32 s55, s53, -1
	s_cmp_eq_u32 s82, 12
	s_cselect_b32 s57, s43, s55
	s_cselect_b32 s56, s78, s54
	s_cselect_b32 s55, s45, s81
	s_cselect_b32 s54, s79, s80
	v_lshl_add_u64 v[184:185], s[52:53], 0, v[136:137]
	s_add_i32 m0, s59, 0xc000
	ds_read_b128 v[176:179], v147
	ds_read_b128 v[180:183], v147 offset:1024
	ds_read_b128 v[196:199], v147 offset:2048
	ds_read_b128 v[200:203], v147 offset:3072
	ds_read_b128 v[204:207], v147 offset:4096
	ds_read_b128 v[208:211], v147 offset:5120
	ds_read_b128 v[212:215], v147 offset:6144
	ds_read_b128 v[216:219], v147 offset:7168
	global_load_lds_dwordx4 v[184:185], off
	v_lshl_add_u64 v[184:185], s[52:53], 0, v[138:139]
	s_add_i32 m0, s59, 0xe000
	s_nop 0
	global_load_lds_dwordx4 v[184:185], off
	s_waitcnt vmcnt(8)
	s_waitcnt lgkmcnt(0)
	s_barrier
	s_setprio 1
	s_waitcnt lgkmcnt(0)
	v_mfma_f32_16x16x32_bf16 v[126:129], v[140:143], v[176:179], 0
	v_mfma_f32_16x16x32_bf16 v[122:125], v[152:155], v[176:179], 0
	v_mfma_f32_16x16x32_bf16 v[110:113], v[140:143], v[196:199], 0
	v_mfma_f32_16x16x32_bf16 v[106:109], v[152:155], v[196:199], 0
	v_mfma_f32_16x16x32_bf16 v[94:97], v[140:143], v[204:207], 0
	v_mfma_f32_16x16x32_bf16 v[90:93], v[152:155], v[204:207], 0
	v_mfma_f32_16x16x32_bf16 v[78:81], v[140:143], v[212:215], 0
	v_mfma_f32_16x16x32_bf16 v[74:77], v[152:155], v[212:215], 0
	v_mfma_f32_16x16x32_bf16 v[126:129], v[148:151], v[180:183], v[126:129]
	v_mfma_f32_16x16x32_bf16 v[122:125], v[156:159], v[180:183], v[122:125]
	v_mfma_f32_16x16x32_bf16 v[110:113], v[148:151], v[200:203], v[110:113]
	v_mfma_f32_16x16x32_bf16 v[106:109], v[156:159], v[200:203], v[106:109]
	v_mfma_f32_16x16x32_bf16 v[94:97], v[148:151], v[208:211], v[94:97]
	v_mfma_f32_16x16x32_bf16 v[90:93], v[156:159], v[208:211], v[90:93]
	v_mfma_f32_16x16x32_bf16 v[78:81], v[148:151], v[216:219], v[78:81]
	v_mfma_f32_16x16x32_bf16 v[74:77], v[156:159], v[216:219], v[74:77]
	s_setprio 0
	s_setprio 1
	v_mfma_f32_16x16x32_bf16 v[118:121], v[160:163], v[176:179], 0
	v_mfma_f32_16x16x32_bf16 v[114:117], v[168:171], v[176:179], 0
	v_mfma_f32_16x16x32_bf16 v[102:105], v[160:163], v[196:199], 0
	v_mfma_f32_16x16x32_bf16 v[98:101], v[168:171], v[196:199], 0
	v_mfma_f32_16x16x32_bf16 v[86:89], v[160:163], v[204:207], 0
	v_mfma_f32_16x16x32_bf16 v[82:85], v[168:171], v[204:207], 0
	v_mfma_f32_16x16x32_bf16 v[70:73], v[160:163], v[212:215], 0
	v_mfma_f32_16x16x32_bf16 v[66:69], v[168:171], v[212:215], 0
	v_mfma_f32_16x16x32_bf16 v[118:121], v[164:167], v[180:183], v[118:121]
	v_mfma_f32_16x16x32_bf16 v[114:117], v[172:175], v[180:183], v[114:117]
	v_mfma_f32_16x16x32_bf16 v[102:105], v[164:167], v[200:203], v[102:105]
	v_mfma_f32_16x16x32_bf16 v[98:101], v[172:175], v[200:203], v[98:101]
	v_mfma_f32_16x16x32_bf16 v[86:89], v[164:167], v[208:211], v[86:89]
	v_mfma_f32_16x16x32_bf16 v[82:85], v[172:175], v[208:211], v[82:85]
	v_mfma_f32_16x16x32_bf16 v[70:73], v[164:167], v[216:219], v[70:73]
	v_mfma_f32_16x16x32_bf16 v[66:69], v[172:175], v[216:219], v[66:69]
	s_setprio 0
	s_barrier
	s_add_i32 s83, s84, s58
	v_lshl_add_u64 v[184:185], s[54:55], 0, v[0:1]
	s_mov_b32 m0, s83
	ds_read_b128 v[176:179], v147 offset:16384
	ds_read_b128 v[180:183], v147 offset:17408
	ds_read_b128 v[196:199], v147 offset:18432
	ds_read_b128 v[200:203], v147 offset:19456
	ds_read_b128 v[204:207], v147 offset:20480
	ds_read_b128 v[208:211], v147 offset:21504
	ds_read_b128 v[212:215], v147 offset:22528
	ds_read_b128 v[216:219], v147 offset:23552
	global_load_lds_dwordx4 v[184:185], off
	s_add_i32 m0, s83, 0x2000
	s_add_u32 s86, s54, 0x40000
	v_lshl_add_u64 v[220:221], s[54:55], 0, v[130:131]
	s_addc_u32 s87, s55, 0
	s_add_i32 s83, s85, s58
	global_load_lds_dwordx4 v[220:221], off
	v_lshl_add_u64 v[222:223], s[86:87], 0, v[0:1]
	s_mov_b32 m0, s83
	v_lshl_add_u64 v[224:225], s[56:57], 0, v[132:133]
	global_load_lds_dwordx4 v[222:223], off
	v_lshl_add_u64 v[222:223], s[86:87], 0, v[130:131]
	s_add_i32 m0, s83, 0x2000
	s_nop 0
	global_load_lds_dwordx4 v[222:223], off
	v_lshl_add_u64 v[222:223], s[56:57], 0, v[134:135]
	s_mov_b32 m0, s59
	s_nop 0
	global_load_lds_dwordx4 v[222:223], off
	s_mov_b32 m0, s60
	s_nop 0
	global_load_lds_dwordx4 v[224:225], off
	s_waitcnt vmcnt(8)
	s_waitcnt lgkmcnt(0)
	s_barrier
; #define PG8_STAGE(bufoff, gbase, voff) do { _Pragma("unroll") for (int _i = 0; _i < 2; ++_i) \
;         __builtin_amdgcn_global_load_lds((const unsigned*)((const char*)(gbase) + (voff)[_i]), (PG8_LAS unsigned*)(lds + (bufoff) + ldsw + _i * 8192), 16, 0, 0); } while (0)
; #define PG8_LDA(dst, b, h) do { _Pragma("unroll") for (int m = 0; m < 4; ++m) _Pragma("unroll") for (int k = 0; k < 2; ++k) dst[m][k] = *(const PG8_LAS bf16x8*)(lds + PG8_SA(b, h) + aoff + m * 2048 + k * 1024); } while (0)
; #define PG8_LDB(dst, b, h) do { _Pragma("unroll") for (int n = 0; n < 2; ++n) _Pragma("unroll") for (int k = 0; k < 2; ++k) dst[n][k] = *(const PG8_LAS bf16x8*)(lds + PG8_SB(b, h) + boff + n * 2048 + k * 1024); } while (0)
; #define PG8_MMA(ai, bj, At, Bt) do { __builtin_amdgcn_s_setprio(1); _Pragma("unroll") for (int k = 0; k < 2; ++k) _Pragma("unroll") for (int m = 0; m < 4; ++m) _Pragma("unroll") for (int n = 0; n < 2; ++n) \
;         acc[ai][bj][m][n] = __builtin_amdgcn_mfma_f32_16x16x32_bf16(Bt[n][k], At[m][k], acc[ai][bj][m][n], 0, 0, 0); __builtin_amdgcn_s_setprio(0); } while (0)
; #define PG8_WAIT_V(n) asm volatile("s_waitcnt vmcnt(" #n ")" ::: "memory")
; #define PG8_WAIT_L(n) asm volatile("s_waitcnt lgkmcnt(" #n ")" ::: "memory")
; #define PG8_BAR __builtin_amdgcn_s_barrier()
; #define PG8_SCHED __builtin_amdgcn_sched_barrier(0)
; template <class Epi, class Sched, bool ALIGN_EPI = false, bool SP2 = false>
; __device__ __forceinline__ void gemm_phase(PG8_LAS unsigned char* lds, const Gemm g, const Sched& S, const Epi& E, int tid_in) {
;     ...
;             PG8_WAIT_V(8); PG8_WAIT_L(0); PG8_BAR; PG8_MMA(1, 0, At, B0); PG8_MMA(1, 1, At, B1); PG8_BAR; PG8_SCHED;
;             PG8_LDB(B0, 1, 0); PG8_LDB(B1, 1, 1); PG8_SCHED; PG8_LDA(At, 1, 0); PG8_STAGE(PG8_SA(0, 1), a2 + hstep, voffA);
;             PG8_WAIT_V(8); PG8_WAIT_L(0); PG8_BAR; PG8_MMA(0, 0, At, B0); PG8_MMA(0, 1, At, B1); PG8_BAR; PG8_SCHED;
	s_setprio 1
	s_waitcnt lgkmcnt(0)
	v_mfma_f32_16x16x32_bf16 v[62:65], v[140:143], v[176:179], 0
	v_mfma_f32_16x16x32_bf16 v[58:61], v[152:155], v[176:179], 0
	v_mfma_f32_16x16x32_bf16 v[46:49], v[140:143], v[196:199], 0
	v_mfma_f32_16x16x32_bf16 v[42:45], v[152:155], v[196:199], 0
	v_mfma_f32_16x16x32_bf16 v[30:33], v[140:143], v[204:207], 0
	v_mfma_f32_16x16x32_bf16 v[26:29], v[152:155], v[204:207], 0
	v_mfma_f32_16x16x32_bf16 v[14:17], v[140:143], v[212:215], 0
	v_mfma_f32_16x16x32_bf16 v[10:13], v[152:155], v[212:215], 0
	v_mfma_f32_16x16x32_bf16 v[62:65], v[148:151], v[180:183], v[62:65]
	v_mfma_f32_16x16x32_bf16 v[58:61], v[156:159], v[180:183], v[58:61]
	v_mfma_f32_16x16x32_bf16 v[46:49], v[148:151], v[200:203], v[46:49]
	v_mfma_f32_16x16x32_bf16 v[42:45], v[156:159], v[200:203], v[42:45]
	v_mfma_f32_16x16x32_bf16 v[30:33], v[148:151], v[208:211], v[30:33]
	v_mfma_f32_16x16x32_bf16 v[26:29], v[156:159], v[208:211], v[26:29]
	v_mfma_f32_16x16x32_bf16 v[14:17], v[148:151], v[216:219], v[14:17]
	v_mfma_f32_16x16x32_bf16 v[10:13], v[156:159], v[216:219], v[10:13]
	s_setprio 0
	s_setprio 1
	v_mfma_f32_16x16x32_bf16 v[54:57], v[160:163], v[176:179], 0
	v_mfma_f32_16x16x32_bf16 v[50:53], v[168:171], v[176:179], 0
	v_mfma_f32_16x16x32_bf16 v[38:41], v[160:163], v[196:199], 0
	v_mfma_f32_16x16x32_bf16 v[34:37], v[168:171], v[196:199], 0
	v_mfma_f32_16x16x32_bf16 v[22:25], v[160:163], v[204:207], 0
	v_mfma_f32_16x16x32_bf16 v[18:21], v[168:171], v[204:207], 0
	v_mfma_f32_16x16x32_bf16 v[6:9], v[160:163], v[212:215], 0
	v_mfma_f32_16x16x32_bf16 v[2:5], v[168:171], v[212:215], 0
	v_mfma_f32_16x16x32_bf16 v[54:57], v[164:167], v[180:183], v[54:57]
	v_mfma_f32_16x16x32_bf16 v[50:53], v[172:175], v[180:183], v[50:53]
	v_mfma_f32_16x16x32_bf16 v[38:41], v[164:167], v[200:203], v[38:41]
	v_mfma_f32_16x16x32_bf16 v[34:37], v[172:175], v[200:203], v[34:37]
	v_mfma_f32_16x16x32_bf16 v[22:25], v[164:167], v[208:211], v[22:25]
	v_mfma_f32_16x16x32_bf16 v[18:21], v[172:175], v[208:211], v[18:21]
	v_mfma_f32_16x16x32_bf16 v[6:9], v[164:167], v[216:219], v[6:9]
	v_mfma_f32_16x16x32_bf16 v[2:5], v[172:175], v[216:219], v[2:5]
	s_setprio 0
	s_barrier
	v_add_u32_e32 v156, s33, v146
	v_add_u32_e32 v172, s74, v146
	ds_read_b128 v[140:143], v156
	ds_read_b128 v[148:151], v156 offset:1024
	ds_read_b128 v[152:155], v156 offset:2048
	ds_read_b128 v[156:159], v156 offset:3072
	ds_read_b128 v[160:163], v172
	ds_read_b128 v[164:167], v172 offset:1024
	ds_read_b128 v[168:171], v172 offset:2048
	ds_read_b128 v[172:175], v172 offset:3072
	s_add_u32 s56, s56, 0x40000
	s_addc_u32 s57, s57, 0
	s_mov_b32 m0, s61
	v_lshl_add_u64 v[226:227], s[56:57], 0, v[134:135]
	ds_read_b128 v[176:179], v147 offset:32768
	ds_read_b128 v[180:183], v147 offset:33792
	ds_read_b128 v[196:199], v147 offset:34816
	ds_read_b128 v[200:203], v147 offset:35840
	ds_read_b128 v[204:207], v147 offset:36864
	ds_read_b128 v[208:211], v147 offset:37888
	ds_read_b128 v[212:215], v147 offset:38912
	ds_read_b128 v[216:219], v147 offset:39936
	global_load_lds_dwordx4 v[226:227], off
	v_lshl_add_u64 v[226:227], s[56:57], 0, v[132:133]
	s_mov_b32 m0, s62
	s_nop 0
	global_load_lds_dwordx4 v[226:227], off
	s_waitcnt vmcnt(8)
	s_waitcnt lgkmcnt(0)
	s_barrier
	s_setprio 1
	s_waitcnt lgkmcnt(0)
	v_mfma_f32_16x16x32_bf16 v[126:129], v[140:143], v[176:179], v[126:129]
	v_mfma_f32_16x16x32_bf16 v[122:125], v[152:155], v[176:179], v[122:125]
	v_mfma_f32_16x16x32_bf16 v[110:113], v[140:143], v[196:199], v[110:113]
	v_mfma_f32_16x16x32_bf16 v[106:109], v[152:155], v[196:199], v[106:109]
	v_mfma_f32_16x16x32_bf16 v[94:97], v[140:143], v[204:207], v[94:97]
	v_mfma_f32_16x16x32_bf16 v[90:93], v[152:155], v[204:207], v[90:93]
	v_mfma_f32_16x16x32_bf16 v[78:81], v[140:143], v[212:215], v[78:81]
	v_mfma_f32_16x16x32_bf16 v[74:77], v[152:155], v[212:215], v[74:77]
	v_mfma_f32_16x16x32_bf16 v[126:129], v[148:151], v[180:183], v[126:129]
	v_mfma_f32_16x16x32_bf16 v[122:125], v[156:159], v[180:183], v[122:125]
	v_mfma_f32_16x16x32_bf16 v[110:113], v[148:151], v[200:203], v[110:113]
	v_mfma_f32_16x16x32_bf16 v[106:109], v[156:159], v[200:203], v[106:109]
	v_mfma_f32_16x16x32_bf16 v[94:97], v[148:151], v[208:211], v[94:97]
	v_mfma_f32_16x16x32_bf16 v[90:93], v[156:159], v[208:211], v[90:93]
	v_mfma_f32_16x16x32_bf16 v[78:81], v[148:151], v[216:219], v[78:81]
	v_mfma_f32_16x16x32_bf16 v[74:77], v[156:159], v[216:219], v[74:77]
	s_setprio 0
	s_setprio 1
	v_mfma_f32_16x16x32_bf16 v[118:121], v[160:163], v[176:179], v[118:121]
	v_mfma_f32_16x16x32_bf16 v[114:117], v[168:171], v[176:179], v[114:117]
	v_mfma_f32_16x16x32_bf16 v[102:105], v[160:163], v[196:199], v[102:105]
	v_mfma_f32_16x16x32_bf16 v[98:101], v[168:171], v[196:199], v[98:101]
	v_mfma_f32_16x16x32_bf16 v[86:89], v[160:163], v[204:207], v[86:89]
	v_mfma_f32_16x16x32_bf16 v[82:85], v[168:171], v[204:207], v[82:85]
	v_mfma_f32_16x16x32_bf16 v[70:73], v[160:163], v[212:215], v[70:73]
	v_mfma_f32_16x16x32_bf16 v[66:69], v[168:171], v[212:215], v[66:69]
	v_mfma_f32_16x16x32_bf16 v[118:121], v[164:167], v[180:183], v[118:121]
	v_mfma_f32_16x16x32_bf16 v[114:117], v[172:175], v[180:183], v[114:117]
	v_mfma_f32_16x16x32_bf16 v[102:105], v[164:167], v[200:203], v[102:105]
	v_mfma_f32_16x16x32_bf16 v[98:101], v[172:175], v[200:203], v[98:101]
	v_mfma_f32_16x16x32_bf16 v[86:89], v[164:167], v[208:211], v[86:89]
	v_mfma_f32_16x16x32_bf16 v[82:85], v[172:175], v[208:211], v[82:85]
	v_mfma_f32_16x16x32_bf16 v[70:73], v[164:167], v[216:219], v[70:73]
	v_mfma_f32_16x16x32_bf16 v[66:69], v[172:175], v[216:219], v[66:69]
	s_setprio 0
	s_barrier
; #define PG8_STAGE(bufoff, gbase, voff) do { _Pragma("unroll") for (int _i = 0; _i < 2; ++_i) \
;         __builtin_amdgcn_global_load_lds((const unsigned*)((const char*)(gbase) + (voff)[_i]), (PG8_LAS unsigned*)(lds + (bufoff) + ldsw + _i * 8192), 16, 0, 0); } while (0)
; #define PG8_LDA(dst, b, h) do { _Pragma("unroll") for (int m = 0; m < 4; ++m) _Pragma("unroll") for (int k = 0; k < 2; ++k) dst[m][k] = *(const PG8_LAS bf16x8*)(lds + PG8_SA(b, h) + aoff + m * 2048 + k * 1024); } while (0)
; #define PG8_LDB(dst, b, h) do { _Pragma("unroll") for (int n = 0; n < 2; ++n) _Pragma("unroll") for (int k = 0; k < 2; ++k) dst[n][k] = *(const PG8_LAS bf16x8*)(lds + PG8_SB(b, h) + boff + n * 2048 + k * 1024); } while (0)
; #define PG8_MMA(ai, bj, At, Bt) do { __builtin_amdgcn_s_setprio(1); _Pragma("unroll") for (int k = 0; k < 2; ++k) _Pragma("unroll") for (int m = 0; m < 4; ++m) _Pragma("unroll") for (int n = 0; n < 2; ++n) \
;         acc[ai][bj][m][n] = __builtin_amdgcn_mfma_f32_16x16x32_bf16(Bt[n][k], At[m][k], acc[ai][bj][m][n], 0, 0, 0); __builtin_amdgcn_s_setprio(0); } while (0)
; #define PG8_WAIT_V(n) asm volatile("s_waitcnt vmcnt(" #n ")" ::: "memory")
; #define PG8_WAIT_L(n) asm volatile("s_waitcnt lgkmcnt(" #n ")" ::: "memory")
; #define PG8_BAR __builtin_amdgcn_s_barrier()
; #define PG8_SCHED __builtin_amdgcn_sched_barrier(0)
; template <class Epi, class Sched, bool ALIGN_EPI = false, bool SP2 = false>
; __device__ __forceinline__ void gemm_phase(PG8_LAS unsigned char* lds, const Gemm g, const Sched& S, const Epi& E, int tid_in) {
;     ...
;             PG8_LDB(B0, 0, 0); PG8_LDB(B1, 0, 1); PG8_SCHED; PG8_LDA(At, 0, 0); PG8_STAGE(PG8_SA(1, 1), a1 + hstep, voffA);
;             PG8_WAIT_V(8); PG8_WAIT_L(0); PG8_BAR; PG8_MMA(0, 0, At, B0); PG8_MMA(0, 1, At, B1); PG8_BAR; PG8_SCHED;
;     ...
;             PG8_LDA(At, 1, 1); PG8_STAGE(PG8_SB(1, 0), b3, voffB); PG8_STAGE(PG8_SB(1, 1), b3 + hstep, voffB); PG8_STAGE(PG8_SA(1, 0), a3, voffA);
;             PG8_WAIT_V(8); PG8_WAIT_L(0); PG8_BAR; PG8_MMA(1, 0, At, B0); PG8_MMA(1, 1, At, B1); PG8_BAR; PG8_SCHED;
	s_add_i32 s56, s33, s58
	v_lshl_add_u64 v[184:185], v[184:185], 0, s[26:27]
	s_mov_b32 m0, s56
	ds_read_b128 v[176:179], v147 offset:49152
	ds_read_b128 v[180:183], v147 offset:50176
	ds_read_b128 v[196:199], v147 offset:51200
	ds_read_b128 v[200:203], v147 offset:52224
	ds_read_b128 v[204:207], v147 offset:53248
	ds_read_b128 v[208:211], v147 offset:54272
	ds_read_b128 v[212:215], v147 offset:55296
	ds_read_b128 v[216:219], v147 offset:56320
	global_load_lds_dwordx4 v[184:185], off
	s_add_i32 m0, s56, 0x2000
	s_add_u32 s54, s54, 0x40080
	v_lshl_add_u64 v[184:185], v[220:221], 0, s[26:27]
	s_addc_u32 s55, s55, 0
	s_add_i32 s56, s74, s58
	global_load_lds_dwordx4 v[184:185], off
	v_lshl_add_u64 v[184:185], s[54:55], 0, v[0:1]
	s_mov_b32 m0, s56
	s_nop 0
	global_load_lds_dwordx4 v[184:185], off
	v_lshl_add_u64 v[184:185], s[54:55], 0, v[130:131]
	s_add_i32 m0, s56, 0x2000
	s_nop 0
	global_load_lds_dwordx4 v[184:185], off
	v_lshl_add_u64 v[184:185], v[222:223], 0, s[26:27]
	s_mov_b32 m0, s65
	s_nop 0
	global_load_lds_dwordx4 v[184:185], off
	v_lshl_add_u64 v[184:185], v[224:225], 0, s[26:27]
	s_mov_b32 m0, s68
	s_nop 0
	global_load_lds_dwordx4 v[184:185], off
	s_waitcnt vmcnt(8)
	s_waitcnt lgkmcnt(0)
	s_barrier
	s_setprio 1
	s_waitcnt lgkmcnt(0)
	v_mfma_f32_16x16x32_bf16 v[62:65], v[140:143], v[176:179], v[62:65]
	v_mfma_f32_16x16x32_bf16 v[58:61], v[152:155], v[176:179], v[58:61]
	v_mfma_f32_16x16x32_bf16 v[46:49], v[140:143], v[196:199], v[46:49]
	v_mfma_f32_16x16x32_bf16 v[42:45], v[152:155], v[196:199], v[42:45]
	v_mfma_f32_16x16x32_bf16 v[30:33], v[140:143], v[204:207], v[30:33]
	v_mfma_f32_16x16x32_bf16 v[26:29], v[152:155], v[204:207], v[26:29]
	v_mfma_f32_16x16x32_bf16 v[14:17], v[140:143], v[212:215], v[14:17]
	v_mfma_f32_16x16x32_bf16 v[10:13], v[152:155], v[212:215], v[10:13]
	v_mfma_f32_16x16x32_bf16 v[62:65], v[148:151], v[180:183], v[62:65]
	v_mfma_f32_16x16x32_bf16 v[58:61], v[156:159], v[180:183], v[58:61]
	v_mfma_f32_16x16x32_bf16 v[46:49], v[148:151], v[200:203], v[46:49]
	v_mfma_f32_16x16x32_bf16 v[42:45], v[156:159], v[200:203], v[42:45]
	v_mfma_f32_16x16x32_bf16 v[30:33], v[148:151], v[208:211], v[30:33]
	v_mfma_f32_16x16x32_bf16 v[26:29], v[156:159], v[208:211], v[26:29]
	v_mfma_f32_16x16x32_bf16 v[14:17], v[148:151], v[216:219], v[14:17]
	v_mfma_f32_16x16x32_bf16 v[10:13], v[156:159], v[216:219], v[10:13]
	s_setprio 0
	s_setprio 1
	v_mfma_f32_16x16x32_bf16 v[54:57], v[160:163], v[176:179], v[54:57]
	v_mfma_f32_16x16x32_bf16 v[50:53], v[168:171], v[176:179], v[50:53]
	v_mfma_f32_16x16x32_bf16 v[38:41], v[160:163], v[196:199], v[38:41]
	v_mfma_f32_16x16x32_bf16 v[34:37], v[168:171], v[196:199], v[34:37]
	v_mfma_f32_16x16x32_bf16 v[22:25], v[160:163], v[204:207], v[22:25]
	v_mfma_f32_16x16x32_bf16 v[18:21], v[168:171], v[204:207], v[18:21]
	v_mfma_f32_16x16x32_bf16 v[6:9], v[160:163], v[212:215], v[6:9]
	v_mfma_f32_16x16x32_bf16 v[2:5], v[168:171], v[212:215], v[2:5]
	v_mfma_f32_16x16x32_bf16 v[54:57], v[164:167], v[180:183], v[54:57]
	v_mfma_f32_16x16x32_bf16 v[50:53], v[172:175], v[180:183], v[50:53]
	v_mfma_f32_16x16x32_bf16 v[38:41], v[164:167], v[200:203], v[38:41]
	v_mfma_f32_16x16x32_bf16 v[34:37], v[172:175], v[200:203], v[34:37]
	v_mfma_f32_16x16x32_bf16 v[22:25], v[164:167], v[208:211], v[22:25]
	v_mfma_f32_16x16x32_bf16 v[18:21], v[172:175], v[208:211], v[18:21]
	v_mfma_f32_16x16x32_bf16 v[6:9], v[164:167], v[216:219], v[6:9]
	v_mfma_f32_16x16x32_bf16 v[2:5], v[172:175], v[216:219], v[2:5]
	s_setprio 0
	s_add_i32 s82, s82, 2
	s_add_u32 s52, s52, 0x100
	s_addc_u32 s53, s53, 0
	s_add_u32 s80, s80, 0x100
	s_addc_u32 s81, s81, 0
	s_cmp_gt_u32 s82, 13
	s_barrier
.LBB0_492:
	v_add_u32_e32 v156, s84, v146
	v_add_u32_e32 v172, s85, v146
	ds_read_b128 v[140:143], v156
	ds_read_b128 v[148:151], v156 offset:1024
	ds_read_b128 v[152:155], v156 offset:2048
	ds_read_b128 v[156:159], v156 offset:3072
	ds_read_b128 v[160:163], v172
	ds_read_b128 v[164:167], v172 offset:1024
	ds_read_b128 v[168:171], v172 offset:2048
	ds_read_b128 v[172:175], v172 offset:3072
	s_add_u32 s54, s52, 0xfffc0080
	s_addc_u32 s55, s53, -1
	s_cmp_eq_u32 s82, 12
	s_cselect_b32 s57, s43, s55
	s_cselect_b32 s56, s78, s54
	s_cselect_b32 s55, s45, s81
	s_cselect_b32 s54, s79, s80
	v_lshl_add_u64 v[184:185], s[52:53], 0, v[136:137]
	s_add_i32 m0, s59, 0xc000
	ds_read_b128 v[176:179], v147
	ds_read_b128 v[180:183], v147 offset:1024
	ds_read_b128 v[196:199], v147 offset:2048
	ds_read_b128 v[200:203], v147 offset:3072
	ds_read_b128 v[204:207], v147 offset:4096
	ds_read_b128 v[208:211], v147 offset:5120
	ds_read_b128 v[212:215], v147 offset:6144
	ds_read_b128 v[216:219], v147 offset:7168
	global_load_lds_dwordx4 v[184:185], off
	v_lshl_add_u64 v[184:185], s[52:53], 0, v[138:139]
	s_add_i32 m0, s59, 0xe000
	s_nop 0
	global_load_lds_dwordx4 v[184:185], off
	s_waitcnt vmcnt(8)
	s_waitcnt lgkmcnt(0)
	s_barrier
; #define PG8_STAGE(bufoff, gbase, voff) do { _Pragma("unroll") for (int _i = 0; _i < 2; ++_i) \
;         __builtin_amdgcn_global_load_lds((const unsigned*)((const char*)(gbase) + (voff)[_i]), (PG8_LAS unsigned*)(lds + (bufoff) + ldsw + _i * 8192), 16, 0, 0); } while (0)
; #define PG8_LDA(dst, b, h) do { _Pragma("unroll") for (int m = 0; m < 4; ++m) _Pragma("unroll") for (int k = 0; k < 2; ++k) dst[m][k] = *(const PG8_LAS bf16x8*)(lds + PG8_SA(b, h) + aoff + m * 2048 + k * 1024); } while (0)
; #define PG8_MMA(ai, bj, At, Bt) do { __builtin_amdgcn_s_setprio(1); _Pragma("unroll") for (int k = 0; k < 2; ++k) _Pragma("unroll") for (int m = 0; m < 4; ++m) _Pragma("unroll") for (int n = 0; n < 2; ++n) \
;         acc[ai][bj][m][n] = __builtin_amdgcn_mfma_f32_16x16x32_bf16(Bt[n][k], At[m][k], acc[ai][bj][m][n], 0, 0, 0); __builtin_amdgcn_s_setprio(0); } while (0)
; #define PG8_WAIT_V(n) asm volatile("s_waitcnt vmcnt(" #n ")" ::: "memory")
; #define PG8_WAIT_L(n) asm volatile("s_waitcnt lgkmcnt(" #n ")" ::: "memory")
; #define PG8_BAR __builtin_amdgcn_s_barrier()
; #define PG8_SCHED __builtin_amdgcn_sched_barrier(0)
; template <class Epi, class Sched, bool ALIGN_EPI = false, bool SP2 = false>
; __device__ __forceinline__ void gemm_phase(PG8_LAS unsigned char* lds, const Gemm g, const Sched& S, const Epi& E, int tid_in) {
;     ...
;             PG8_WAIT_V(8); PG8_WAIT_L(0); PG8_BAR; PG8_MMA(0, 0, At, B0); PG8_MMA(0, 1, At, B1); PG8_BAR; PG8_SCHED;
;             PG8_LDA(At, 0, 1); PG8_STAGE(PG8_SB(0, 0), b2, voffB); PG8_STAGE(PG8_SB(0, 1), b2 + hstep, voffB); PG8_STAGE(PG8_SA(0, 0), a2, voffA);
;             PG8_WAIT_V(8); PG8_WAIT_L(0); PG8_BAR; PG8_MMA(1, 0, At, B0); PG8_MMA(1, 1, At, B1); PG8_BAR; PG8_SCHED;
	s_setprio 1
	s_waitcnt lgkmcnt(0)
	v_mfma_f32_16x16x32_bf16 v[126:129], v[140:143], v[176:179], v[126:129]
	v_mfma_f32_16x16x32_bf16 v[122:125], v[152:155], v[176:179], v[122:125]
	v_mfma_f32_16x16x32_bf16 v[110:113], v[140:143], v[196:199], v[110:113]
	v_mfma_f32_16x16x32_bf16 v[106:109], v[152:155], v[196:199], v[106:109]
	v_mfma_f32_16x16x32_bf16 v[94:97], v[140:143], v[204:207], v[94:97]
	v_mfma_f32_16x16x32_bf16 v[90:93], v[152:155], v[204:207], v[90:93]
	v_mfma_f32_16x16x32_bf16 v[78:81], v[140:143], v[212:215], v[78:81]
	v_mfma_f32_16x16x32_bf16 v[74:77], v[152:155], v[212:215], v[74:77]
	v_mfma_f32_16x16x32_bf16 v[126:129], v[148:151], v[180:183], v[126:129]
	v_mfma_f32_16x16x32_bf16 v[122:125], v[156:159], v[180:183], v[122:125]
	v_mfma_f32_16x16x32_bf16 v[110:113], v[148:151], v[200:203], v[110:113]
	v_mfma_f32_16x16x32_bf16 v[106:109], v[156:159], v[200:203], v[106:109]
	v_mfma_f32_16x16x32_bf16 v[94:97], v[148:151], v[208:211], v[94:97]
	v_mfma_f32_16x16x32_bf16 v[90:93], v[156:159], v[208:211], v[90:93]
	v_mfma_f32_16x16x32_bf16 v[78:81], v[148:151], v[216:219], v[78:81]
	v_mfma_f32_16x16x32_bf16 v[74:77], v[156:159], v[216:219], v[74:77]
	s_setprio 0
	s_setprio 1
	v_mfma_f32_16x16x32_bf16 v[118:121], v[160:163], v[176:179], v[118:121]
	v_mfma_f32_16x16x32_bf16 v[114:117], v[168:171], v[176:179], v[114:117]
	v_mfma_f32_16x16x32_bf16 v[102:105], v[160:163], v[196:199], v[102:105]
	v_mfma_f32_16x16x32_bf16 v[98:101], v[168:171], v[196:199], v[98:101]
	v_mfma_f32_16x16x32_bf16 v[86:89], v[160:163], v[204:207], v[86:89]
	v_mfma_f32_16x16x32_bf16 v[82:85], v[168:171], v[204:207], v[82:85]
	v_mfma_f32_16x16x32_bf16 v[70:73], v[160:163], v[212:215], v[70:73]
	v_mfma_f32_16x16x32_bf16 v[66:69], v[168:171], v[212:215], v[66:69]
	v_mfma_f32_16x16x32_bf16 v[118:121], v[164:167], v[180:183], v[118:121]
	v_mfma_f32_16x16x32_bf16 v[114:117], v[172:175], v[180:183], v[114:117]
	v_mfma_f32_16x16x32_bf16 v[102:105], v[164:167], v[200:203], v[102:105]
	v_mfma_f32_16x16x32_bf16 v[98:101], v[172:175], v[200:203], v[98:101]
	v_mfma_f32_16x16x32_bf16 v[86:89], v[164:167], v[208:211], v[86:89]
	v_mfma_f32_16x16x32_bf16 v[82:85], v[172:175], v[208:211], v[82:85]
	v_mfma_f32_16x16x32_bf16 v[70:73], v[164:167], v[216:219], v[70:73]
	v_mfma_f32_16x16x32_bf16 v[66:69], v[172:175], v[216:219], v[66:69]
	s_setprio 0
	s_barrier
	s_add_i32 s83, s84, s58
	v_lshl_add_u64 v[184:185], s[54:55], 0, v[0:1]
	s_mov_b32 m0, s83
	ds_read_b128 v[176:179], v147 offset:16384
	ds_read_b128 v[180:183], v147 offset:17408
	ds_read_b128 v[196:199], v147 offset:18432
	ds_read_b128 v[200:203], v147 offset:19456
	ds_read_b128 v[204:207], v147 offset:20480
	ds_read_b128 v[208:211], v147 offset:21504
	ds_read_b128 v[212:215], v147 offset:22528
	ds_read_b128 v[216:219], v147 offset:23552
	global_load_lds_dwordx4 v[184:185], off
	s_add_i32 m0, s83, 0x2000
	s_add_u32 s86, s54, 0x40000
	v_lshl_add_u64 v[220:221], s[54:55], 0, v[130:131]
	s_addc_u32 s87, s55, 0
	s_add_i32 s83, s85, s58
	global_load_lds_dwordx4 v[220:221], off
	v_lshl_add_u64 v[222:223], s[86:87], 0, v[0:1]
	s_mov_b32 m0, s83
	v_lshl_add_u64 v[224:225], s[56:57], 0, v[132:133]
	global_load_lds_dwordx4 v[222:223], off
	v_lshl_add_u64 v[222:223], s[86:87], 0, v[130:131]
	s_add_i32 m0, s83, 0x2000
	s_nop 0
	global_load_lds_dwordx4 v[222:223], off
	v_lshl_add_u64 v[222:223], s[56:57], 0, v[134:135]
	s_mov_b32 m0, s59
	s_nop 0
	global_load_lds_dwordx4 v[222:223], off
	s_mov_b32 m0, s60
	s_nop 0
	global_load_lds_dwordx4 v[224:225], off
	s_waitcnt vmcnt(8)
	s_waitcnt lgkmcnt(0)
	s_barrier
	s_setprio 1
	s_waitcnt lgkmcnt(0)
	v_mfma_f32_16x16x32_bf16 v[62:65], v[140:143], v[176:179], v[62:65]
	v_mfma_f32_16x16x32_bf16 v[58:61], v[152:155], v[176:179], v[58:61]
	v_mfma_f32_16x16x32_bf16 v[46:49], v[140:143], v[196:199], v[46:49]
	v_mfma_f32_16x16x32_bf16 v[42:45], v[152:155], v[196:199], v[42:45]
	v_mfma_f32_16x16x32_bf16 v[30:33], v[140:143], v[204:207], v[30:33]
	v_mfma_f32_16x16x32_bf16 v[26:29], v[152:155], v[204:207], v[26:29]
	v_mfma_f32_16x16x32_bf16 v[14:17], v[140:143], v[212:215], v[14:17]
	v_mfma_f32_16x16x32_bf16 v[10:13], v[152:155], v[212:215], v[10:13]
	v_mfma_f32_16x16x32_bf16 v[62:65], v[148:151], v[180:183], v[62:65]
	v_mfma_f32_16x16x32_bf16 v[58:61], v[156:159], v[180:183], v[58:61]
	v_mfma_f32_16x16x32_bf16 v[46:49], v[148:151], v[200:203], v[46:49]
	v_mfma_f32_16x16x32_bf16 v[42:45], v[156:159], v[200:203], v[42:45]
	v_mfma_f32_16x16x32_bf16 v[30:33], v[148:151], v[208:211], v[30:33]
	v_mfma_f32_16x16x32_bf16 v[26:29], v[156:159], v[208:211], v[26:29]
	v_mfma_f32_16x16x32_bf16 v[14:17], v[148:151], v[216:219], v[14:17]
	v_mfma_f32_16x16x32_bf16 v[10:13], v[156:159], v[216:219], v[10:13]
	s_setprio 0
	s_setprio 1
	v_mfma_f32_16x16x32_bf16 v[54:57], v[160:163], v[176:179], v[54:57]
	v_mfma_f32_16x16x32_bf16 v[50:53], v[168:171], v[176:179], v[50:53]
	v_mfma_f32_16x16x32_bf16 v[38:41], v[160:163], v[196:199], v[38:41]
	v_mfma_f32_16x16x32_bf16 v[34:37], v[168:171], v[196:199], v[34:37]
	v_mfma_f32_16x16x32_bf16 v[22:25], v[160:163], v[204:207], v[22:25]
	v_mfma_f32_16x16x32_bf16 v[18:21], v[168:171], v[204:207], v[18:21]
	v_mfma_f32_16x16x32_bf16 v[6:9], v[160:163], v[212:215], v[6:9]
	v_mfma_f32_16x16x32_bf16 v[2:5], v[168:171], v[212:215], v[2:5]
	v_mfma_f32_16x16x32_bf16 v[54:57], v[164:167], v[180:183], v[54:57]
	v_mfma_f32_16x16x32_bf16 v[50:53], v[172:175], v[180:183], v[50:53]
	v_mfma_f32_16x16x32_bf16 v[38:41], v[164:167], v[200:203], v[38:41]
	v_mfma_f32_16x16x32_bf16 v[34:37], v[172:175], v[200:203], v[34:37]
	v_mfma_f32_16x16x32_bf16 v[22:25], v[164:167], v[208:211], v[22:25]
	v_mfma_f32_16x16x32_bf16 v[18:21], v[172:175], v[208:211], v[18:21]
	v_mfma_f32_16x16x32_bf16 v[6:9], v[164:167], v[216:219], v[6:9]
	v_mfma_f32_16x16x32_bf16 v[2:5], v[172:175], v[216:219], v[2:5]
	s_setprio 0
	s_barrier
; #define PG8_STAGE(bufoff, gbase, voff) do { _Pragma("unroll") for (int _i = 0; _i < 2; ++_i) \
;         __builtin_amdgcn_global_load_lds((const unsigned*)((const char*)(gbase) + (voff)[_i]), (PG8_LAS unsigned*)(lds + (bufoff) + ldsw + _i * 8192), 16, 0, 0); } while (0)
; #define PG8_LDA(dst, b, h) do { _Pragma("unroll") for (int m = 0; m < 4; ++m) _Pragma("unroll") for (int k = 0; k < 2; ++k) dst[m][k] = *(const PG8_LAS bf16x8*)(lds + PG8_SA(b, h) + aoff + m * 2048 + k * 1024); } while (0)
; #define PG8_LDB(dst, b, h) do { _Pragma("unroll") for (int n = 0; n < 2; ++n) _Pragma("unroll") for (int k = 0; k < 2; ++k) dst[n][k] = *(const PG8_LAS bf16x8*)(lds + PG8_SB(b, h) + boff + n * 2048 + k * 1024); } while (0)
; #define PG8_MMA(ai, bj, At, Bt) do { __builtin_amdgcn_s_setprio(1); _Pragma("unroll") for (int k = 0; k < 2; ++k) _Pragma("unroll") for (int m = 0; m < 4; ++m) _Pragma("unroll") for (int n = 0; n < 2; ++n) \
;         acc[ai][bj][m][n] = __builtin_amdgcn_mfma_f32_16x16x32_bf16(Bt[n][k], At[m][k], acc[ai][bj][m][n], 0, 0, 0); __builtin_amdgcn_s_setprio(0); } while (0)
; #define PG8_WAIT_V(n) asm volatile("s_waitcnt vmcnt(" #n ")" ::: "memory")
; #define PG8_WAIT_L(n) asm volatile("s_waitcnt lgkmcnt(" #n ")" ::: "memory")
; #define PG8_BAR __builtin_amdgcn_s_barrier()
; #define PG8_SCHED __builtin_amdgcn_sched_barrier(0)
; template <class Epi, class Sched, bool ALIGN_EPI = false, bool SP2 = false>
; __device__ __forceinline__ void gemm_phase(PG8_LAS unsigned char* lds, const Gemm g, const Sched& S, const Epi& E, int tid_in) {
;     ...
;             PG8_LDB(B0, 1, 0); PG8_LDB(B1, 1, 1); PG8_SCHED; PG8_LDA(At, 1, 0); PG8_STAGE(PG8_SA(0, 1), a2 + hstep, voffA);
;             PG8_WAIT_V(8); PG8_WAIT_L(0); PG8_BAR; PG8_MMA(0, 0, At, B0); PG8_MMA(0, 1, At, B1); PG8_BAR; PG8_SCHED;
	v_add_u32_e32 v156, s33, v146
	v_add_u32_e32 v172, s74, v146
	ds_read_b128 v[140:143], v156
	ds_read_b128 v[148:151], v156 offset:1024
	ds_read_b128 v[152:155], v156 offset:2048
	ds_read_b128 v[156:159], v156 offset:3072
	ds_read_b128 v[160:163], v172
	ds_read_b128 v[164:167], v172 offset:1024
	ds_read_b128 v[168:171], v172 offset:2048
	ds_read_b128 v[172:175], v172 offset:3072
	s_add_u32 s56, s56, 0x40000
	s_addc_u32 s57, s57, 0
	s_mov_b32 m0, s61
	v_lshl_add_u64 v[226:227], s[56:57], 0, v[134:135]
	ds_read_b128 v[176:179], v147 offset:32768
	ds_read_b128 v[180:183], v147 offset:33792
	ds_read_b128 v[196:199], v147 offset:34816
	ds_read_b128 v[200:203], v147 offset:35840
	ds_read_b128 v[204:207], v147 offset:36864
	ds_read_b128 v[208:211], v147 offset:37888
	ds_read_b128 v[212:215], v147 offset:38912
	ds_read_b128 v[216:219], v147 offset:39936
	global_load_lds_dwordx4 v[226:227], off
	v_lshl_add_u64 v[226:227], s[56:57], 0, v[132:133]
	s_mov_b32 m0, s62
	s_nop 0
	global_load_lds_dwordx4 v[226:227], off
	s_waitcnt vmcnt(8)
	s_waitcnt lgkmcnt(0)
	s_barrier
	s_setprio 1
	s_waitcnt lgkmcnt(0)
	v_mfma_f32_16x16x32_bf16 v[126:129], v[140:143], v[176:179], v[126:129]
	v_mfma_f32_16x16x32_bf16 v[122:125], v[152:155], v[176:179], v[122:125]
	v_mfma_f32_16x16x32_bf16 v[110:113], v[140:143], v[196:199], v[110:113]
	v_mfma_f32_16x16x32_bf16 v[106:109], v[152:155], v[196:199], v[106:109]
	v_mfma_f32_16x16x32_bf16 v[94:97], v[140:143], v[204:207], v[94:97]
	v_mfma_f32_16x16x32_bf16 v[90:93], v[152:155], v[204:207], v[90:93]
	v_mfma_f32_16x16x32_bf16 v[78:81], v[140:143], v[212:215], v[78:81]
	v_mfma_f32_16x16x32_bf16 v[74:77], v[152:155], v[212:215], v[74:77]
	v_mfma_f32_16x16x32_bf16 v[126:129], v[148:151], v[180:183], v[126:129]
	v_mfma_f32_16x16x32_bf16 v[122:125], v[156:159], v[180:183], v[122:125]
	v_mfma_f32_16x16x32_bf16 v[110:113], v[148:151], v[200:203], v[110:113]
	v_mfma_f32_16x16x32_bf16 v[106:109], v[156:159], v[200:203], v[106:109]
	v_mfma_f32_16x16x32_bf16 v[94:97], v[148:151], v[208:211], v[94:97]
	v_mfma_f32_16x16x32_bf16 v[90:93], v[156:159], v[208:211], v[90:93]
	v_mfma_f32_16x16x32_bf16 v[78:81], v[148:151], v[216:219], v[78:81]
	v_mfma_f32_16x16x32_bf16 v[74:77], v[156:159], v[216:219], v[74:77]
	s_setprio 0
	s_setprio 1
	v_mfma_f32_16x16x32_bf16 v[118:121], v[160:163], v[176:179], v[118:121]
	v_mfma_f32_16x16x32_bf16 v[114:117], v[168:171], v[176:179], v[114:117]
	v_mfma_f32_16x16x32_bf16 v[102:105], v[160:163], v[196:199], v[102:105]
	v_mfma_f32_16x16x32_bf16 v[98:101], v[168:171], v[196:199], v[98:101]
	v_mfma_f32_16x16x32_bf16 v[86:89], v[160:163], v[204:207], v[86:89]
	v_mfma_f32_16x16x32_bf16 v[82:85], v[168:171], v[204:207], v[82:85]
	v_mfma_f32_16x16x32_bf16 v[70:73], v[160:163], v[212:215], v[70:73]
	v_mfma_f32_16x16x32_bf16 v[66:69], v[168:171], v[212:215], v[66:69]
	v_mfma_f32_16x16x32_bf16 v[118:121], v[164:167], v[180:183], v[118:121]
	v_mfma_f32_16x16x32_bf16 v[114:117], v[172:175], v[180:183], v[114:117]
	v_mfma_f32_16x16x32_bf16 v[102:105], v[164:167], v[200:203], v[102:105]
	v_mfma_f32_16x16x32_bf16 v[98:101], v[172:175], v[200:203], v[98:101]
	v_mfma_f32_16x16x32_bf16 v[86:89], v[164:167], v[208:211], v[86:89]
	v_mfma_f32_16x16x32_bf16 v[82:85], v[172:175], v[208:211], v[82:85]
	v_mfma_f32_16x16x32_bf16 v[70:73], v[164:167], v[216:219], v[70:73]
	v_mfma_f32_16x16x32_bf16 v[66:69], v[172:175], v[216:219], v[66:69]
	s_setprio 0
	s_barrier
; #define PG8_STAGE(bufoff, gbase, voff) do { _Pragma("unroll") for (int _i = 0; _i < 2; ++_i) \
;         __builtin_amdgcn_global_load_lds((const unsigned*)((const char*)(gbase) + (voff)[_i]), (PG8_LAS unsigned*)(lds + (bufoff) + ldsw + _i * 8192), 16, 0, 0); } while (0)
; #define PG8_LDA(dst, b, h) do { _Pragma("unroll") for (int m = 0; m < 4; ++m) _Pragma("unroll") for (int k = 0; k < 2; ++k) dst[m][k] = *(const PG8_LAS bf16x8*)(lds + PG8_SA(b, h) + aoff + m * 2048 + k * 1024); } while (0)
; #define PG8_MMA(ai, bj, At, Bt) do { __builtin_amdgcn_s_setprio(1); _Pragma("unroll") for (int k = 0; k < 2; ++k) _Pragma("unroll") for (int m = 0; m < 4; ++m) _Pragma("unroll") for (int n = 0; n < 2; ++n) \
;         acc[ai][bj][m][n] = __builtin_amdgcn_mfma_f32_16x16x32_bf16(Bt[n][k], At[m][k], acc[ai][bj][m][n], 0, 0, 0); __builtin_amdgcn_s_setprio(0); } while (0)
; #define PG8_WAIT_V(n) asm volatile("s_waitcnt vmcnt(" #n ")" ::: "memory")
; #define PG8_WAIT_L(n) asm volatile("s_waitcnt lgkmcnt(" #n ")" ::: "memory")
; #define PG8_BAR __builtin_amdgcn_s_barrier()
; #define PG8_SCHED __builtin_amdgcn_sched_barrier(0)
; template <class Epi, class Sched, bool ALIGN_EPI = false, bool SP2 = false>
; __device__ __forceinline__ void gemm_phase(PG8_LAS unsigned char* lds, const Gemm g, const Sched& S, const Epi& E, int tid_in) {
;     ...
;             PG8_LDA(At, 1, 1); PG8_STAGE(PG8_SB(1, 0), b3, voffB); PG8_STAGE(PG8_SB(1, 1), b3 + hstep, voffB); PG8_STAGE(PG8_SA(1, 0), a3, voffA);
;             PG8_WAIT_V(8); PG8_WAIT_L(0); PG8_BAR; PG8_MMA(1, 0, At, B0); PG8_MMA(1, 1, At, B1); PG8_BAR; PG8_SCHED;
;     ...
;         if constexpr (ALIGN_EPI) { if (wr == 0) PG8_BAR; }
	s_add_i32 s56, s33, s58
	v_lshl_add_u64 v[184:185], v[184:185], 0, s[26:27]
	s_mov_b32 m0, s56
	ds_read_b128 v[176:179], v147 offset:49152
	ds_read_b128 v[180:183], v147 offset:50176
	ds_read_b128 v[196:199], v147 offset:51200
	ds_read_b128 v[200:203], v147 offset:52224
	ds_read_b128 v[204:207], v147 offset:53248
	ds_read_b128 v[208:211], v147 offset:54272
	ds_read_b128 v[212:215], v147 offset:55296
	ds_read_b128 v[216:219], v147 offset:56320
	global_load_lds_dwordx4 v[184:185], off
	s_add_i32 m0, s56, 0x2000
	s_add_u32 s54, s54, 0x40080
	v_lshl_add_u64 v[184:185], v[220:221], 0, s[26:27]
	s_addc_u32 s55, s55, 0
	s_add_i32 s56, s74, s58
	global_load_lds_dwordx4 v[184:185], off
	v_lshl_add_u64 v[184:185], s[54:55], 0, v[0:1]
	s_mov_b32 m0, s56
	s_nop 0
	global_load_lds_dwordx4 v[184:185], off
	v_lshl_add_u64 v[184:185], s[54:55], 0, v[130:131]
	s_add_i32 m0, s56, 0x2000
	s_nop 0
	global_load_lds_dwordx4 v[184:185], off
	v_lshl_add_u64 v[184:185], v[222:223], 0, s[26:27]
	s_mov_b32 m0, s65
	s_nop 0
	global_load_lds_dwordx4 v[184:185], off
	v_lshl_add_u64 v[184:185], v[224:225], 0, s[26:27]
	s_mov_b32 m0, s68
	s_nop 0
	global_load_lds_dwordx4 v[184:185], off
	s_waitcnt vmcnt(8)
	s_waitcnt lgkmcnt(0)
	s_barrier
	s_setprio 1
	s_waitcnt lgkmcnt(0)
	v_mfma_f32_16x16x32_bf16 v[62:65], v[140:143], v[176:179], v[62:65]
	v_mfma_f32_16x16x32_bf16 v[58:61], v[152:155], v[176:179], v[58:61]
	v_mfma_f32_16x16x32_bf16 v[46:49], v[140:143], v[196:199], v[46:49]
	v_mfma_f32_16x16x32_bf16 v[42:45], v[152:155], v[196:199], v[42:45]
	v_mfma_f32_16x16x32_bf16 v[30:33], v[140:143], v[204:207], v[30:33]
	v_mfma_f32_16x16x32_bf16 v[26:29], v[152:155], v[204:207], v[26:29]
	v_mfma_f32_16x16x32_bf16 v[14:17], v[140:143], v[212:215], v[14:17]
	v_mfma_f32_16x16x32_bf16 v[10:13], v[152:155], v[212:215], v[10:13]
	v_mfma_f32_16x16x32_bf16 v[62:65], v[148:151], v[180:183], v[62:65]
	v_mfma_f32_16x16x32_bf16 v[58:61], v[156:159], v[180:183], v[58:61]
	v_mfma_f32_16x16x32_bf16 v[46:49], v[148:151], v[200:203], v[46:49]
	v_mfma_f32_16x16x32_bf16 v[42:45], v[156:159], v[200:203], v[42:45]
	v_mfma_f32_16x16x32_bf16 v[30:33], v[148:151], v[208:211], v[30:33]
	v_mfma_f32_16x16x32_bf16 v[26:29], v[156:159], v[208:211], v[26:29]
	v_mfma_f32_16x16x32_bf16 v[14:17], v[148:151], v[216:219], v[14:17]
	v_mfma_f32_16x16x32_bf16 v[10:13], v[156:159], v[216:219], v[10:13]
	s_setprio 0
	s_setprio 1
	v_mfma_f32_16x16x32_bf16 v[54:57], v[160:163], v[176:179], v[54:57]
	v_mfma_f32_16x16x32_bf16 v[50:53], v[168:171], v[176:179], v[50:53]
	v_mfma_f32_16x16x32_bf16 v[38:41], v[160:163], v[196:199], v[38:41]
	v_mfma_f32_16x16x32_bf16 v[34:37], v[168:171], v[196:199], v[34:37]
	v_mfma_f32_16x16x32_bf16 v[22:25], v[160:163], v[204:207], v[22:25]
	v_mfma_f32_16x16x32_bf16 v[18:21], v[168:171], v[204:207], v[18:21]
	v_mfma_f32_16x16x32_bf16 v[6:9], v[160:163], v[212:215], v[6:9]
	v_mfma_f32_16x16x32_bf16 v[2:5], v[168:171], v[212:215], v[2:5]
	v_mfma_f32_16x16x32_bf16 v[54:57], v[164:167], v[180:183], v[54:57]
	v_mfma_f32_16x16x32_bf16 v[50:53], v[172:175], v[180:183], v[50:53]
	v_mfma_f32_16x16x32_bf16 v[38:41], v[164:167], v[200:203], v[38:41]
	v_mfma_f32_16x16x32_bf16 v[34:37], v[172:175], v[200:203], v[34:37]
	v_mfma_f32_16x16x32_bf16 v[22:25], v[164:167], v[208:211], v[22:25]
	v_mfma_f32_16x16x32_bf16 v[18:21], v[172:175], v[208:211], v[18:21]
	v_mfma_f32_16x16x32_bf16 v[6:9], v[164:167], v[216:219], v[6:9]
	v_mfma_f32_16x16x32_bf16 v[2:5], v[172:175], v[216:219], v[2:5]
	s_setprio 0
	s_add_i32 s82, s82, 2
	s_add_u32 s52, s52, 0x100
	s_addc_u32 s53, s53, 0
	s_add_u32 s80, s80, 0x100
	s_addc_u32 s81, s81, 0
	s_cmp_gt_u32 s82, 13
	s_barrier
	s_cbranch_scc0 .LBB0_492
	s_and_b64 vcc, exec, s[40:41]
	s_cbranch_vccz .LBB0_495
	s_barrier

; #define PG8_STAGE(bufoff, gbase, voff) do { _Pragma("unroll") for (int _i = 0; _i < 2; ++_i) \
;         __builtin_amdgcn_global_load_lds((const unsigned*)((const char*)(gbase) + (voff)[_i]), (PG8_LAS unsigned*)(lds + (bufoff) + ldsw + _i * 8192), 16, 0, 0); } while (0)
; #define PG8_LDA(dst, b, h) do { _Pragma("unroll") for (int m = 0; m < 4; ++m) _Pragma("unroll") for (int k = 0; k < 2; ++k) dst[m][k] = *(const PG8_LAS bf16x8*)(lds + PG8_SA(b, h) + aoff + m * 2048 + k * 1024); } while (0)
; #define PG8_LDB(dst, b, h) do { _Pragma("unroll") for (int n = 0; n < 2; ++n) _Pragma("unroll") for (int k = 0; k < 2; ++k) dst[n][k] = *(const PG8_LAS bf16x8*)(lds + PG8_SB(b, h) + boff + n * 2048 + k * 1024); } while (0)
; #define PG8_WAIT_V(n) asm volatile("s_waitcnt vmcnt(" #n ")" ::: "memory")
; #define PG8_WAIT_L(n) asm volatile("s_waitcnt lgkmcnt(" #n ")" ::: "memory")
; #define PG8_BAR __builtin_amdgcn_s_barrier()
; #define PG8_SCHED __builtin_amdgcn_sched_barrier(0)
; template <class Epi, class Sched, bool ALIGN_EPI = false, bool SP2 = false>
; __device__ __forceinline__ void gemm_phase(PG8_LAS unsigned char* lds, const Gemm g, const Sched& S, const Epi& E, int tid_in) {
;     ...
;         const char* nA = has_next ? (const char*)g.A + (size_t)nxt.pm * tstep : cA; const char* nB = has_next ? (const char*)g.Bt + (size_t)nxt.pn * tstep : cB;
;         for (int t = 0; t < nt; t += 2) {
;             const bool last = (t == nt - 2);
;             const char* a1 = cA + (size_t)(t + 1) * kstep;
;             const char* a2 = last ? nA : cA + (size_t)(t + 2) * kstep; const char* b2 = last ? nB : cB + (size_t)(t + 2) * kstep;
;             const char* a3 = a2 + kstep; const char* b3 = b2 + kstep;
;             if (last && has_next) S.a_ready(nxt);
;             if constexpr (SP2) {
;             PG8_LDB(B0, 0, 0); PG8_LDB(B1, 0, 1); PG8_SCHED; PG8_LDA(At, 0, 0); PG8_STAGE(PG8_SA(1, 1), a1 + hstep, voffA);
;             PG8_WAIT_V(8); PG8_WAIT_L(0); PG8_BAR; PG8_MMA(0, 0, At, B0); PG8_MMA(0, 1, At, B1); PG8_BAR; PG8_SCHED;
;             PG8_LDA(At, 0, 1); PG8_STAGE(PG8_SB(0, 0), b2, voffB); PG8_STAGE(PG8_SB(0, 1), b2 + hstep, voffB); PG8_STAGE(PG8_SA(0, 0), a2, voffA);
;             PG8_WAIT_V(8); PG8_WAIT_L(0); PG8_BAR; PG8_MMA(1, 0, At, B0); PG8_MMA(1, 1, At, B1); PG8_BAR; PG8_SCHED;
.LBB0_566:
	s_ashr_i32 s43, s42, 31
	s_lshl_b64 s[46:47], s[42:43], 21
	s_add_u32 s46, s58, s46
	s_addc_u32 s47, s59, s47
	s_and_b64 s[48:49], s[40:41], exec
	s_cselect_b32 s43, s47, s51
	s_cselect_b32 s79, s46, s50
	s_ashr_i32 s45, s44, 31
	s_lshl_b64 s[48:49], s[44:45], 21
	s_add_u32 s48, s56, s48
	s_addc_u32 s49, s57, s49
	s_and_b64 s[54:55], s[40:41], exec
	s_cselect_b32 s45, s49, s53
	s_cselect_b32 s80, s48, s52
	s_add_u32 s50, s50, 0x100080
	s_addc_u32 s51, s51, 0
	s_add_u32 s81, s52, 0x100
	s_addc_u32 s82, s53, 0
	s_mov_b32 s83, -2
	s_waitcnt lgkmcnt(0)
	v_add_u32_e32 v134, s84, v210
	v_add_u32_e32 v158, s85, v210
	ds_read_b128 v[106:109], v134
	ds_read_b128 v[110:113], v134 offset:1024
	ds_read_b128 v[130:133], v134 offset:2048
	ds_read_b128 v[134:137], v134 offset:3072
	ds_read_b128 v[146:149], v158
	ds_read_b128 v[150:153], v158 offset:1024
	ds_read_b128 v[154:157], v158 offset:2048
	ds_read_b128 v[158:161], v158 offset:3072
	s_add_u32 s52, s50, 0xfff00080
	s_addc_u32 s53, s51, -1
	s_cmp_eq_u32 s83, 60
	s_cselect_b32 s55, s43, s53
	s_cselect_b32 s54, s79, s52
	s_cselect_b32 s53, s45, s82
	s_cselect_b32 s52, s80, s81
	v_lshl_add_u64 v[216:217], s[50:51], 0, v[202:203]
	s_add_i32 m0, s61, 0xc000
	ds_read_b128 v[162:165], v211
	ds_read_b128 v[166:169], v211 offset:1024
	ds_read_b128 v[170:173], v211 offset:2048
	ds_read_b128 v[174:177], v211 offset:3072
	ds_read_b128 v[178:181], v211 offset:4096
	ds_read_b128 v[182:185], v211 offset:5120
	ds_read_b128 v[206:209], v211 offset:6144
	ds_read_b128 v[212:215], v211 offset:7168
	global_load_lds_dwordx4 v[216:217], off
	v_lshl_add_u64 v[216:217], s[50:51], 0, v[204:205]
	s_add_i32 m0, s61, 0xe000
	s_nop 0
	global_load_lds_dwordx4 v[216:217], off
	s_waitcnt vmcnt(8)
	s_waitcnt lgkmcnt(0)
	s_barrier
	s_setprio 1
	s_waitcnt lgkmcnt(0)
	v_mfma_f32_16x16x32_bf16 v[142:145], v[106:109], v[162:165], 0
	v_mfma_f32_16x16x32_bf16 v[138:141], v[130:133], v[162:165], 0
	v_mfma_f32_16x16x32_bf16 v[118:121], v[106:109], v[170:173], 0
	v_mfma_f32_16x16x32_bf16 v[114:117], v[130:133], v[170:173], 0
	v_mfma_f32_16x16x32_bf16 v[94:97], v[106:109], v[178:181], 0
	v_mfma_f32_16x16x32_bf16 v[90:93], v[130:133], v[178:181], 0
	v_mfma_f32_16x16x32_bf16 v[78:81], v[106:109], v[206:209], 0
	v_mfma_f32_16x16x32_bf16 v[74:77], v[130:133], v[206:209], 0
	v_mfma_f32_16x16x32_bf16 v[142:145], v[110:113], v[166:169], v[142:145]
	v_mfma_f32_16x16x32_bf16 v[138:141], v[134:137], v[166:169], v[138:141]
	v_mfma_f32_16x16x32_bf16 v[118:121], v[110:113], v[174:177], v[118:121]
	v_mfma_f32_16x16x32_bf16 v[114:117], v[134:137], v[174:177], v[114:117]
	v_mfma_f32_16x16x32_bf16 v[94:97], v[110:113], v[182:185], v[94:97]
	v_mfma_f32_16x16x32_bf16 v[90:93], v[134:137], v[182:185], v[90:93]
	v_mfma_f32_16x16x32_bf16 v[78:81], v[110:113], v[212:215], v[78:81]
	v_mfma_f32_16x16x32_bf16 v[74:77], v[134:137], v[212:215], v[74:77]
	s_setprio 0
	s_setprio 1
	v_mfma_f32_16x16x32_bf16 v[126:129], v[146:149], v[162:165], 0
	v_mfma_f32_16x16x32_bf16 v[122:125], v[154:157], v[162:165], 0
	v_mfma_f32_16x16x32_bf16 v[102:105], v[146:149], v[170:173], 0
	v_mfma_f32_16x16x32_bf16 v[98:101], v[154:157], v[170:173], 0
	v_mfma_f32_16x16x32_bf16 v[86:89], v[146:149], v[178:181], 0
	v_mfma_f32_16x16x32_bf16 v[82:85], v[154:157], v[178:181], 0
	v_mfma_f32_16x16x32_bf16 v[70:73], v[146:149], v[206:209], 0
	v_mfma_f32_16x16x32_bf16 v[66:69], v[154:157], v[206:209], 0
	v_mfma_f32_16x16x32_bf16 v[126:129], v[150:153], v[166:169], v[126:129]
	v_mfma_f32_16x16x32_bf16 v[122:125], v[158:161], v[166:169], v[122:125]
	v_mfma_f32_16x16x32_bf16 v[102:105], v[150:153], v[174:177], v[102:105]
	v_mfma_f32_16x16x32_bf16 v[98:101], v[158:161], v[174:177], v[98:101]
	v_mfma_f32_16x16x32_bf16 v[86:89], v[150:153], v[182:185], v[86:89]
	v_mfma_f32_16x16x32_bf16 v[82:85], v[158:161], v[182:185], v[82:85]
	v_mfma_f32_16x16x32_bf16 v[70:73], v[150:153], v[212:215], v[70:73]
	v_mfma_f32_16x16x32_bf16 v[66:69], v[158:161], v[212:215], v[66:69]
	s_setprio 0
	s_barrier
	s_add_i32 s86, s84, s60
	v_lshl_add_u64 v[216:217], s[52:53], 0, v[0:1]
	s_mov_b32 m0, s86
	ds_read_b128 v[162:165], v211 offset:16384
	ds_read_b128 v[166:169], v211 offset:17408
	ds_read_b128 v[170:173], v211 offset:18432
	ds_read_b128 v[174:177], v211 offset:19456
	ds_read_b128 v[178:181], v211 offset:20480
	ds_read_b128 v[182:185], v211 offset:21504
	ds_read_b128 v[206:209], v211 offset:22528
	ds_read_b128 v[212:215], v211 offset:23552
	global_load_lds_dwordx4 v[216:217], off
	s_add_i32 m0, s86, 0x2000
	s_add_u32 s86, s52, 0x100000
	v_lshl_add_u64 v[218:219], s[52:53], 0, v[196:197]
	s_addc_u32 s87, s53, 0
	s_add_i32 s92, s85, s60
	global_load_lds_dwordx4 v[218:219], off
	v_lshl_add_u64 v[220:221], s[86:87], 0, v[0:1]
	s_mov_b32 m0, s92
	v_lshl_add_u64 v[222:223], s[54:55], 0, v[198:199]
	global_load_lds_dwordx4 v[220:221], off
	v_lshl_add_u64 v[220:221], s[86:87], 0, v[196:197]
	s_add_i32 m0, s92, 0x2000
	s_nop 0
	global_load_lds_dwordx4 v[220:221], off
	v_lshl_add_u64 v[220:221], s[54:55], 0, v[200:201]
	s_mov_b32 m0, s61
	s_nop 0
	global_load_lds_dwordx4 v[220:221], off
	s_mov_b32 m0, s62
	s_nop 0
	global_load_lds_dwordx4 v[222:223], off
	s_waitcnt vmcnt(8)
	s_waitcnt lgkmcnt(0)
	s_barrier
; #define PG8_STAGE(bufoff, gbase, voff) do { _Pragma("unroll") for (int _i = 0; _i < 2; ++_i) \
;         __builtin_amdgcn_global_load_lds((const unsigned*)((const char*)(gbase) + (voff)[_i]), (PG8_LAS unsigned*)(lds + (bufoff) + ldsw + _i * 8192), 16, 0, 0); } while (0)
; #define PG8_LDA(dst, b, h) do { _Pragma("unroll") for (int m = 0; m < 4; ++m) _Pragma("unroll") for (int k = 0; k < 2; ++k) dst[m][k] = *(const PG8_LAS bf16x8*)(lds + PG8_SA(b, h) + aoff + m * 2048 + k * 1024); } while (0)
; #define PG8_LDB(dst, b, h) do { _Pragma("unroll") for (int n = 0; n < 2; ++n) _Pragma("unroll") for (int k = 0; k < 2; ++k) dst[n][k] = *(const PG8_LAS bf16x8*)(lds + PG8_SB(b, h) + boff + n * 2048 + k * 1024); } while (0)
; #define PG8_MMA(ai, bj, At, Bt) do { __builtin_amdgcn_s_setprio(1); _Pragma("unroll") for (int k = 0; k < 2; ++k) _Pragma("unroll") for (int m = 0; m < 4; ++m) _Pragma("unroll") for (int n = 0; n < 2; ++n) \
;         acc[ai][bj][m][n] = __builtin_amdgcn_mfma_f32_16x16x32_bf16(Bt[n][k], At[m][k], acc[ai][bj][m][n], 0, 0, 0); __builtin_amdgcn_s_setprio(0); } while (0)
; #define PG8_WAIT_V(n) asm volatile("s_waitcnt vmcnt(" #n ")" ::: "memory")
; #define PG8_WAIT_L(n) asm volatile("s_waitcnt lgkmcnt(" #n ")" ::: "memory")
; #define PG8_BAR __builtin_amdgcn_s_barrier()
; #define PG8_SCHED __builtin_amdgcn_sched_barrier(0)
; template <class Epi, class Sched, bool ALIGN_EPI = false, bool SP2 = false>
; __device__ __forceinline__ void gemm_phase(PG8_LAS unsigned char* lds, const Gemm g, const Sched& S, const Epi& E, int tid_in) {
;     ...
;             PG8_WAIT_V(8); PG8_WAIT_L(0); PG8_BAR; PG8_MMA(1, 0, At, B0); PG8_MMA(1, 1, At, B1); PG8_BAR; PG8_SCHED;
;             PG8_LDB(B0, 1, 0); PG8_LDB(B1, 1, 1); PG8_SCHED; PG8_LDA(At, 1, 0); PG8_STAGE(PG8_SA(0, 1), a2 + hstep, voffA);
;             PG8_WAIT_V(8); PG8_WAIT_L(0); PG8_BAR; PG8_MMA(0, 0, At, B0); PG8_MMA(0, 1, At, B1); PG8_BAR; PG8_SCHED;
	s_setprio 1
	s_waitcnt lgkmcnt(0)
	v_mfma_f32_16x16x32_bf16 v[62:65], v[106:109], v[162:165], 0
	v_mfma_f32_16x16x32_bf16 v[58:61], v[130:133], v[162:165], 0
	v_mfma_f32_16x16x32_bf16 v[46:49], v[106:109], v[170:173], 0
	v_mfma_f32_16x16x32_bf16 v[42:45], v[130:133], v[170:173], 0
	v_mfma_f32_16x16x32_bf16 v[30:33], v[106:109], v[178:181], 0
	v_mfma_f32_16x16x32_bf16 v[26:29], v[130:133], v[178:181], 0
	v_mfma_f32_16x16x32_bf16 v[14:17], v[106:109], v[206:209], 0
	v_mfma_f32_16x16x32_bf16 v[10:13], v[130:133], v[206:209], 0
	v_mfma_f32_16x16x32_bf16 v[62:65], v[110:113], v[166:169], v[62:65]
	v_mfma_f32_16x16x32_bf16 v[58:61], v[134:137], v[166:169], v[58:61]
	v_mfma_f32_16x16x32_bf16 v[46:49], v[110:113], v[174:177], v[46:49]
	v_mfma_f32_16x16x32_bf16 v[42:45], v[134:137], v[174:177], v[42:45]
	v_mfma_f32_16x16x32_bf16 v[30:33], v[110:113], v[182:185], v[30:33]
	v_mfma_f32_16x16x32_bf16 v[26:29], v[134:137], v[182:185], v[26:29]
	v_mfma_f32_16x16x32_bf16 v[14:17], v[110:113], v[212:215], v[14:17]
	v_mfma_f32_16x16x32_bf16 v[10:13], v[134:137], v[212:215], v[10:13]
	s_setprio 0
	s_setprio 1
	v_mfma_f32_16x16x32_bf16 v[54:57], v[146:149], v[162:165], 0
	v_mfma_f32_16x16x32_bf16 v[50:53], v[154:157], v[162:165], 0
	v_mfma_f32_16x16x32_bf16 v[38:41], v[146:149], v[170:173], 0
	v_mfma_f32_16x16x32_bf16 v[34:37], v[154:157], v[170:173], 0
	v_mfma_f32_16x16x32_bf16 v[22:25], v[146:149], v[178:181], 0
	v_mfma_f32_16x16x32_bf16 v[18:21], v[154:157], v[178:181], 0
	v_mfma_f32_16x16x32_bf16 v[6:9], v[146:149], v[206:209], 0
	v_mfma_f32_16x16x32_bf16 v[2:5], v[154:157], v[206:209], 0
	v_mfma_f32_16x16x32_bf16 v[54:57], v[150:153], v[166:169], v[54:57]
	v_mfma_f32_16x16x32_bf16 v[50:53], v[158:161], v[166:169], v[50:53]
	v_mfma_f32_16x16x32_bf16 v[38:41], v[150:153], v[174:177], v[38:41]
	v_mfma_f32_16x16x32_bf16 v[34:37], v[158:161], v[174:177], v[34:37]
	v_mfma_f32_16x16x32_bf16 v[22:25], v[150:153], v[182:185], v[22:25]
	v_mfma_f32_16x16x32_bf16 v[18:21], v[158:161], v[182:185], v[18:21]
	v_mfma_f32_16x16x32_bf16 v[6:9], v[150:153], v[212:215], v[6:9]
	v_mfma_f32_16x16x32_bf16 v[2:5], v[158:161], v[212:215], v[2:5]
	s_setprio 0
	s_barrier
	v_add_u32_e32 v134, s33, v210
	v_add_u32_e32 v158, s74, v210
	ds_read_b128 v[106:109], v134
	ds_read_b128 v[110:113], v134 offset:1024
	ds_read_b128 v[130:133], v134 offset:2048
	ds_read_b128 v[134:137], v134 offset:3072
	ds_read_b128 v[146:149], v158
	ds_read_b128 v[150:153], v158 offset:1024
	ds_read_b128 v[154:157], v158 offset:2048
	ds_read_b128 v[158:161], v158 offset:3072
	s_add_u32 s54, s54, 0x100000
	s_addc_u32 s55, s55, 0
	s_mov_b32 m0, s63
	v_lshl_add_u64 v[224:225], s[54:55], 0, v[200:201]
	ds_read_b128 v[162:165], v211 offset:32768
	ds_read_b128 v[166:169], v211 offset:33792
	ds_read_b128 v[170:173], v211 offset:34816
	ds_read_b128 v[174:177], v211 offset:35840
	ds_read_b128 v[178:181], v211 offset:36864
	ds_read_b128 v[182:185], v211 offset:37888
	ds_read_b128 v[206:209], v211 offset:38912
	ds_read_b128 v[212:215], v211 offset:39936
	global_load_lds_dwordx4 v[224:225], off
	v_lshl_add_u64 v[224:225], s[54:55], 0, v[198:199]
	s_mov_b32 m0, s64
	s_nop 0
	global_load_lds_dwordx4 v[224:225], off
	s_waitcnt vmcnt(8)
	s_waitcnt lgkmcnt(0)
	s_barrier
	s_setprio 1
	s_waitcnt lgkmcnt(0)
	v_mfma_f32_16x16x32_bf16 v[142:145], v[106:109], v[162:165], v[142:145]
	v_mfma_f32_16x16x32_bf16 v[138:141], v[130:133], v[162:165], v[138:141]
	v_mfma_f32_16x16x32_bf16 v[118:121], v[106:109], v[170:173], v[118:121]
	v_mfma_f32_16x16x32_bf16 v[114:117], v[130:133], v[170:173], v[114:117]
	v_mfma_f32_16x16x32_bf16 v[94:97], v[106:109], v[178:181], v[94:97]
	v_mfma_f32_16x16x32_bf16 v[90:93], v[130:133], v[178:181], v[90:93]
	v_mfma_f32_16x16x32_bf16 v[78:81], v[106:109], v[206:209], v[78:81]
	v_mfma_f32_16x16x32_bf16 v[74:77], v[130:133], v[206:209], v[74:77]
	v_mfma_f32_16x16x32_bf16 v[142:145], v[110:113], v[166:169], v[142:145]
	v_mfma_f32_16x16x32_bf16 v[138:141], v[134:137], v[166:169], v[138:141]
	v_mfma_f32_16x16x32_bf16 v[118:121], v[110:113], v[174:177], v[118:121]
	v_mfma_f32_16x16x32_bf16 v[114:117], v[134:137], v[174:177], v[114:117]
	v_mfma_f32_16x16x32_bf16 v[94:97], v[110:113], v[182:185], v[94:97]
	v_mfma_f32_16x16x32_bf16 v[90:93], v[134:137], v[182:185], v[90:93]
	v_mfma_f32_16x16x32_bf16 v[78:81], v[110:113], v[212:215], v[78:81]
	v_mfma_f32_16x16x32_bf16 v[74:77], v[134:137], v[212:215], v[74:77]
	s_setprio 0
	s_setprio 1
	v_mfma_f32_16x16x32_bf16 v[126:129], v[146:149], v[162:165], v[126:129]
	v_mfma_f32_16x16x32_bf16 v[122:125], v[154:157], v[162:165], v[122:125]
	v_mfma_f32_16x16x32_bf16 v[102:105], v[146:149], v[170:173], v[102:105]
	v_mfma_f32_16x16x32_bf16 v[98:101], v[154:157], v[170:173], v[98:101]
	v_mfma_f32_16x16x32_bf16 v[86:89], v[146:149], v[178:181], v[86:89]
	v_mfma_f32_16x16x32_bf16 v[82:85], v[154:157], v[178:181], v[82:85]
	v_mfma_f32_16x16x32_bf16 v[70:73], v[146:149], v[206:209], v[70:73]
	v_mfma_f32_16x16x32_bf16 v[66:69], v[154:157], v[206:209], v[66:69]
	v_mfma_f32_16x16x32_bf16 v[126:129], v[150:153], v[166:169], v[126:129]
	v_mfma_f32_16x16x32_bf16 v[122:125], v[158:161], v[166:169], v[122:125]
	v_mfma_f32_16x16x32_bf16 v[102:105], v[150:153], v[174:177], v[102:105]
	v_mfma_f32_16x16x32_bf16 v[98:101], v[158:161], v[174:177], v[98:101]
	v_mfma_f32_16x16x32_bf16 v[86:89], v[150:153], v[182:185], v[86:89]
	v_mfma_f32_16x16x32_bf16 v[82:85], v[158:161], v[182:185], v[82:85]
	v_mfma_f32_16x16x32_bf16 v[70:73], v[150:153], v[212:215], v[70:73]
	v_mfma_f32_16x16x32_bf16 v[66:69], v[158:161], v[212:215], v[66:69]
	s_setprio 0
	s_barrier
; #define PG8_STAGE(bufoff, gbase, voff) do { _Pragma("unroll") for (int _i = 0; _i < 2; ++_i) \
;         __builtin_amdgcn_global_load_lds((const unsigned*)((const char*)(gbase) + (voff)[_i]), (PG8_LAS unsigned*)(lds + (bufoff) + ldsw + _i * 8192), 16, 0, 0); } while (0)
; #define PG8_LDA(dst, b, h) do { _Pragma("unroll") for (int m = 0; m < 4; ++m) _Pragma("unroll") for (int k = 0; k < 2; ++k) dst[m][k] = *(const PG8_LAS bf16x8*)(lds + PG8_SA(b, h) + aoff + m * 2048 + k * 1024); } while (0)
; #define PG8_LDB(dst, b, h) do { _Pragma("unroll") for (int n = 0; n < 2; ++n) _Pragma("unroll") for (int k = 0; k < 2; ++k) dst[n][k] = *(const PG8_LAS bf16x8*)(lds + PG8_SB(b, h) + boff + n * 2048 + k * 1024); } while (0)
; #define PG8_MMA(ai, bj, At, Bt) do { __builtin_amdgcn_s_setprio(1); _Pragma("unroll") for (int k = 0; k < 2; ++k) _Pragma("unroll") for (int m = 0; m < 4; ++m) _Pragma("unroll") for (int n = 0; n < 2; ++n) \
;         acc[ai][bj][m][n] = __builtin_amdgcn_mfma_f32_16x16x32_bf16(Bt[n][k], At[m][k], acc[ai][bj][m][n], 0, 0, 0); __builtin_amdgcn_s_setprio(0); } while (0)
; #define PG8_WAIT_V(n) asm volatile("s_waitcnt vmcnt(" #n ")" ::: "memory")
; #define PG8_WAIT_L(n) asm volatile("s_waitcnt lgkmcnt(" #n ")" ::: "memory")
; #define PG8_BAR __builtin_amdgcn_s_barrier()
; #define PG8_SCHED __builtin_amdgcn_sched_barrier(0)
; template <class Epi, class Sched, bool ALIGN_EPI = false, bool SP2 = false>
; __device__ __forceinline__ void gemm_phase(PG8_LAS unsigned char* lds, const Gemm g, const Sched& S, const Epi& E, int tid_in) {
;     ...
;             PG8_LDB(B0, 0, 0); PG8_LDB(B1, 0, 1); PG8_SCHED; PG8_LDA(At, 0, 0); PG8_STAGE(PG8_SA(1, 1), a1 + hstep, voffA);
;             PG8_WAIT_V(8); PG8_WAIT_L(0); PG8_BAR; PG8_MMA(0, 0, At, B0); PG8_MMA(0, 1, At, B1); PG8_BAR; PG8_SCHED;
;     ...
;             PG8_LDA(At, 1, 1); PG8_STAGE(PG8_SB(1, 0), b3, voffB); PG8_STAGE(PG8_SB(1, 1), b3 + hstep, voffB); PG8_STAGE(PG8_SA(1, 0), a3, voffA);
;             PG8_WAIT_V(8); PG8_WAIT_L(0); PG8_BAR; PG8_MMA(1, 0, At, B0); PG8_MMA(1, 1, At, B1); PG8_BAR; PG8_SCHED;
	s_add_i32 s54, s33, s60
	v_lshl_add_u64 v[216:217], v[216:217], 0, s[26:27]
	s_mov_b32 m0, s54
	ds_read_b128 v[162:165], v211 offset:49152
	ds_read_b128 v[166:169], v211 offset:50176
	ds_read_b128 v[170:173], v211 offset:51200
	ds_read_b128 v[174:177], v211 offset:52224
	ds_read_b128 v[178:181], v211 offset:53248
	ds_read_b128 v[182:185], v211 offset:54272
	ds_read_b128 v[206:209], v211 offset:55296
	ds_read_b128 v[212:215], v211 offset:56320
	global_load_lds_dwordx4 v[216:217], off
	s_add_i32 m0, s54, 0x2000
	s_add_u32 s52, s52, 0x100080
	v_lshl_add_u64 v[216:217], v[218:219], 0, s[26:27]
	s_addc_u32 s53, s53, 0
	s_add_i32 s54, s74, s60
	global_load_lds_dwordx4 v[216:217], off
	v_lshl_add_u64 v[216:217], s[52:53], 0, v[0:1]
	s_mov_b32 m0, s54
	s_nop 0
	global_load_lds_dwordx4 v[216:217], off
	v_lshl_add_u64 v[216:217], s[52:53], 0, v[196:197]
	s_add_i32 m0, s54, 0x2000
	s_nop 0
	global_load_lds_dwordx4 v[216:217], off
	v_lshl_add_u64 v[216:217], v[220:221], 0, s[26:27]
	s_mov_b32 m0, s75
	s_nop 0
	global_load_lds_dwordx4 v[216:217], off
	v_lshl_add_u64 v[216:217], v[222:223], 0, s[26:27]
	s_mov_b32 m0, s76
	s_nop 0
	global_load_lds_dwordx4 v[216:217], off
	s_waitcnt vmcnt(8)
	s_waitcnt lgkmcnt(0)
	s_barrier
	s_setprio 1
	s_waitcnt lgkmcnt(0)
	v_mfma_f32_16x16x32_bf16 v[62:65], v[106:109], v[162:165], v[62:65]
	v_mfma_f32_16x16x32_bf16 v[58:61], v[130:133], v[162:165], v[58:61]
	v_mfma_f32_16x16x32_bf16 v[46:49], v[106:109], v[170:173], v[46:49]
	v_mfma_f32_16x16x32_bf16 v[42:45], v[130:133], v[170:173], v[42:45]
	v_mfma_f32_16x16x32_bf16 v[30:33], v[106:109], v[178:181], v[30:33]
	v_mfma_f32_16x16x32_bf16 v[26:29], v[130:133], v[178:181], v[26:29]
	v_mfma_f32_16x16x32_bf16 v[14:17], v[106:109], v[206:209], v[14:17]
	v_mfma_f32_16x16x32_bf16 v[10:13], v[130:133], v[206:209], v[10:13]
	v_mfma_f32_16x16x32_bf16 v[62:65], v[110:113], v[166:169], v[62:65]
	v_mfma_f32_16x16x32_bf16 v[58:61], v[134:137], v[166:169], v[58:61]
	v_mfma_f32_16x16x32_bf16 v[46:49], v[110:113], v[174:177], v[46:49]
	v_mfma_f32_16x16x32_bf16 v[42:45], v[134:137], v[174:177], v[42:45]
	v_mfma_f32_16x16x32_bf16 v[30:33], v[110:113], v[182:185], v[30:33]
	v_mfma_f32_16x16x32_bf16 v[26:29], v[134:137], v[182:185], v[26:29]
	v_mfma_f32_16x16x32_bf16 v[14:17], v[110:113], v[212:215], v[14:17]
	v_mfma_f32_16x16x32_bf16 v[10:13], v[134:137], v[212:215], v[10:13]
	s_setprio 0
	s_setprio 1
	v_mfma_f32_16x16x32_bf16 v[54:57], v[146:149], v[162:165], v[54:57]
	v_mfma_f32_16x16x32_bf16 v[50:53], v[154:157], v[162:165], v[50:53]
	v_mfma_f32_16x16x32_bf16 v[38:41], v[146:149], v[170:173], v[38:41]
	v_mfma_f32_16x16x32_bf16 v[34:37], v[154:157], v[170:173], v[34:37]
	v_mfma_f32_16x16x32_bf16 v[22:25], v[146:149], v[178:181], v[22:25]
	v_mfma_f32_16x16x32_bf16 v[18:21], v[154:157], v[178:181], v[18:21]
	v_mfma_f32_16x16x32_bf16 v[6:9], v[146:149], v[206:209], v[6:9]
	v_mfma_f32_16x16x32_bf16 v[2:5], v[154:157], v[206:209], v[2:5]
	v_mfma_f32_16x16x32_bf16 v[54:57], v[150:153], v[166:169], v[54:57]
	v_mfma_f32_16x16x32_bf16 v[50:53], v[158:161], v[166:169], v[50:53]
	v_mfma_f32_16x16x32_bf16 v[38:41], v[150:153], v[174:177], v[38:41]
	v_mfma_f32_16x16x32_bf16 v[34:37], v[158:161], v[174:177], v[34:37]
	v_mfma_f32_16x16x32_bf16 v[22:25], v[150:153], v[182:185], v[22:25]
	v_mfma_f32_16x16x32_bf16 v[18:21], v[158:161], v[182:185], v[18:21]
	v_mfma_f32_16x16x32_bf16 v[6:9], v[150:153], v[212:215], v[6:9]
	v_mfma_f32_16x16x32_bf16 v[2:5], v[158:161], v[212:215], v[2:5]
	s_setprio 0
	s_add_i32 s83, s83, 2
	s_add_u32 s50, s50, 0x100
	s_addc_u32 s51, s51, 0
	s_add_u32 s81, s81, 0x100
	s_addc_u32 s82, s82, 0
	s_cmp_gt_u32 s83, 61
	s_barrier
.LBB0_567:
	v_add_u32_e32 v134, s84, v210
	v_add_u32_e32 v158, s85, v210
	ds_read_b128 v[106:109], v134
	ds_read_b128 v[110:113], v134 offset:1024
	ds_read_b128 v[130:133], v134 offset:2048
	ds_read_b128 v[134:137], v134 offset:3072
	ds_read_b128 v[146:149], v158
	ds_read_b128 v[150:153], v158 offset:1024
	ds_read_b128 v[154:157], v158 offset:2048
	ds_read_b128 v[158:161], v158 offset:3072
	s_add_u32 s52, s50, 0xfff00080
	s_addc_u32 s53, s51, -1
	s_cmp_eq_u32 s83, 60
	s_cselect_b32 s55, s43, s53
	s_cselect_b32 s54, s79, s52
	s_cselect_b32 s53, s45, s82
	s_cselect_b32 s52, s80, s81
	v_lshl_add_u64 v[216:217], s[50:51], 0, v[202:203]
	s_add_i32 m0, s61, 0xc000
	ds_read_b128 v[162:165], v211
	ds_read_b128 v[166:169], v211 offset:1024
	ds_read_b128 v[170:173], v211 offset:2048
	ds_read_b128 v[174:177], v211 offset:3072
	ds_read_b128 v[178:181], v211 offset:4096
	ds_read_b128 v[182:185], v211 offset:5120
	ds_read_b128 v[206:209], v211 offset:6144
	ds_read_b128 v[212:215], v211 offset:7168
	global_load_lds_dwordx4 v[216:217], off
	v_lshl_add_u64 v[216:217], s[50:51], 0, v[204:205]
	s_add_i32 m0, s61, 0xe000
	s_nop 0
	global_load_lds_dwordx4 v[216:217], off
	s_waitcnt vmcnt(8)
	s_waitcnt lgkmcnt(0)
	s_barrier
; #define PG8_STAGE(bufoff, gbase, voff) do { _Pragma("unroll") for (int _i = 0; _i < 2; ++_i) \
;         __builtin_amdgcn_global_load_lds((const unsigned*)((const char*)(gbase) + (voff)[_i]), (PG8_LAS unsigned*)(lds + (bufoff) + ldsw + _i * 8192), 16, 0, 0); } while (0)
; #define PG8_LDA(dst, b, h) do { _Pragma("unroll") for (int m = 0; m < 4; ++m) _Pragma("unroll") for (int k = 0; k < 2; ++k) dst[m][k] = *(const PG8_LAS bf16x8*)(lds + PG8_SA(b, h) + aoff + m * 2048 + k * 1024); } while (0)
; #define PG8_MMA(ai, bj, At, Bt) do { __builtin_amdgcn_s_setprio(1); _Pragma("unroll") for (int k = 0; k < 2; ++k) _Pragma("unroll") for (int m = 0; m < 4; ++m) _Pragma("unroll") for (int n = 0; n < 2; ++n) \
;         acc[ai][bj][m][n] = __builtin_amdgcn_mfma_f32_16x16x32_bf16(Bt[n][k], At[m][k], acc[ai][bj][m][n], 0, 0, 0); __builtin_amdgcn_s_setprio(0); } while (0)
; #define PG8_WAIT_V(n) asm volatile("s_waitcnt vmcnt(" #n ")" ::: "memory")
; #define PG8_WAIT_L(n) asm volatile("s_waitcnt lgkmcnt(" #n ")" ::: "memory")
; #define PG8_BAR __builtin_amdgcn_s_barrier()
; #define PG8_SCHED __builtin_amdgcn_sched_barrier(0)
; template <class Epi, class Sched, bool ALIGN_EPI = false, bool SP2 = false>
; __device__ __forceinline__ void gemm_phase(PG8_LAS unsigned char* lds, const Gemm g, const Sched& S, const Epi& E, int tid_in) {
;     ...
;             PG8_WAIT_V(8); PG8_WAIT_L(0); PG8_BAR; PG8_MMA(0, 0, At, B0); PG8_MMA(0, 1, At, B1); PG8_BAR; PG8_SCHED;
;             PG8_LDA(At, 0, 1); PG8_STAGE(PG8_SB(0, 0), b2, voffB); PG8_STAGE(PG8_SB(0, 1), b2 + hstep, voffB); PG8_STAGE(PG8_SA(0, 0), a2, voffA);
;             PG8_WAIT_V(8); PG8_WAIT_L(0); PG8_BAR; PG8_MMA(1, 0, At, B0); PG8_MMA(1, 1, At, B1); PG8_BAR; PG8_SCHED;
	s_setprio 1
	s_waitcnt lgkmcnt(0)
	v_mfma_f32_16x16x32_bf16 v[142:145], v[106:109], v[162:165], v[142:145]
	v_mfma_f32_16x16x32_bf16 v[138:141], v[130:133], v[162:165], v[138:141]
	v_mfma_f32_16x16x32_bf16 v[118:121], v[106:109], v[170:173], v[118:121]
	v_mfma_f32_16x16x32_bf16 v[114:117], v[130:133], v[170:173], v[114:117]
	v_mfma_f32_16x16x32_bf16 v[94:97], v[106:109], v[178:181], v[94:97]
	v_mfma_f32_16x16x32_bf16 v[90:93], v[130:133], v[178:181], v[90:93]
	v_mfma_f32_16x16x32_bf16 v[78:81], v[106:109], v[206:209], v[78:81]
	v_mfma_f32_16x16x32_bf16 v[74:77], v[130:133], v[206:209], v[74:77]
	v_mfma_f32_16x16x32_bf16 v[142:145], v[110:113], v[166:169], v[142:145]
	v_mfma_f32_16x16x32_bf16 v[138:141], v[134:137], v[166:169], v[138:141]
	v_mfma_f32_16x16x32_bf16 v[118:121], v[110:113], v[174:177], v[118:121]
	v_mfma_f32_16x16x32_bf16 v[114:117], v[134:137], v[174:177], v[114:117]
	v_mfma_f32_16x16x32_bf16 v[94:97], v[110:113], v[182:185], v[94:97]
	v_mfma_f32_16x16x32_bf16 v[90:93], v[134:137], v[182:185], v[90:93]
	v_mfma_f32_16x16x32_bf16 v[78:81], v[110:113], v[212:215], v[78:81]
	v_mfma_f32_16x16x32_bf16 v[74:77], v[134:137], v[212:215], v[74:77]
	s_setprio 0
	s_setprio 1
	v_mfma_f32_16x16x32_bf16 v[126:129], v[146:149], v[162:165], v[126:129]
	v_mfma_f32_16x16x32_bf16 v[122:125], v[154:157], v[162:165], v[122:125]
	v_mfma_f32_16x16x32_bf16 v[102:105], v[146:149], v[170:173], v[102:105]
	v_mfma_f32_16x16x32_bf16 v[98:101], v[154:157], v[170:173], v[98:101]
	v_mfma_f32_16x16x32_bf16 v[86:89], v[146:149], v[178:181], v[86:89]
	v_mfma_f32_16x16x32_bf16 v[82:85], v[154:157], v[178:181], v[82:85]
	v_mfma_f32_16x16x32_bf16 v[70:73], v[146:149], v[206:209], v[70:73]
	v_mfma_f32_16x16x32_bf16 v[66:69], v[154:157], v[206:209], v[66:69]
	v_mfma_f32_16x16x32_bf16 v[126:129], v[150:153], v[166:169], v[126:129]
	v_mfma_f32_16x16x32_bf16 v[122:125], v[158:161], v[166:169], v[122:125]
	v_mfma_f32_16x16x32_bf16 v[102:105], v[150:153], v[174:177], v[102:105]
	v_mfma_f32_16x16x32_bf16 v[98:101], v[158:161], v[174:177], v[98:101]
	v_mfma_f32_16x16x32_bf16 v[86:89], v[150:153], v[182:185], v[86:89]
	v_mfma_f32_16x16x32_bf16 v[82:85], v[158:161], v[182:185], v[82:85]
	v_mfma_f32_16x16x32_bf16 v[70:73], v[150:153], v[212:215], v[70:73]
	v_mfma_f32_16x16x32_bf16 v[66:69], v[158:161], v[212:215], v[66:69]
	s_setprio 0
	s_barrier
	s_add_i32 s86, s84, s60
	v_lshl_add_u64 v[216:217], s[52:53], 0, v[0:1]
	s_mov_b32 m0, s86
	ds_read_b128 v[162:165], v211 offset:16384
	ds_read_b128 v[166:169], v211 offset:17408
	ds_read_b128 v[170:173], v211 offset:18432
	ds_read_b128 v[174:177], v211 offset:19456
	ds_read_b128 v[178:181], v211 offset:20480
	ds_read_b128 v[182:185], v211 offset:21504
	ds_read_b128 v[206:209], v211 offset:22528
	ds_read_b128 v[212:215], v211 offset:23552
	global_load_lds_dwordx4 v[216:217], off
	s_add_i32 m0, s86, 0x2000
	s_add_u32 s86, s52, 0x100000
	v_lshl_add_u64 v[218:219], s[52:53], 0, v[196:197]
	s_addc_u32 s87, s53, 0
	s_add_i32 s92, s85, s60
	global_load_lds_dwordx4 v[218:219], off
	v_lshl_add_u64 v[220:221], s[86:87], 0, v[0:1]
	s_mov_b32 m0, s92
	v_lshl_add_u64 v[222:223], s[54:55], 0, v[198:199]
	global_load_lds_dwordx4 v[220:221], off
	v_lshl_add_u64 v[220:221], s[86:87], 0, v[196:197]
	s_add_i32 m0, s92, 0x2000
	s_nop 0
	global_load_lds_dwordx4 v[220:221], off
	v_lshl_add_u64 v[220:221], s[54:55], 0, v[200:201]
	s_mov_b32 m0, s61
	s_nop 0
	global_load_lds_dwordx4 v[220:221], off
	s_mov_b32 m0, s62
	s_nop 0
	global_load_lds_dwordx4 v[222:223], off
	s_waitcnt vmcnt(8)
	s_waitcnt lgkmcnt(0)
	s_barrier
	s_setprio 1
	s_waitcnt lgkmcnt(0)
	v_mfma_f32_16x16x32_bf16 v[62:65], v[106:109], v[162:165], v[62:65]
	v_mfma_f32_16x16x32_bf16 v[58:61], v[130:133], v[162:165], v[58:61]
	v_mfma_f32_16x16x32_bf16 v[46:49], v[106:109], v[170:173], v[46:49]
	v_mfma_f32_16x16x32_bf16 v[42:45], v[130:133], v[170:173], v[42:45]
	v_mfma_f32_16x16x32_bf16 v[30:33], v[106:109], v[178:181], v[30:33]
	v_mfma_f32_16x16x32_bf16 v[26:29], v[130:133], v[178:181], v[26:29]
	v_mfma_f32_16x16x32_bf16 v[14:17], v[106:109], v[206:209], v[14:17]
	v_mfma_f32_16x16x32_bf16 v[10:13], v[130:133], v[206:209], v[10:13]
	v_mfma_f32_16x16x32_bf16 v[62:65], v[110:113], v[166:169], v[62:65]
	v_mfma_f32_16x16x32_bf16 v[58:61], v[134:137], v[166:169], v[58:61]
	v_mfma_f32_16x16x32_bf16 v[46:49], v[110:113], v[174:177], v[46:49]
	v_mfma_f32_16x16x32_bf16 v[42:45], v[134:137], v[174:177], v[42:45]
	v_mfma_f32_16x16x32_bf16 v[30:33], v[110:113], v[182:185], v[30:33]
	v_mfma_f32_16x16x32_bf16 v[26:29], v[134:137], v[182:185], v[26:29]
	v_mfma_f32_16x16x32_bf16 v[14:17], v[110:113], v[212:215], v[14:17]
	v_mfma_f32_16x16x32_bf16 v[10:13], v[134:137], v[212:215], v[10:13]
	s_setprio 0
	s_setprio 1
	v_mfma_f32_16x16x32_bf16 v[54:57], v[146:149], v[162:165], v[54:57]
	v_mfma_f32_16x16x32_bf16 v[50:53], v[154:157], v[162:165], v[50:53]
	v_mfma_f32_16x16x32_bf16 v[38:41], v[146:149], v[170:173], v[38:41]
	v_mfma_f32_16x16x32_bf16 v[34:37], v[154:157], v[170:173], v[34:37]
	v_mfma_f32_16x16x32_bf16 v[22:25], v[146:149], v[178:181], v[22:25]
	v_mfma_f32_16x16x32_bf16 v[18:21], v[154:157], v[178:181], v[18:21]
	v_mfma_f32_16x16x32_bf16 v[6:9], v[146:149], v[206:209], v[6:9]
	v_mfma_f32_16x16x32_bf16 v[2:5], v[154:157], v[206:209], v[2:5]
	v_mfma_f32_16x16x32_bf16 v[54:57], v[150:153], v[166:169], v[54:57]
	v_mfma_f32_16x16x32_bf16 v[50:53], v[158:161], v[166:169], v[50:53]
	v_mfma_f32_16x16x32_bf16 v[38:41], v[150:153], v[174:177], v[38:41]
	v_mfma_f32_16x16x32_bf16 v[34:37], v[158:161], v[174:177], v[34:37]
	v_mfma_f32_16x16x32_bf16 v[22:25], v[150:153], v[182:185], v[22:25]
	v_mfma_f32_16x16x32_bf16 v[18:21], v[158:161], v[182:185], v[18:21]
	v_mfma_f32_16x16x32_bf16 v[6:9], v[150:153], v[212:215], v[6:9]
	v_mfma_f32_16x16x32_bf16 v[2:5], v[158:161], v[212:215], v[2:5]
	s_setprio 0
	s_barrier
; #define PG8_STAGE(bufoff, gbase, voff) do { _Pragma("unroll") for (int _i = 0; _i < 2; ++_i) \
;         __builtin_amdgcn_global_load_lds((const unsigned*)((const char*)(gbase) + (voff)[_i]), (PG8_LAS unsigned*)(lds + (bufoff) + ldsw + _i * 8192), 16, 0, 0); } while (0)
; #define PG8_LDA(dst, b, h) do { _Pragma("unroll") for (int m = 0; m < 4; ++m) _Pragma("unroll") for (int k = 0; k < 2; ++k) dst[m][k] = *(const PG8_LAS bf16x8*)(lds + PG8_SA(b, h) + aoff + m * 2048 + k * 1024); } while (0)
; #define PG8_LDB(dst, b, h) do { _Pragma("unroll") for (int n = 0; n < 2; ++n) _Pragma("unroll") for (int k = 0; k < 2; ++k) dst[n][k] = *(const PG8_LAS bf16x8*)(lds + PG8_SB(b, h) + boff + n * 2048 + k * 1024); } while (0)
; #define PG8_MMA(ai, bj, At, Bt) do { __builtin_amdgcn_s_setprio(1); _Pragma("unroll") for (int k = 0; k < 2; ++k) _Pragma("unroll") for (int m = 0; m < 4; ++m) _Pragma("unroll") for (int n = 0; n < 2; ++n) \
;         acc[ai][bj][m][n] = __builtin_amdgcn_mfma_f32_16x16x32_bf16(Bt[n][k], At[m][k], acc[ai][bj][m][n], 0, 0, 0); __builtin_amdgcn_s_setprio(0); } while (0)
; #define PG8_WAIT_V(n) asm volatile("s_waitcnt vmcnt(" #n ")" ::: "memory")
; #define PG8_WAIT_L(n) asm volatile("s_waitcnt lgkmcnt(" #n ")" ::: "memory")
; #define PG8_BAR __builtin_amdgcn_s_barrier()
; #define PG8_SCHED __builtin_amdgcn_sched_barrier(0)
; template <class Epi, class Sched, bool ALIGN_EPI = false, bool SP2 = false>
; __device__ __forceinline__ void gemm_phase(PG8_LAS unsigned char* lds, const Gemm g, const Sched& S, const Epi& E, int tid_in) {
;     ...
;             PG8_LDB(B0, 1, 0); PG8_LDB(B1, 1, 1); PG8_SCHED; PG8_LDA(At, 1, 0); PG8_STAGE(PG8_SA(0, 1), a2 + hstep, voffA);
;             PG8_WAIT_V(8); PG8_WAIT_L(0); PG8_BAR; PG8_MMA(0, 0, At, B0); PG8_MMA(0, 1, At, B1); PG8_BAR; PG8_SCHED;
	v_add_u32_e32 v134, s33, v210
	v_add_u32_e32 v158, s74, v210
	ds_read_b128 v[106:109], v134
	ds_read_b128 v[110:113], v134 offset:1024
	ds_read_b128 v[130:133], v134 offset:2048
	ds_read_b128 v[134:137], v134 offset:3072
	ds_read_b128 v[146:149], v158
	ds_read_b128 v[150:153], v158 offset:1024
	ds_read_b128 v[154:157], v158 offset:2048
	ds_read_b128 v[158:161], v158 offset:3072
	s_add_u32 s54, s54, 0x100000
	s_addc_u32 s55, s55, 0
	s_mov_b32 m0, s63
	v_lshl_add_u64 v[224:225], s[54:55], 0, v[200:201]
	ds_read_b128 v[162:165], v211 offset:32768
	ds_read_b128 v[166:169], v211 offset:33792
	ds_read_b128 v[170:173], v211 offset:34816
	ds_read_b128 v[174:177], v211 offset:35840
	ds_read_b128 v[178:181], v211 offset:36864
	ds_read_b128 v[182:185], v211 offset:37888
	ds_read_b128 v[206:209], v211 offset:38912
	ds_read_b128 v[212:215], v211 offset:39936
	global_load_lds_dwordx4 v[224:225], off
	v_lshl_add_u64 v[224:225], s[54:55], 0, v[198:199]
	s_mov_b32 m0, s64
	s_nop 0
	global_load_lds_dwordx4 v[224:225], off
	s_waitcnt vmcnt(8)
	s_waitcnt lgkmcnt(0)
	s_barrier
	s_setprio 1
	s_waitcnt lgkmcnt(0)
	v_mfma_f32_16x16x32_bf16 v[142:145], v[106:109], v[162:165], v[142:145]
	v_mfma_f32_16x16x32_bf16 v[138:141], v[130:133], v[162:165], v[138:141]
	v_mfma_f32_16x16x32_bf16 v[118:121], v[106:109], v[170:173], v[118:121]
	v_mfma_f32_16x16x32_bf16 v[114:117], v[130:133], v[170:173], v[114:117]
	v_mfma_f32_16x16x32_bf16 v[94:97], v[106:109], v[178:181], v[94:97]
	v_mfma_f32_16x16x32_bf16 v[90:93], v[130:133], v[178:181], v[90:93]
	v_mfma_f32_16x16x32_bf16 v[78:81], v[106:109], v[206:209], v[78:81]
	v_mfma_f32_16x16x32_bf16 v[74:77], v[130:133], v[206:209], v[74:77]
	v_mfma_f32_16x16x32_bf16 v[142:145], v[110:113], v[166:169], v[142:145]
	v_mfma_f32_16x16x32_bf16 v[138:141], v[134:137], v[166:169], v[138:141]
	v_mfma_f32_16x16x32_bf16 v[118:121], v[110:113], v[174:177], v[118:121]
	v_mfma_f32_16x16x32_bf16 v[114:117], v[134:137], v[174:177], v[114:117]
	v_mfma_f32_16x16x32_bf16 v[94:97], v[110:113], v[182:185], v[94:97]
	v_mfma_f32_16x16x32_bf16 v[90:93], v[134:137], v[182:185], v[90:93]
	v_mfma_f32_16x16x32_bf16 v[78:81], v[110:113], v[212:215], v[78:81]
	v_mfma_f32_16x16x32_bf16 v[74:77], v[134:137], v[212:215], v[74:77]
	s_setprio 0
	s_setprio 1
	v_mfma_f32_16x16x32_bf16 v[126:129], v[146:149], v[162:165], v[126:129]
	v_mfma_f32_16x16x32_bf16 v[122:125], v[154:157], v[162:165], v[122:125]
	v_mfma_f32_16x16x32_bf16 v[102:105], v[146:149], v[170:173], v[102:105]
	v_mfma_f32_16x16x32_bf16 v[98:101], v[154:157], v[170:173], v[98:101]
	v_mfma_f32_16x16x32_bf16 v[86:89], v[146:149], v[178:181], v[86:89]
	v_mfma_f32_16x16x32_bf16 v[82:85], v[154:157], v[178:181], v[82:85]
	v_mfma_f32_16x16x32_bf16 v[70:73], v[146:149], v[206:209], v[70:73]
	v_mfma_f32_16x16x32_bf16 v[66:69], v[154:157], v[206:209], v[66:69]
	v_mfma_f32_16x16x32_bf16 v[126:129], v[150:153], v[166:169], v[126:129]
	v_mfma_f32_16x16x32_bf16 v[122:125], v[158:161], v[166:169], v[122:125]
	v_mfma_f32_16x16x32_bf16 v[102:105], v[150:153], v[174:177], v[102:105]
	v_mfma_f32_16x16x32_bf16 v[98:101], v[158:161], v[174:177], v[98:101]
	v_mfma_f32_16x16x32_bf16 v[86:89], v[150:153], v[182:185], v[86:89]
	v_mfma_f32_16x16x32_bf16 v[82:85], v[158:161], v[182:185], v[82:85]
	v_mfma_f32_16x16x32_bf16 v[70:73], v[150:153], v[212:215], v[70:73]
	v_mfma_f32_16x16x32_bf16 v[66:69], v[158:161], v[212:215], v[66:69]
	s_setprio 0
	s_barrier
; #define PG8_STAGE(bufoff, gbase, voff) do { _Pragma("unroll") for (int _i = 0; _i < 2; ++_i) \
;         __builtin_amdgcn_global_load_lds((const unsigned*)((const char*)(gbase) + (voff)[_i]), (PG8_LAS unsigned*)(lds + (bufoff) + ldsw + _i * 8192), 16, 0, 0); } while (0)
; #define PG8_LDA(dst, b, h) do { _Pragma("unroll") for (int m = 0; m < 4; ++m) _Pragma("unroll") for (int k = 0; k < 2; ++k) dst[m][k] = *(const PG8_LAS bf16x8*)(lds + PG8_SA(b, h) + aoff + m * 2048 + k * 1024); } while (0)
; #define PG8_MMA(ai, bj, At, Bt) do { __builtin_amdgcn_s_setprio(1); _Pragma("unroll") for (int k = 0; k < 2; ++k) _Pragma("unroll") for (int m = 0; m < 4; ++m) _Pragma("unroll") for (int n = 0; n < 2; ++n) \
;         acc[ai][bj][m][n] = __builtin_amdgcn_mfma_f32_16x16x32_bf16(Bt[n][k], At[m][k], acc[ai][bj][m][n], 0, 0, 0); __builtin_amdgcn_s_setprio(0); } while (0)
; #define PG8_WAIT_V(n) asm volatile("s_waitcnt vmcnt(" #n ")" ::: "memory")
; #define PG8_WAIT_L(n) asm volatile("s_waitcnt lgkmcnt(" #n ")" ::: "memory")
; #define PG8_BAR __builtin_amdgcn_s_barrier()
; #define PG8_SCHED __builtin_amdgcn_sched_barrier(0)
; template <class Epi, class Sched, bool ALIGN_EPI = false, bool SP2 = false>
; __device__ __forceinline__ void gemm_phase(PG8_LAS unsigned char* lds, const Gemm g, const Sched& S, const Epi& E, int tid_in) {
;     ...
;             PG8_LDA(At, 1, 1); PG8_STAGE(PG8_SB(1, 0), b3, voffB); PG8_STAGE(PG8_SB(1, 1), b3 + hstep, voffB); PG8_STAGE(PG8_SA(1, 0), a3, voffA);
;             PG8_WAIT_V(8); PG8_WAIT_L(0); PG8_BAR; PG8_MMA(1, 0, At, B0); PG8_MMA(1, 1, At, B1); PG8_BAR; PG8_SCHED;
;     ...
;         if constexpr (ALIGN_EPI) { if (wr == 0) PG8_BAR; }
	s_add_i32 s54, s33, s60
	v_lshl_add_u64 v[216:217], v[216:217], 0, s[26:27]
	s_mov_b32 m0, s54
	ds_read_b128 v[162:165], v211 offset:49152
	ds_read_b128 v[166:169], v211 offset:50176
	ds_read_b128 v[170:173], v211 offset:51200
	ds_read_b128 v[174:177], v211 offset:52224
	ds_read_b128 v[178:181], v211 offset:53248
	ds_read_b128 v[182:185], v211 offset:54272
	ds_read_b128 v[206:209], v211 offset:55296
	ds_read_b128 v[212:215], v211 offset:56320
	global_load_lds_dwordx4 v[216:217], off
	s_add_i32 m0, s54, 0x2000
	s_add_u32 s52, s52, 0x100080
	v_lshl_add_u64 v[216:217], v[218:219], 0, s[26:27]
	s_addc_u32 s53, s53, 0
	s_add_i32 s54, s74, s60
	global_load_lds_dwordx4 v[216:217], off
	v_lshl_add_u64 v[216:217], s[52:53], 0, v[0:1]
	s_mov_b32 m0, s54
	s_nop 0
	global_load_lds_dwordx4 v[216:217], off
	v_lshl_add_u64 v[216:217], s[52:53], 0, v[196:197]
	s_add_i32 m0, s54, 0x2000
	s_nop 0
	global_load_lds_dwordx4 v[216:217], off
	v_lshl_add_u64 v[216:217], v[220:221], 0, s[26:27]
	s_mov_b32 m0, s75
	s_nop 0
	global_load_lds_dwordx4 v[216:217], off
	v_lshl_add_u64 v[216:217], v[222:223], 0, s[26:27]
	s_mov_b32 m0, s76
	s_nop 0
	global_load_lds_dwordx4 v[216:217], off
	s_waitcnt vmcnt(8)
	s_waitcnt lgkmcnt(0)
	s_barrier
	s_setprio 1
	s_waitcnt lgkmcnt(0)
	v_mfma_f32_16x16x32_bf16 v[62:65], v[106:109], v[162:165], v[62:65]
	v_mfma_f32_16x16x32_bf16 v[58:61], v[130:133], v[162:165], v[58:61]
	v_mfma_f32_16x16x32_bf16 v[46:49], v[106:109], v[170:173], v[46:49]
	v_mfma_f32_16x16x32_bf16 v[42:45], v[130:133], v[170:173], v[42:45]
	v_mfma_f32_16x16x32_bf16 v[30:33], v[106:109], v[178:181], v[30:33]
	v_mfma_f32_16x16x32_bf16 v[26:29], v[130:133], v[178:181], v[26:29]
	v_mfma_f32_16x16x32_bf16 v[14:17], v[106:109], v[206:209], v[14:17]
	v_mfma_f32_16x16x32_bf16 v[10:13], v[130:133], v[206:209], v[10:13]
	v_mfma_f32_16x16x32_bf16 v[62:65], v[110:113], v[166:169], v[62:65]
	v_mfma_f32_16x16x32_bf16 v[58:61], v[134:137], v[166:169], v[58:61]
	v_mfma_f32_16x16x32_bf16 v[46:49], v[110:113], v[174:177], v[46:49]
	v_mfma_f32_16x16x32_bf16 v[42:45], v[134:137], v[174:177], v[42:45]
	v_mfma_f32_16x16x32_bf16 v[30:33], v[110:113], v[182:185], v[30:33]
	v_mfma_f32_16x16x32_bf16 v[26:29], v[134:137], v[182:185], v[26:29]
	v_mfma_f32_16x16x32_bf16 v[14:17], v[110:113], v[212:215], v[14:17]
	v_mfma_f32_16x16x32_bf16 v[10:13], v[134:137], v[212:215], v[10:13]
	s_setprio 0
	s_setprio 1
	v_mfma_f32_16x16x32_bf16 v[54:57], v[146:149], v[162:165], v[54:57]
	v_mfma_f32_16x16x32_bf16 v[50:53], v[154:157], v[162:165], v[50:53]
	v_mfma_f32_16x16x32_bf16 v[38:41], v[146:149], v[170:173], v[38:41]
	v_mfma_f32_16x16x32_bf16 v[34:37], v[154:157], v[170:173], v[34:37]
	v_mfma_f32_16x16x32_bf16 v[22:25], v[146:149], v[178:181], v[22:25]
	v_mfma_f32_16x16x32_bf16 v[18:21], v[154:157], v[178:181], v[18:21]
	v_mfma_f32_16x16x32_bf16 v[6:9], v[146:149], v[206:209], v[6:9]
	v_mfma_f32_16x16x32_bf16 v[2:5], v[154:157], v[206:209], v[2:5]
	v_mfma_f32_16x16x32_bf16 v[54:57], v[150:153], v[166:169], v[54:57]
	v_mfma_f32_16x16x32_bf16 v[50:53], v[158:161], v[166:169], v[50:53]
	v_mfma_f32_16x16x32_bf16 v[38:41], v[150:153], v[174:177], v[38:41]
	v_mfma_f32_16x16x32_bf16 v[34:37], v[158:161], v[174:177], v[34:37]
	v_mfma_f32_16x16x32_bf16 v[22:25], v[150:153], v[182:185], v[22:25]
	v_mfma_f32_16x16x32_bf16 v[18:21], v[158:161], v[182:185], v[18:21]
	v_mfma_f32_16x16x32_bf16 v[6:9], v[150:153], v[212:215], v[6:9]
	v_mfma_f32_16x16x32_bf16 v[2:5], v[158:161], v[212:215], v[2:5]
	s_setprio 0
	s_add_i32 s83, s83, 2
	s_add_u32 s50, s50, 0x100
	s_addc_u32 s51, s51, 0
	s_add_u32 s81, s81, 0x100
	s_addc_u32 s82, s82, 0
	s_cmp_gt_u32 s83, 61
	s_barrier
	s_cbranch_scc0 .LBB0_567
	s_and_b64 vcc, exec, s[38:39]
	s_cbranch_vccz .LBB0_570
	s_barrier
